# all flat_load of f32 weights/gains replaced by global_load (no lgkmcnt coupling, more loads in flight)
# speedup vs baseline: 1.0006x; 1.0006x over previous
.LBB0_16:
	s_ashr_i32 s0, s50, 2
	s_and_b32 s38, s20, 1
	s_mul_hi_i32 s1, s40, s0
	s_mul_i32 s0, s40, s0
	s_add_u32 s34, s34, s0
	s_addc_u32 s35, s35, s1
	s_ashr_i32 s0, s20, 1
	s_ashr_i32 s1, s0, 31
	s_lshl_b64 s[0:1], s[0:1], 15
	s_add_u32 s34, s34, s0
	v_lshlrev_b32_e32 v0, 2, v0
	s_addc_u32 s35, s35, s1
	v_lshl_add_u64 v[16:17], s[42:43], 0, v[0:1]
	s_lshl_b32 s20, s36, 2
	v_lshl_add_u64 v[18:19], v[16:17], 0, s[20:21]
	v_lshl_add_u64 v[20:21], v[18:19], 0, s[20:21]
	v_lshl_add_u64 v[22:23], v[20:21], 0, s[20:21]
	v_lshl_add_u64 v[24:25], v[22:23], 0, s[20:21]
	v_lshl_add_u64 v[26:27], v[24:25], 0, s[20:21]
	v_lshl_add_u64 v[28:29], v[26:27], 0, s[20:21]
	v_lshl_add_u64 v[30:31], v[28:29], 0, s[20:21]
	global_load_dword v15, v[16:17], off
	global_load_dword v32, v[18:19], off
	global_load_dword v33, v[20:21], off
	global_load_dword v34, v[22:23], off
	global_load_dword v35, v[24:25], off
	global_load_dword v36, v[26:27], off
	global_load_dword v37, v[28:29], off
	global_load_dword v38, v[30:31], off
	v_lshl_add_u64 v[16:17], v[30:31], 0, s[20:21]
	global_load_dword v24, v[16:17], off
	v_lshl_add_u64 v[16:17], v[16:17], 0, s[20:21]
	global_load_dword v25, v[16:17], off
	v_lshl_add_u64 v[16:17], v[16:17], 0, s[20:21]
	global_load_dword v26, v[16:17], off
	v_lshl_add_u64 v[16:17], v[16:17], 0, s[20:21]
	global_load_dword v27, v[16:17], off
	v_lshl_add_u64 v[16:17], v[16:17], 0, s[20:21]
	global_load_dword v28, v[16:17], off
	v_lshl_add_u64 v[16:17], v[16:17], 0, s[20:21]
	global_load_dword v29, v[16:17], off
	v_lshl_add_u64 v[16:17], v[16:17], 0, s[20:21]
	global_load_dword v30, v[16:17], off
	v_lshl_add_u64 v[16:17], v[16:17], 0, s[20:21]
	global_load_dword v31, v[16:17], off
	v_lshl_add_u64 v[16:17], v[16:17], 0, s[20:21]
	global_load_dword v39, v[16:17], off
	v_lshl_add_u64 v[16:17], v[16:17], 0, s[20:21]
	global_load_dword v40, v[16:17], off
	v_lshl_add_u64 v[16:17], v[16:17], 0, s[20:21]
	global_load_dword v41, v[16:17], off
	v_lshl_add_u64 v[16:17], v[16:17], 0, s[20:21]
	global_load_dword v42, v[16:17], off
	v_lshl_add_u64 v[16:17], v[16:17], 0, s[20:21]
	global_load_dword v43, v[16:17], off
	v_lshl_add_u64 v[16:17], v[16:17], 0, s[20:21]
	global_load_dword v44, v[16:17], off
	v_lshl_add_u64 v[16:17], v[16:17], 0, s[20:21]
	global_load_dword v45, v[16:17], off
	v_lshl_add_u64 v[16:17], v[16:17], 0, s[20:21]
	global_load_dword v46, v[16:17], off
	v_lshl_add_u64 v[16:17], v[16:17], 0, s[20:21]
	global_load_dword v47, v[16:17], off
	v_lshl_add_u64 v[16:17], v[16:17], 0, s[20:21]
	global_load_dword v48, v[16:17], off
	v_lshl_add_u64 v[16:17], v[16:17], 0, s[20:21]
	global_load_dword v49, v[16:17], off
	v_lshl_add_u64 v[16:17], v[16:17], 0, s[20:21]
	global_load_dword v50, v[16:17], off
	v_lshl_add_u64 v[16:17], v[16:17], 0, s[20:21]
	global_load_dword v51, v[16:17], off
	v_lshl_add_u64 v[16:17], v[16:17], 0, s[20:21]
	global_load_dword v52, v[16:17], off
	v_lshl_add_u64 v[16:17], v[16:17], 0, s[20:21]
	global_load_dword v53, v[16:17], off
	v_lshl_add_u64 v[16:17], v[16:17], 0, s[20:21]
	global_load_dword v54, v[16:17], off
	s_and_b32 s0, s37, 0xc0
	v_add_u32_e32 v0, s0, v10
	v_lshlrev_b32_e32 v16, 7, v0
	v_lshrrev_b32_e32 v0, 3, v0
	v_and_or_b32 v0, v0, 14, s38
	v_and_b32_e32 v16, 0xffffc000, v16
	v_lshlrev_b32_e32 v0, 10, v0
	s_waitcnt vmcnt(0) lgkmcnt(0)
	v_readlane_b32 s0, v14, 0
	v_or3_b32 v0, v0, v16, v12
	s_nop 0
	v_mov_b32_e32 v16, s0
	v_readlane_b32 s0, v14, 1
	v_cndmask_b32_e64 v16, v16, 1.0, s[30:31]
	v_mul_f32_e32 v15, v15, v16
	v_mov_b32_e32 v17, s0
	v_readlane_b32 s0, v14, 2
	v_cndmask_b32_e64 v17, v17, 1.0, s[30:31]
	v_mul_f32_e32 v16, v32, v17
	v_mov_b32_e32 v18, s0
	v_readlane_b32 s0, v14, 3
	v_cndmask_b32_e64 v18, v18, 1.0, s[30:31]
	v_cvt_pk_bf16_f32 v16, v15, v16
	v_mul_f32_e32 v15, v33, v18
	v_mov_b32_e32 v19, s0
	v_readlane_b32 s0, v14, 4
	v_cndmask_b32_e64 v19, v19, 1.0, s[30:31]
	v_mul_f32_e32 v17, v34, v19
	v_mov_b32_e32 v20, s0
	v_readlane_b32 s0, v14, 5
	v_cndmask_b32_e64 v20, v20, 1.0, s[30:31]
	v_cvt_pk_bf16_f32 v17, v15, v17
	v_mul_f32_e32 v15, v35, v20
	v_mov_b32_e32 v21, s0
	v_readlane_b32 s0, v14, 6
	v_cndmask_b32_e64 v21, v21, 1.0, s[30:31]
	v_mul_f32_e32 v18, v36, v21
	v_mov_b32_e32 v22, s0
	v_readlane_b32 s0, v14, 7
	v_cndmask_b32_e64 v22, v22, 1.0, s[30:31]
	v_cvt_pk_bf16_f32 v18, v15, v18
	v_mul_f32_e32 v15, v37, v22
	v_mov_b32_e32 v23, s0
	v_cndmask_b32_e64 v23, v23, 1.0, s[30:31]
	v_readlane_b32 s0, v14, 8
	v_mul_f32_e32 v19, v38, v23
	v_lshl_add_u64 v[20:21], s[34:35], 0, v[0:1]
	v_mov_b32_e32 v0, s0
	v_readlane_b32 s0, v14, 9
	v_cvt_pk_bf16_f32 v19, v15, v19
	v_lshl_add_u64 v[22:23], v[20:21], 0, v[2:3]
	global_store_dwordx4 v[22:23], v[16:19], off
	v_mov_b32_e32 v15, s0
	v_readlane_b32 s0, v14, 10
	v_cndmask_b32_e64 v0, v0, 1.0, s[30:31]
	v_cndmask_b32_e64 v15, v15, 1.0, s[30:31]
	v_mov_b32_e32 v16, s0
	v_readlane_b32 s0, v14, 11
	v_cndmask_b32_e64 v17, v16, 1.0, s[30:31]
	v_mul_f32_e32 v0, v24, v0
	v_mov_b32_e32 v16, s0
	v_readlane_b32 s0, v14, 12
	v_cndmask_b32_e64 v18, v16, 1.0, s[30:31]
	v_mul_f32_e32 v15, v25, v15
	v_mov_b32_e32 v16, s0
	v_readlane_b32 s0, v14, 13
	v_cndmask_b32_e64 v19, v16, 1.0, s[30:31]
	s_nop 0
	v_mov_b32_e32 v16, s0
	v_readlane_b32 s0, v14, 14
	v_cndmask_b32_e64 v32, v16, 1.0, s[30:31]
	s_nop 0
	v_mov_b32_e32 v16, s0
	v_readlane_b32 s0, v14, 15
	v_cndmask_b32_e64 v33, v16, 1.0, s[30:31]
	s_nop 0
	v_mov_b32_e32 v16, s0
	v_cndmask_b32_e64 v34, v16, 1.0, s[30:31]
	v_cvt_pk_bf16_f32 v16, v0, v15
	v_mul_f32_e32 v0, v26, v17
	v_mul_f32_e32 v15, v27, v18
	v_cvt_pk_bf16_f32 v17, v0, v15
	v_mul_f32_e32 v0, v28, v19
	v_mul_f32_e32 v15, v29, v32
	v_cvt_pk_bf16_f32 v18, v0, v15
	v_mul_f32_e32 v0, v30, v33
	v_readlane_b32 s0, v14, 16
	v_mul_f32_e32 v15, v31, v34
	v_cvt_pk_bf16_f32 v19, v0, v15
	global_store_dwordx4 v[22:23], v[16:19], off offset:16
	v_mov_b32_e32 v0, s0
	v_readlane_b32 s0, v14, 17
	v_cndmask_b32_e64 v0, v0, 1.0, s[30:31]
	v_mul_f32_e32 v0, v39, v0
	v_mov_b32_e32 v15, s0
	v_readlane_b32 s0, v14, 18
	v_cndmask_b32_e64 v15, v15, 1.0, s[30:31]
	v_mul_f32_e32 v15, v40, v15
	v_mov_b32_e32 v16, s0
	v_readlane_b32 s0, v14, 19
	v_cndmask_b32_e64 v17, v16, 1.0, s[30:31]
	s_nop 0
	v_mov_b32_e32 v16, s0
	v_readlane_b32 s0, v14, 20
	v_cndmask_b32_e64 v18, v16, 1.0, s[30:31]
	s_nop 0
	v_mov_b32_e32 v16, s0
	v_readlane_b32 s0, v14, 21
	v_cndmask_b32_e64 v19, v16, 1.0, s[30:31]
	s_nop 0
	v_mov_b32_e32 v16, s0
	v_readlane_b32 s0, v14, 22
	v_cndmask_b32_e64 v22, v16, 1.0, s[30:31]
	s_nop 0
	v_mov_b32_e32 v16, s0
	v_readlane_b32 s0, v14, 23
	v_cndmask_b32_e64 v23, v16, 1.0, s[30:31]
	s_nop 0
	v_mov_b32_e32 v16, s0
	v_cndmask_b32_e64 v24, v16, 1.0, s[30:31]
	v_cvt_pk_bf16_f32 v16, v0, v15
	v_mul_f32_e32 v0, v41, v17
	v_mul_f32_e32 v15, v42, v18
	v_cvt_pk_bf16_f32 v17, v0, v15
	v_mul_f32_e32 v0, v43, v19
	v_mul_f32_e32 v15, v44, v22
	v_cvt_pk_bf16_f32 v18, v0, v15
	v_mul_f32_e32 v0, v45, v23
	v_readlane_b32 s0, v14, 24
	v_mul_f32_e32 v15, v46, v24
	v_cvt_pk_bf16_f32 v19, v0, v15
	v_lshl_add_u64 v[22:23], v[20:21], 0, v[4:5]
	v_mov_b32_e32 v0, s0
	v_readlane_b32 s0, v14, 25
	global_store_dwordx4 v[22:23], v[16:19], off
	v_cndmask_b32_e64 v0, v0, 1.0, s[30:31]
	v_mov_b32_e32 v15, s0
	v_readlane_b32 s0, v14, 26
	v_cndmask_b32_e64 v15, v15, 1.0, s[30:31]
	v_mul_f32_e32 v0, v47, v0
	v_mov_b32_e32 v16, s0
	v_readlane_b32 s0, v14, 27
	v_cndmask_b32_e64 v16, v16, 1.0, s[30:31]
	s_nop 0
	v_mov_b32_e32 v17, s0
	v_readlane_b32 s0, v14, 28
	v_cndmask_b32_e64 v17, v17, 1.0, s[30:31]
	s_nop 0
	v_mov_b32_e32 v18, s0
	v_readlane_b32 s0, v14, 29
	v_cndmask_b32_e64 v18, v18, 1.0, s[30:31]
	s_nop 0
	v_mov_b32_e32 v19, s0
	v_readlane_b32 s0, v14, 30
	v_cndmask_b32_e64 v19, v19, 1.0, s[30:31]
	s_nop 0
	v_mov_b32_e32 v22, s0
	v_readlane_b32 s0, v14, 31
	v_cndmask_b32_e64 v22, v22, 1.0, s[30:31]
	s_nop 0
	v_mov_b32_e32 v14, s0
	v_cndmask_b32_e64 v23, v14, 1.0, s[30:31]
	v_mul_f32_e32 v14, v48, v15
	v_cvt_pk_bf16_f32 v14, v0, v14
	v_mul_f32_e32 v0, v49, v16
	v_mul_f32_e32 v15, v50, v17
	v_cvt_pk_bf16_f32 v15, v0, v15
	v_mul_f32_e32 v0, v51, v18
	v_mul_f32_e32 v16, v52, v19
	v_mul_f32_e32 v17, v54, v23
	v_lshl_add_u64 v[18:19], v[20:21], 0, v[6:7]
	v_cvt_pk_bf16_f32 v16, v0, v16
	v_mul_f32_e32 v0, v53, v22
	v_cvt_pk_bf16_f32 v17, v0, v17
	global_store_dwordx4 v[18:19], v[14:17], off offset:16
	s_add_i32 s0, s49, 0x800
	s_cmp_lt_i32 s49, 0xbc00
	s_mov_b32 s49, s0
	s_cbranch_scc0 .LBB0_32

.LBB0_27:
	s_lshl_b32 s0, s20, 5
	s_ashr_i32 s1, s0, 31
	s_lshl_b64 s[42:43], s[0:1], 2
	s_add_u32 s1, s44, s42
	s_addc_u32 s37, s45, s43
	s_cmp_lg_u64 s[44:45], 0
	s_cselect_b32 s44, s1, 0
	s_mul_hi_i32 s1, s36, s0
	s_mul_i32 s0, s36, s0
	s_cselect_b32 s45, s37, 0
	s_lshl_b32 s37, s50, 6
	s_lshl_b64 s[0:1], s[0:1], 2
	s_add_u32 s42, s30, s0
	s_addc_u32 s43, s31, s1
	s_cmp_eq_u64 s[44:45], 0
	s_cselect_b64 s[30:31], -1, 0
	s_and_b64 s[0:1], s[30:31], exec
	s_cselect_b32 s1, s43, s45
	s_cselect_b32 s0, s42, s44
	v_lshl_add_u64 v[14:15], s[0:1], 0, v[8:9]
	global_load_dword v14, v[14:15], off
	v_add_u32_e32 v16, s37, v10
	s_andn2_b64 vcc, exec, s[38:39]
	v_and_or_b32 v0, v16, s33, v13
	s_cbranch_vccnz .LBB0_16
	v_cmp_lt_i32_e64 s[38:39], s46, v0
	v_cmp_gt_i32_e32 vcc, s47, v0
	s_and_saveexec_b64 s[0:1], vcc
	v_and_b32_e32 v15, 0x60, v16
	v_cmp_ne_u32_e32 vcc, 0, v15
	s_andn2_b64 s[38:39], s[38:39], exec
	s_and_b64 s[44:45], vcc, exec
	v_and_or_b32 v15, v16, s48, v11
	s_or_b64 s[38:39], s[38:39], s[44:45]
	s_or_b64 exec, exec, s[0:1]
	s_and_saveexec_b64 s[0:1], s[38:39]
	s_cbranch_execz .LBB0_15
	v_mov_b32_e32 v15, v0
	s_branch .LBB0_15

.LBB0_41:
	s_ashr_i32 s51, s50, 31
	s_and_b64 s[0:1], s[52:53], exec
	s_cselect_b32 s1, s57, 0xd000000
	s_cselect_b32 s28, s6, s18
	s_mul_hi_i32 s54, s1, s50
	s_mul_i32 s1, s1, s50
	s_cselect_b32 s20, s7, s19
	s_cselect_b32 s69, s5, s11
	s_cselect_b32 s70, s4, s10
	s_cselect_b32 s0, s60, 0x3400
	s_add_u32 s1, s28, s1
	s_addc_u32 s20, s20, s54
	s_lshl_b64 s[54:55], s[50:51], 14
	s_add_u32 s28, s70, s54
	s_addc_u32 s51, s69, s55
	s_mul_hi_u32 s55, s0, s22
	s_mul_i32 s54, s0, s22
	s_lshl_b64 s[54:55], s[54:55], 2
	s_add_u32 s54, s1, s54
	s_addc_u32 s55, s20, s55
	s_add_u32 s70, s28, s36
	s_addc_u32 s71, s51, s37
	v_ashrrev_i32_e32 v3, 31, v2
	v_lshl_add_u64 v[12:13], v[2:3], 2, s[70:71]
	v_and_b32_e32 v3, 0x7fffe0, v2
	global_load_dword v26, v[12:13], off
	v_mul_u32_u24_e32 v3, s0, v3
	v_add_lshl_u32 v0, v0, v3, 2
	v_lshl_add_u64 v[6:7], s[54:55], 0, v[0:1]
	s_lshl_b32 s20, s0, 2
	v_lshl_add_u64 v[14:15], v[6:7], 0, s[20:21]
	global_load_dword v3, v[6:7], off
	global_load_dword v11, v[14:15], off
	s_lshl_b32 s20, s0, 3
	v_lshl_add_u64 v[14:15], v[6:7], 0, s[20:21]
	s_mul_i32 s20, s0, 12
	global_load_dword v20, v[14:15], off
	v_lshl_add_u64 v[14:15], v[6:7], 0, s[20:21]
	global_load_dword v21, v[14:15], off
	s_lshl_b32 s20, s0, 4
	v_lshl_add_u64 v[14:15], v[6:7], 0, s[20:21]
	global_load_dword v22, v[14:15], off
	s_mul_i32 s20, s0, 20
	v_lshl_add_u64 v[14:15], v[6:7], 0, s[20:21]
	global_load_dword v23, v[14:15], off
	s_mul_i32 s20, s0, 24
	v_lshl_add_u64 v[14:15], v[6:7], 0, s[20:21]
	global_load_dword v24, v[14:15], off
	s_mul_i32 s20, s0, 28
	v_lshl_add_u64 v[14:15], v[6:7], 0, s[20:21]
	global_load_dword v25, v[14:15], off
	s_lshl_b32 s20, s0, 5
	v_lshl_add_u64 v[14:15], v[6:7], 0, s[20:21]
	s_mul_i32 s20, s0, 36
	v_lshl_add_u64 v[16:17], v[6:7], 0, s[20:21]
	s_mul_i32 s20, s0, 40
	global_load_dword v27, v[14:15], off
	global_load_dword v28, v[16:17], off
	global_load_dword v34, v[12:13], off offset:256
	global_load_dword v56, v[12:13], off offset:512
	global_load_dword v72, v[12:13], off offset:768
	global_load_dword v89, v[12:13], off offset:1024
	global_load_dword v74, v[12:13], off offset:1280
	global_load_dword v5, v[12:13], off offset:1536
	global_load_dword v0, v[12:13], off offset:1792
	v_lshl_add_u64 v[12:13], v[6:7], 0, s[20:21]
	s_mul_i32 s20, s0, 44
	global_load_dword v29, v[12:13], off
	v_lshl_add_u64 v[12:13], v[6:7], 0, s[20:21]
	global_load_dword v30, v[12:13], off
	s_mul_i32 s20, s0, 48
	v_lshl_add_u64 v[12:13], v[6:7], 0, s[20:21]
	s_mul_i32 s20, s0, 52
	v_lshl_add_u64 v[14:15], v[6:7], 0, s[20:21]
	s_mul_i32 s20, s0, 56
	v_lshl_add_u64 v[16:17], v[6:7], 0, s[20:21]
	s_mul_i32 s20, s0, 60
	v_lshl_add_u64 v[18:19], v[6:7], 0, s[20:21]
	global_load_dword v12, v[12:13], off
	s_nop 0
	global_load_dword v13, v[14:15], off
	s_nop 0
	global_load_dword v14, v[16:17], off
	global_load_dword v15, v[18:19], off
	v_cmp_gt_u32_e32 vcc, 32, v2
	s_waitcnt vmcnt(0) lgkmcnt(0)
	v_readlane_b32 s1, v26, 0
	v_readlane_b32 s20, v26, 32
	v_readlane_b32 s28, v26, 1
	v_readlane_b32 s51, v26, 33
	v_mov_b32_e32 v16, s20
	v_mov_b32_e32 v17, s1
	v_mov_b32_e32 v18, s51
	v_mov_b32_e32 v19, s28
	v_readlane_b32 s54, v26, 2
	v_readlane_b32 s55, v26, 34
	v_cndmask_b32_e32 v16, v16, v17, vcc
	v_cndmask_b32_e32 v17, v18, v19, vcc
	v_mul_f32_e32 v3, v3, v16
	v_mul_f32_e32 v11, v11, v17
	v_mov_b32_e32 v16, s55
	v_mov_b32_e32 v17, s54
	v_readlane_b32 s1, v26, 3
	v_readlane_b32 s20, v26, 35
	v_cndmask_b32_e32 v16, v16, v17, vcc
	v_mov_b32_e32 v18, s1
	v_mov_b32_e32 v17, s20
	v_cndmask_b32_e32 v17, v17, v18, vcc
	v_readlane_b32 s1, v26, 4
	v_readlane_b32 s20, v26, 36
	v_mul_f32_e32 v18, v21, v17
	v_mov_b32_e32 v19, s1
	v_mov_b32_e32 v17, s20
	v_cndmask_b32_e32 v17, v17, v19, vcc
	v_readlane_b32 s1, v26, 5
	v_readlane_b32 s20, v26, 37
	v_mul_f32_e32 v16, v20, v16
	v_mul_f32_e32 v19, v22, v17
	v_mov_b32_e32 v17, s20
	v_mov_b32_e32 v20, s1
	v_cndmask_b32_e32 v17, v17, v20, vcc
	v_readlane_b32 s1, v26, 6
	v_readlane_b32 s20, v26, 38
	v_mul_f32_e32 v20, v23, v17
	v_mov_b32_e32 v21, s1
	v_mov_b32_e32 v17, s20
	v_cndmask_b32_e32 v17, v17, v21, vcc
	v_readlane_b32 s1, v26, 7
	v_readlane_b32 s20, v26, 39
	v_mul_f32_e32 v21, v24, v17
	v_mov_b32_e32 v22, s1
	v_mov_b32_e32 v17, s20
	v_cndmask_b32_e32 v17, v17, v22, vcc
	v_readlane_b32 s1, v26, 8
	v_readlane_b32 s20, v26, 40
	v_mul_f32_e32 v22, v25, v17
	v_mov_b32_e32 v23, s1
	v_mov_b32_e32 v17, s20
	v_cndmask_b32_e32 v17, v17, v23, vcc
	v_readlane_b32 s1, v26, 9
	v_readlane_b32 s20, v26, 41
	v_mul_f32_e32 v23, v27, v17
	v_mov_b32_e32 v24, s1
	v_mov_b32_e32 v17, s20
	v_cndmask_b32_e32 v17, v17, v24, vcc
	v_readlane_b32 s1, v26, 10
	v_readlane_b32 s20, v26, 42
	v_mul_f32_e32 v24, v28, v17
	v_mov_b32_e32 v25, s1
	v_mov_b32_e32 v17, s20
	v_cndmask_b32_e32 v17, v17, v25, vcc
	v_readlane_b32 s1, v26, 11
	v_readlane_b32 s20, v26, 43
	v_mul_f32_e32 v25, v29, v17
	v_mov_b32_e32 v27, s1
	v_mov_b32_e32 v17, s20
	v_cndmask_b32_e32 v17, v17, v27, vcc
	v_readlane_b32 s1, v26, 12
	v_readlane_b32 s20, v26, 44
	v_mul_f32_e32 v27, v30, v17
	v_mov_b32_e32 v28, s1
	v_mov_b32_e32 v17, s20
	v_cndmask_b32_e32 v17, v17, v28, vcc
	v_readlane_b32 s1, v26, 13
	v_readlane_b32 s20, v26, 45
	v_mul_f32_e32 v28, v12, v17
	v_mov_b32_e32 v17, s1
	v_mov_b32_e32 v12, s20
	v_cndmask_b32_e32 v12, v12, v17, vcc
	v_readlane_b32 s1, v26, 14
	v_readlane_b32 s20, v26, 46
	v_mul_f32_e32 v29, v13, v12
	v_mov_b32_e32 v13, s1
	v_mov_b32_e32 v12, s20
	v_cndmask_b32_e32 v12, v12, v13, vcc
	v_readlane_b32 s1, v26, 15
	v_readlane_b32 s20, v26, 47
	v_mul_f32_e32 v30, v14, v12
	v_mov_b32_e32 v13, s1
	v_mov_b32_e32 v12, s20
	v_cvt_pk_bf16_f32 v17, v3, v11
	v_cndmask_b32_e32 v12, v12, v13, vcc
	v_lshlrev_b32_e32 v3, 16, v17
	v_and_b32_e32 v11, 0xffff0000, v17
	v_max_f32_e64 v11, |v11|, |v11|
	v_max_f32_e64 v3, |v3|, |v3|
	v_mul_f32_e32 v31, v15, v12
	v_max_f32_e32 v3, v3, v11
	v_cvt_pk_bf16_f32 v16, v16, v18
	v_cvt_pk_bf16_f32 v15, v19, v20
	s_lshl_b32 s20, s0, 6
	v_lshlrev_b32_e32 v11, 16, v16
	v_and_b32_e32 v12, 0xffff0000, v16
	v_max_f32_e64 v12, |v12|, |v12|
	v_max_f32_e64 v11, |v11|, |v11|
	v_max_f32_e32 v11, v11, v12
	v_max3_f32 v32, v3, 0, v11
	v_lshlrev_b32_e32 v3, 16, v15
	v_and_b32_e32 v11, 0xffff0000, v15
	v_max_f32_e64 v20, |v11|, |v11|
	v_max_f32_e64 v33, |v3|, |v3|
	v_cvt_pk_bf16_f32 v14, v21, v22
	v_cvt_pk_bf16_f32 v13, v23, v24
	v_cvt_pk_bf16_f32 v12, v25, v27
	v_cvt_pk_bf16_f32 v11, v28, v29
	v_cvt_pk_bf16_f32 v3, v30, v31
	v_lshl_add_u64 v[18:19], v[6:7], 0, s[20:21]
	s_mul_i32 s20, s0, 0x44
	global_load_dword v27, v[18:19], off
	v_lshlrev_b32_e32 v21, 16, v14
	v_and_b32_e32 v22, 0xffff0000, v14
	v_lshl_add_u64 v[18:19], v[6:7], 0, s[20:21]
	global_load_dword v28, v[18:19], off
	v_max_f32_e64 v18, |v22|, |v22|
	v_max_f32_e64 v19, |v21|, |v21|
	s_mul_i32 s20, s0, 0x48
	v_max_f32_e32 v20, v33, v20
	v_max_f32_e32 v21, v19, v18
	v_lshl_add_u64 v[18:19], v[6:7], 0, s[20:21]
	s_mul_i32 s20, s0, 0x4c
	global_load_dword v29, v[18:19], off
	v_max3_f32 v20, v32, v20, v21
	v_lshlrev_b32_e32 v21, 16, v13
	v_and_b32_e32 v22, 0xffff0000, v13
	v_lshl_add_u64 v[18:19], v[6:7], 0, s[20:21]
	global_load_dword v30, v[18:19], off
	v_max_f32_e64 v18, |v22|, |v22|
	v_max_f32_e64 v19, |v21|, |v21|
	s_mul_i32 s20, s0, 0x50
	v_max_f32_e32 v21, v19, v18
	v_lshl_add_u64 v[18:19], v[6:7], 0, s[20:21]
	global_load_dword v31, v[18:19], off
	v_and_b32_e32 v18, 0xffff0000, v12
	s_mul_i32 s20, s0, 0x54
	v_lshlrev_b32_e32 v22, 16, v12
	v_max_f32_e64 v23, |v18|, |v18|
	v_lshl_add_u64 v[18:19], v[6:7], 0, s[20:21]
	global_load_dword v32, v[18:19], off
	v_max_f32_e64 v18, |v22|, |v22|
	v_max_f32_e32 v18, v18, v23
	s_mul_i32 s20, s0, 0x58
	v_max3_f32 v20, v20, v21, v18
	v_lshl_add_u64 v[18:19], v[6:7], 0, s[20:21]
	global_load_dword v33, v[18:19], off
	v_and_b32_e32 v18, 0xffff0000, v11
	s_mul_i32 s20, s0, 0x5c
	v_lshlrev_b32_e32 v21, 16, v11
	v_max_f32_e64 v22, |v18|, |v18|
	v_lshl_add_u64 v[18:19], v[6:7], 0, s[20:21]
	global_load_dword v35, v[18:19], off
	v_max_f32_e64 v18, |v21|, |v21|
	s_mul_i32 s20, s0, 0x60
	v_max_f32_e32 v21, v18, v22
	v_lshl_add_u64 v[18:19], v[6:7], 0, s[20:21]
	v_lshlrev_b32_e32 v22, 16, v3
	global_load_dword v36, v[18:19], off
	v_and_b32_e32 v18, 0xffff0000, v3
	s_mul_i32 s20, s0, 0x64
	v_max_f32_e64 v23, |v18|, |v18|
	v_max_f32_e64 v22, |v22|, |v22|
	v_lshl_add_u64 v[18:19], v[6:7], 0, s[20:21]
	global_load_dword v37, v[18:19], off
	v_max_f32_e32 v18, v22, v23
	s_mul_i32 s20, s0, 0x68
	v_max3_f32 v38, v20, v21, v18
	v_lshl_add_u64 v[18:19], v[6:7], 0, s[20:21]
	global_load_dword v39, v[18:19], off
	s_mul_i32 s20, s0, 0x6c
	v_lshl_add_u64 v[18:19], v[6:7], 0, s[20:21]
	global_load_dword v40, v[18:19], off
	s_mul_i32 s20, s0, 0x70
	v_lshl_add_u64 v[18:19], v[6:7], 0, s[20:21]
	s_mul_i32 s20, s0, 0x74
	v_lshl_add_u64 v[20:21], v[6:7], 0, s[20:21]
	s_mul_i32 s20, s0, 0x78
	v_lshl_add_u64 v[22:23], v[6:7], 0, s[20:21]
	s_mul_i32 s20, s0, 0x7c
	v_lshl_add_u64 v[24:25], v[6:7], 0, s[20:21]
	global_load_dword v18, v[18:19], off
	s_nop 0
	global_load_dword v19, v[20:21], off
	s_nop 0
	global_load_dword v20, v[22:23], off
	global_load_dword v21, v[24:25], off
	v_readlane_b32 s1, v26, 16
	v_readlane_b32 s20, v26, 48
	s_nop 0
	v_mov_b32_e32 v23, s1
	v_mov_b32_e32 v22, s20
	v_readlane_b32 s1, v26, 17
	v_readlane_b32 s20, v26, 49
	v_cndmask_b32_e32 v22, v22, v23, vcc
	v_mov_b32_e32 v24, s1
	v_mov_b32_e32 v23, s20
	v_readlane_b32 s1, v26, 18
	v_readlane_b32 s20, v26, 50
	v_cndmask_b32_e32 v23, v23, v24, vcc
	v_mov_b32_e32 v25, s1
	v_mov_b32_e32 v24, s20
	v_readlane_b32 s1, v26, 19
	v_readlane_b32 s20, v26, 51
	s_waitcnt vmcnt(0) lgkmcnt(0)
	v_mul_f32_e32 v22, v27, v22
	v_cndmask_b32_e32 v24, v24, v25, vcc
	v_mov_b32_e32 v25, s20
	v_mov_b32_e32 v27, s1
	v_cndmask_b32_e32 v25, v25, v27, vcc
	v_readlane_b32 s1, v26, 20
	v_readlane_b32 s20, v26, 52
	v_mul_f32_e32 v23, v28, v23
	v_mov_b32_e32 v28, s1
	v_mul_f32_e32 v27, v30, v25
	v_mov_b32_e32 v25, s20
	v_cndmask_b32_e32 v25, v25, v28, vcc
	v_readlane_b32 s1, v26, 21
	v_readlane_b32 s20, v26, 53
	v_mul_f32_e32 v24, v29, v24
	v_mul_f32_e32 v28, v31, v25
	v_mov_b32_e32 v25, s20
	v_mov_b32_e32 v29, s1
	v_cndmask_b32_e32 v25, v25, v29, vcc
	v_readlane_b32 s1, v26, 22
	v_readlane_b32 s20, v26, 54
	v_mul_f32_e32 v29, v32, v25
	v_mov_b32_e32 v30, s1
	v_mov_b32_e32 v25, s20
	v_cndmask_b32_e32 v25, v25, v30, vcc
	v_readlane_b32 s1, v26, 23
	v_readlane_b32 s20, v26, 55
	v_mul_f32_e32 v30, v33, v25
	v_mov_b32_e32 v31, s1
	v_mov_b32_e32 v25, s20
	v_cndmask_b32_e32 v25, v25, v31, vcc
	v_readlane_b32 s1, v26, 24
	v_readlane_b32 s20, v26, 56
	v_mul_f32_e32 v31, v35, v25
	v_mov_b32_e32 v32, s1
	v_mov_b32_e32 v25, s20
	v_cndmask_b32_e32 v25, v25, v32, vcc
	v_readlane_b32 s1, v26, 25
	v_readlane_b32 s20, v26, 57
	v_mul_f32_e32 v32, v36, v25
	v_mov_b32_e32 v33, s1
	v_mov_b32_e32 v25, s20
	v_cndmask_b32_e32 v25, v25, v33, vcc
	v_readlane_b32 s1, v26, 26
	v_readlane_b32 s20, v26, 58
	v_mul_f32_e32 v33, v37, v25
	v_mov_b32_e32 v35, s1
	v_mov_b32_e32 v25, s20
	v_cndmask_b32_e32 v25, v25, v35, vcc
	v_readlane_b32 s1, v26, 27
	v_readlane_b32 s20, v26, 59
	v_mul_f32_e32 v35, v39, v25
	v_mov_b32_e32 v36, s1
	v_mov_b32_e32 v25, s20
	v_cndmask_b32_e32 v25, v25, v36, vcc
	v_readlane_b32 s1, v26, 28
	v_readlane_b32 s20, v26, 60
	v_mul_f32_e32 v36, v40, v25
	v_mov_b32_e32 v37, s1
	v_mov_b32_e32 v25, s20
	v_cndmask_b32_e32 v25, v25, v37, vcc
	v_readlane_b32 s1, v26, 29
	v_readlane_b32 s20, v26, 61
	v_mul_f32_e32 v18, v18, v25
	v_mov_b32_e32 v37, s1
	v_mov_b32_e32 v25, s20
	v_cndmask_b32_e32 v25, v25, v37, vcc
	v_readlane_b32 s1, v26, 30
	v_readlane_b32 s20, v26, 62
	v_mul_f32_e32 v19, v19, v25
	v_mov_b32_e32 v37, s1
	v_mov_b32_e32 v25, s20
	v_cndmask_b32_e32 v25, v25, v37, vcc
	v_readlane_b32 s1, v26, 31
	v_readlane_b32 s20, v26, 63
	v_mul_f32_e32 v37, v20, v25
	v_mov_b32_e32 v25, s1
	v_mov_b32_e32 v20, s20
	v_cndmask_b32_e32 v20, v20, v25, vcc
	v_mul_f32_e32 v26, v21, v20
	v_cvt_pk_bf16_f32 v25, v22, v23
	v_cvt_pk_bf16_f32 v24, v24, v27
	v_cvt_pk_bf16_f32 v23, v28, v29
	s_lshl_b32 s20, s0, 8
	v_lshlrev_b32_e32 v20, 16, v25
	v_and_b32_e32 v21, 0xffff0000, v25
	v_max_f32_e64 v21, |v21|, |v21|
	v_max_f32_e64 v20, |v20|, |v20|
	v_max_f32_e32 v20, v20, v21
	v_lshlrev_b32_e32 v21, 16, v24
	v_and_b32_e32 v22, 0xffff0000, v24
	v_max_f32_e64 v22, |v22|, |v22|
	v_max_f32_e64 v21, |v21|, |v21|
	v_max_f32_e32 v21, v21, v22
	v_max3_f32 v38, v38, v20, v21
	v_lshlrev_b32_e32 v20, 16, v23
	v_and_b32_e32 v21, 0xffff0000, v23
	v_max_f32_e64 v28, |v21|, |v21|
	v_max_f32_e64 v29, |v20|, |v20|
	v_cvt_pk_bf16_f32 v22, v30, v31
	v_cvt_pk_bf16_f32 v21, v32, v33
	v_cvt_pk_bf16_f32 v20, v35, v36
	v_cvt_pk_bf16_f32 v19, v18, v19
	v_cvt_pk_bf16_f32 v18, v37, v26
	v_lshl_add_u64 v[26:27], v[6:7], 0, s[20:21]
	s_mul_i32 s20, s0, 0x104
	global_load_dword v35, v[26:27], off
	v_max_f32_e32 v28, v29, v28
	v_lshlrev_b32_e32 v29, 16, v22
	v_and_b32_e32 v30, 0xffff0000, v22
	v_lshl_add_u64 v[26:27], v[6:7], 0, s[20:21]
	global_load_dword v36, v[26:27], off
	v_max_f32_e64 v26, |v30|, |v30|
	v_max_f32_e64 v27, |v29|, |v29|
	s_mul_i32 s20, s0, 0x108
	v_max_f32_e32 v29, v27, v26
	v_lshl_add_u64 v[26:27], v[6:7], 0, s[20:21]
	s_mul_i32 s20, s0, 0x10c
	global_load_dword v37, v[26:27], off
	v_max3_f32 v28, v38, v28, v29
	v_lshlrev_b32_e32 v29, 16, v21
	v_and_b32_e32 v30, 0xffff0000, v21
	v_lshl_add_u64 v[26:27], v[6:7], 0, s[20:21]
	global_load_dword v38, v[26:27], off
	v_max_f32_e64 v26, |v30|, |v30|
	v_max_f32_e64 v27, |v29|, |v29|
	s_mul_i32 s20, s0, 0x110
	v_max_f32_e32 v29, v27, v26
	v_lshl_add_u64 v[26:27], v[6:7], 0, s[20:21]
	global_load_dword v39, v[26:27], off
	v_and_b32_e32 v26, 0xffff0000, v20
	s_mul_i32 s20, s0, 0x114
	v_lshlrev_b32_e32 v30, 16, v20
	v_max_f32_e64 v31, |v26|, |v26|
	v_lshl_add_u64 v[26:27], v[6:7], 0, s[20:21]
	global_load_dword v40, v[26:27], off
	v_max_f32_e64 v26, |v30|, |v30|
	v_max_f32_e32 v26, v26, v31
	s_mul_i32 s20, s0, 0x118
	v_max3_f32 v28, v28, v29, v26
	v_lshl_add_u64 v[26:27], v[6:7], 0, s[20:21]
	global_load_dword v41, v[26:27], off
	v_and_b32_e32 v26, 0xffff0000, v19
	s_mul_i32 s20, s0, 0x11c
	v_lshlrev_b32_e32 v29, 16, v19
	v_max_f32_e64 v30, |v26|, |v26|
	v_lshl_add_u64 v[26:27], v[6:7], 0, s[20:21]
	global_load_dword v42, v[26:27], off
	v_max_f32_e64 v26, |v29|, |v29|
	s_mul_i32 s20, s0, 0x120
	v_max_f32_e32 v29, v26, v30
	v_lshl_add_u64 v[26:27], v[6:7], 0, s[20:21]
	v_lshlrev_b32_e32 v30, 16, v18
	global_load_dword v43, v[26:27], off
	v_and_b32_e32 v26, 0xffff0000, v18
	s_mul_i32 s20, s0, 0x124
	v_max_f32_e64 v31, |v26|, |v26|
	v_max_f32_e64 v30, |v30|, |v30|
	v_lshl_add_u64 v[26:27], v[6:7], 0, s[20:21]
	global_load_dword v44, v[26:27], off
	v_max_f32_e32 v26, v30, v31
	s_mul_i32 s20, s0, 0x128
	v_max3_f32 v45, v28, v29, v26
	v_lshl_add_u64 v[26:27], v[6:7], 0, s[20:21]
	global_load_dword v46, v[26:27], off
	s_mul_i32 s20, s0, 0x12c
	v_lshl_add_u64 v[26:27], v[6:7], 0, s[20:21]
	global_load_dword v47, v[26:27], off
	s_mul_i32 s20, s0, 0x130
	v_lshl_add_u64 v[26:27], v[6:7], 0, s[20:21]
	s_mul_i32 s20, s0, 0x134
	v_lshl_add_u64 v[28:29], v[6:7], 0, s[20:21]
	s_mul_i32 s20, s0, 0x138
	v_lshl_add_u64 v[30:31], v[6:7], 0, s[20:21]
	s_mul_i32 s20, s0, 0x13c
	v_lshl_add_u64 v[32:33], v[6:7], 0, s[20:21]
	global_load_dword v26, v[26:27], off
	s_nop 0
	global_load_dword v27, v[28:29], off
	s_nop 0
	global_load_dword v28, v[30:31], off
	global_load_dword v29, v[32:33], off
	v_readlane_b32 s1, v34, 0
	v_readlane_b32 s20, v34, 32
	s_nop 0
	v_mov_b32_e32 v31, s1
	v_mov_b32_e32 v30, s20
	v_readlane_b32 s1, v34, 1
	v_readlane_b32 s20, v34, 33
	v_cndmask_b32_e32 v30, v30, v31, vcc
	v_mov_b32_e32 v32, s1
	v_mov_b32_e32 v31, s20
	v_readlane_b32 s1, v34, 2
	v_readlane_b32 s20, v34, 34
	v_cndmask_b32_e32 v31, v31, v32, vcc
	v_mov_b32_e32 v33, s1
	v_mov_b32_e32 v32, s20
	v_readlane_b32 s1, v34, 3
	v_readlane_b32 s20, v34, 35
	s_waitcnt vmcnt(0) lgkmcnt(0)
	v_mul_f32_e32 v30, v35, v30
	v_cndmask_b32_e32 v32, v32, v33, vcc
	v_mov_b32_e32 v33, s20
	v_mov_b32_e32 v35, s1
	v_cndmask_b32_e32 v33, v33, v35, vcc
	v_readlane_b32 s1, v34, 4
	v_readlane_b32 s20, v34, 36
	v_mul_f32_e32 v31, v36, v31
	v_mov_b32_e32 v36, s1
	v_mul_f32_e32 v35, v38, v33
	v_mov_b32_e32 v33, s20
	v_cndmask_b32_e32 v33, v33, v36, vcc
	v_readlane_b32 s1, v34, 5
	v_readlane_b32 s20, v34, 37
	v_mul_f32_e32 v32, v37, v32
	v_mul_f32_e32 v36, v39, v33
	v_mov_b32_e32 v33, s20
	v_mov_b32_e32 v37, s1
	v_cndmask_b32_e32 v33, v33, v37, vcc
	v_readlane_b32 s1, v34, 6
	v_readlane_b32 s20, v34, 38
	v_mul_f32_e32 v37, v40, v33
	v_mov_b32_e32 v38, s1
	v_mov_b32_e32 v33, s20
	v_cndmask_b32_e32 v33, v33, v38, vcc
	v_readlane_b32 s1, v34, 7
	v_readlane_b32 s20, v34, 39
	v_mul_f32_e32 v38, v41, v33
	v_mov_b32_e32 v39, s1
	v_mov_b32_e32 v33, s20
	v_cndmask_b32_e32 v33, v33, v39, vcc
	v_readlane_b32 s1, v34, 8
	v_readlane_b32 s20, v34, 40
	v_mul_f32_e32 v39, v42, v33
	v_mov_b32_e32 v40, s1
	v_mov_b32_e32 v33, s20
	v_cndmask_b32_e32 v33, v33, v40, vcc
	v_readlane_b32 s1, v34, 9
	v_readlane_b32 s20, v34, 41
	v_mul_f32_e32 v40, v43, v33
	v_mov_b32_e32 v41, s1
	v_mov_b32_e32 v33, s20
	v_cndmask_b32_e32 v33, v33, v41, vcc
	v_readlane_b32 s1, v34, 10
	v_readlane_b32 s20, v34, 42
	v_mul_f32_e32 v41, v44, v33
	v_mov_b32_e32 v42, s1
	v_mov_b32_e32 v33, s20
	v_cndmask_b32_e32 v33, v33, v42, vcc
	v_readlane_b32 s1, v34, 11
	v_readlane_b32 s20, v34, 43
	v_mul_f32_e32 v42, v46, v33
	v_mov_b32_e32 v43, s1
	v_mov_b32_e32 v33, s20
	v_cndmask_b32_e32 v33, v33, v43, vcc
	v_readlane_b32 s1, v34, 12
	v_readlane_b32 s20, v34, 44
	v_mul_f32_e32 v43, v47, v33
	v_mov_b32_e32 v44, s1
	v_mov_b32_e32 v33, s20
	v_cndmask_b32_e32 v33, v33, v44, vcc
	v_readlane_b32 s1, v34, 13
	v_readlane_b32 s20, v34, 45
	v_mul_f32_e32 v26, v26, v33
	v_mov_b32_e32 v44, s1
	v_mov_b32_e32 v33, s20
	v_cndmask_b32_e32 v33, v33, v44, vcc
	v_readlane_b32 s1, v34, 14
	v_readlane_b32 s20, v34, 46
	v_mul_f32_e32 v27, v27, v33
	v_mov_b32_e32 v44, s1
	v_mov_b32_e32 v33, s20
	v_cndmask_b32_e32 v33, v33, v44, vcc
	v_readlane_b32 s1, v34, 15
	v_readlane_b32 s20, v34, 47
	v_mul_f32_e32 v44, v28, v33
	v_mov_b32_e32 v33, s1
	v_mov_b32_e32 v28, s20
	v_cndmask_b32_e32 v28, v28, v33, vcc
	v_mul_f32_e32 v46, v29, v28
	v_cvt_pk_bf16_f32 v33, v30, v31
	v_cvt_pk_bf16_f32 v32, v32, v35
	v_cvt_pk_bf16_f32 v31, v36, v37
	s_mul_i32 s20, s0, 0x140
	v_lshlrev_b32_e32 v28, 16, v33
	v_and_b32_e32 v29, 0xffff0000, v33
	v_max_f32_e64 v29, |v29|, |v29|
	v_max_f32_e64 v28, |v28|, |v28|
	v_max_f32_e32 v28, v28, v29
	v_lshlrev_b32_e32 v29, 16, v32
	v_and_b32_e32 v30, 0xffff0000, v32
	v_max_f32_e64 v30, |v30|, |v30|
	v_max_f32_e64 v29, |v29|, |v29|
	v_max_f32_e32 v29, v29, v30
	v_max3_f32 v35, v45, v28, v29
	v_lshlrev_b32_e32 v28, 16, v31
	v_and_b32_e32 v29, 0xffff0000, v31
	v_max_f32_e64 v45, |v29|, |v29|
	v_max_f32_e64 v47, |v28|, |v28|
	v_cvt_pk_bf16_f32 v30, v38, v39
	v_cvt_pk_bf16_f32 v29, v40, v41
	v_cvt_pk_bf16_f32 v28, v42, v43
	v_cvt_pk_bf16_f32 v27, v26, v27
	v_cvt_pk_bf16_f32 v26, v44, v46
	v_lshl_add_u64 v[36:37], v[6:7], 0, s[20:21]
	s_mul_i32 s20, s0, 0x144
	global_load_dword v44, v[36:37], off
	v_lshlrev_b32_e32 v39, 16, v30
	v_and_b32_e32 v40, 0xffff0000, v30
	v_lshl_add_u64 v[36:37], v[6:7], 0, s[20:21]
	v_max_f32_e32 v38, v47, v45
	global_load_dword v45, v[36:37], off
	v_max_f32_e64 v36, |v40|, |v40|
	v_max_f32_e64 v37, |v39|, |v39|
	s_mul_i32 s20, s0, 0x148
	v_max_f32_e32 v39, v37, v36
	v_lshl_add_u64 v[36:37], v[6:7], 0, s[20:21]
	s_mul_i32 s20, s0, 0x14c
	global_load_dword v46, v[36:37], off
	v_max3_f32 v35, v35, v38, v39
	v_lshlrev_b32_e32 v38, 16, v29
	v_and_b32_e32 v39, 0xffff0000, v29
	v_lshl_add_u64 v[36:37], v[6:7], 0, s[20:21]
	global_load_dword v47, v[36:37], off
	v_max_f32_e64 v36, |v39|, |v39|
	v_max_f32_e64 v37, |v38|, |v38|
	s_mul_i32 s20, s0, 0x150
	v_max_f32_e32 v38, v37, v36
	v_lshl_add_u64 v[36:37], v[6:7], 0, s[20:21]
	global_load_dword v48, v[36:37], off
	v_and_b32_e32 v36, 0xffff0000, v28
	s_mul_i32 s20, s0, 0x154
	v_lshlrev_b32_e32 v39, 16, v28
	v_max_f32_e64 v40, |v36|, |v36|
	v_lshl_add_u64 v[36:37], v[6:7], 0, s[20:21]
	global_load_dword v49, v[36:37], off
	v_max_f32_e64 v36, |v39|, |v39|
	v_max_f32_e32 v36, v36, v40
	s_mul_i32 s20, s0, 0x158
	v_max3_f32 v35, v35, v38, v36
	v_lshl_add_u64 v[36:37], v[6:7], 0, s[20:21]
	global_load_dword v50, v[36:37], off
	v_and_b32_e32 v36, 0xffff0000, v27
	s_mul_i32 s20, s0, 0x15c
	v_lshlrev_b32_e32 v38, 16, v27
	v_max_f32_e64 v39, |v36|, |v36|
	v_lshl_add_u64 v[36:37], v[6:7], 0, s[20:21]
	global_load_dword v51, v[36:37], off
	v_max_f32_e64 v36, |v38|, |v38|
	s_mul_i32 s20, s0, 0x160
	v_max_f32_e32 v38, v36, v39
	v_lshl_add_u64 v[36:37], v[6:7], 0, s[20:21]
	v_lshlrev_b32_e32 v39, 16, v26
	global_load_dword v52, v[36:37], off
	v_and_b32_e32 v36, 0xffff0000, v26
	s_mul_i32 s20, s0, 0x164
	v_max_f32_e64 v40, |v36|, |v36|
	v_max_f32_e64 v39, |v39|, |v39|
	v_lshl_add_u64 v[36:37], v[6:7], 0, s[20:21]
	global_load_dword v53, v[36:37], off
	v_max_f32_e32 v36, v39, v40
	s_mul_i32 s20, s0, 0x168
	v_max3_f32 v35, v35, v38, v36
	v_lshl_add_u64 v[36:37], v[6:7], 0, s[20:21]
	s_mul_i32 s20, s0, 0x16c
	global_load_dword v54, v[36:37], off
	v_lshl_add_u64 v[36:37], v[6:7], 0, s[20:21]
	s_mul_i32 s20, s0, 0x170
	global_load_dword v55, v[36:37], off
	v_lshl_add_u64 v[36:37], v[6:7], 0, s[20:21]
	s_mul_i32 s20, s0, 0x174
	v_lshl_add_u64 v[38:39], v[6:7], 0, s[20:21]
	s_mul_i32 s20, s0, 0x178
	v_lshl_add_u64 v[40:41], v[6:7], 0, s[20:21]
	s_mul_i32 s20, s0, 0x17c
	v_lshl_add_u64 v[42:43], v[6:7], 0, s[20:21]
	global_load_dword v36, v[36:37], off
	s_nop 0
	global_load_dword v37, v[38:39], off
	s_nop 0
	global_load_dword v38, v[40:41], off
	global_load_dword v39, v[42:43], off
	v_readlane_b32 s1, v34, 16
	v_readlane_b32 s20, v34, 48
	s_nop 0
	v_mov_b32_e32 v41, s1
	v_mov_b32_e32 v40, s20
	v_readlane_b32 s1, v34, 17
	v_readlane_b32 s20, v34, 49
	v_cndmask_b32_e32 v40, v40, v41, vcc
	v_mov_b32_e32 v42, s1
	v_mov_b32_e32 v41, s20
	v_readlane_b32 s1, v34, 18
	v_readlane_b32 s20, v34, 50
	v_cndmask_b32_e32 v41, v41, v42, vcc
	v_mov_b32_e32 v43, s1
	v_mov_b32_e32 v42, s20
	v_readlane_b32 s1, v34, 19
	v_readlane_b32 s20, v34, 51
	s_waitcnt vmcnt(0) lgkmcnt(0)
	v_mul_f32_e32 v40, v44, v40
	v_cndmask_b32_e32 v42, v42, v43, vcc
	v_mov_b32_e32 v43, s20
	v_mov_b32_e32 v44, s1
	v_readlane_b32 s1, v34, 20
	v_readlane_b32 s20, v34, 52
	v_mul_f32_e32 v41, v45, v41
	v_cndmask_b32_e32 v43, v43, v44, vcc
	v_mov_b32_e32 v44, s20
	v_mov_b32_e32 v45, s1
	v_readlane_b32 s1, v34, 21
	v_readlane_b32 s20, v34, 53
	v_mul_f32_e32 v42, v46, v42
	v_cndmask_b32_e32 v44, v44, v45, vcc
	v_mov_b32_e32 v45, s20
	v_mov_b32_e32 v46, s1
	v_readlane_b32 s1, v34, 22
	v_readlane_b32 s20, v34, 54
	v_mul_f32_e32 v43, v47, v43
	v_cndmask_b32_e32 v45, v45, v46, vcc
	v_mov_b32_e32 v46, s20
	v_mov_b32_e32 v47, s1
	v_readlane_b32 s1, v34, 23
	v_readlane_b32 s20, v34, 55
	v_mul_f32_e32 v44, v48, v44
	v_cndmask_b32_e32 v46, v46, v47, vcc
	v_mov_b32_e32 v47, s20
	v_mov_b32_e32 v48, s1
	v_readlane_b32 s1, v34, 24
	v_readlane_b32 s20, v34, 56
	v_mul_f32_e32 v45, v49, v45
	v_cndmask_b32_e32 v47, v47, v48, vcc
	v_mov_b32_e32 v48, s20
	v_mov_b32_e32 v49, s1
	v_readlane_b32 s1, v34, 25
	v_readlane_b32 s20, v34, 57
	v_mul_f32_e32 v46, v50, v46
	v_cndmask_b32_e32 v48, v48, v49, vcc
	v_mov_b32_e32 v49, s20
	v_mov_b32_e32 v50, s1
	v_readlane_b32 s1, v34, 26
	v_readlane_b32 s20, v34, 58
	v_mul_f32_e32 v47, v51, v47
	v_cndmask_b32_e32 v49, v49, v50, vcc
	v_mov_b32_e32 v50, s20
	v_mov_b32_e32 v51, s1
	v_readlane_b32 s1, v34, 27
	v_readlane_b32 s20, v34, 59
	v_mul_f32_e32 v48, v52, v48
	v_cndmask_b32_e32 v50, v50, v51, vcc
	v_mov_b32_e32 v51, s20
	v_mov_b32_e32 v52, s1
	v_readlane_b32 s1, v34, 28
	v_readlane_b32 s20, v34, 60
	v_mul_f32_e32 v49, v53, v49
	v_cndmask_b32_e32 v51, v51, v52, vcc
	v_mov_b32_e32 v52, s20
	v_mov_b32_e32 v53, s1
	v_cndmask_b32_e32 v52, v52, v53, vcc
	v_readlane_b32 s1, v34, 29
	v_readlane_b32 s20, v34, 61
	v_mul_f32_e32 v52, v36, v52
	v_mov_b32_e32 v53, s1
	v_mov_b32_e32 v36, s20
	v_cndmask_b32_e32 v36, v36, v53, vcc
	v_readlane_b32 s1, v34, 30
	v_readlane_b32 s20, v34, 62
	v_mul_f32_e32 v53, v37, v36
	v_mov_b32_e32 v37, s1
	v_mov_b32_e32 v36, s20
	v_cndmask_b32_e32 v36, v36, v37, vcc
	v_readlane_b32 s1, v34, 31
	v_readlane_b32 s20, v34, 63
	v_mul_f32_e32 v50, v54, v50
	v_mul_f32_e32 v54, v38, v36
	v_mov_b32_e32 v34, s20
	v_mov_b32_e32 v36, s1
	v_cndmask_b32_e32 v34, v34, v36, vcc
	v_cvt_pk_bf16_f32 v41, v40, v41
	v_cvt_pk_bf16_f32 v40, v42, v43
	v_mul_f32_e32 v51, v55, v51
	v_lshlrev_b32_e32 v36, 16, v41
	v_and_b32_e32 v37, 0xffff0000, v41
	v_max_f32_e64 v37, |v37|, |v37|
	v_max_f32_e64 v36, |v36|, |v36|
	v_max_f32_e32 v36, v36, v37
	v_lshlrev_b32_e32 v37, 16, v40
	v_and_b32_e32 v38, 0xffff0000, v40
	v_max_f32_e64 v38, |v38|, |v38|
	v_max_f32_e64 v37, |v37|, |v37|
	v_max_f32_e32 v37, v37, v38
	v_mul_f32_e32 v34, v39, v34
	v_max3_f32 v55, v35, v36, v37
	v_cvt_pk_bf16_f32 v39, v44, v45
	s_lshl_b32 s20, s0, 9
	v_lshlrev_b32_e32 v35, 16, v39
	v_and_b32_e32 v36, 0xffff0000, v39
	v_max_f32_e64 v44, |v36|, |v36|
	v_max_f32_e64 v45, |v35|, |v35|
	v_cvt_pk_bf16_f32 v38, v46, v47
	v_cvt_pk_bf16_f32 v37, v48, v49
	v_cvt_pk_bf16_f32 v36, v50, v51
	v_cvt_pk_bf16_f32 v35, v52, v53
	v_cvt_pk_bf16_f32 v34, v54, v34
	v_lshl_add_u64 v[42:43], v[6:7], 0, s[20:21]
	s_mul_i32 s20, s0, 0x204
	global_load_dword v54, v[42:43], off
	v_max_f32_e32 v44, v45, v44
	v_lshlrev_b32_e32 v45, 16, v38
	v_and_b32_e32 v46, 0xffff0000, v38
	v_lshl_add_u64 v[42:43], v[6:7], 0, s[20:21]
	global_load_dword v57, v[42:43], off
	v_max_f32_e64 v42, |v46|, |v46|
	v_max_f32_e64 v43, |v45|, |v45|
	s_mul_i32 s20, s0, 0x208
	v_max_f32_e32 v45, v43, v42
	v_lshl_add_u64 v[42:43], v[6:7], 0, s[20:21]
	s_mul_i32 s20, s0, 0x20c
	global_load_dword v58, v[42:43], off
	v_max3_f32 v44, v55, v44, v45
	v_lshlrev_b32_e32 v45, 16, v37
	v_and_b32_e32 v46, 0xffff0000, v37
	v_lshl_add_u64 v[42:43], v[6:7], 0, s[20:21]
	global_load_dword v55, v[42:43], off
	v_max_f32_e64 v42, |v46|, |v46|
	v_max_f32_e64 v43, |v45|, |v45|
	v_max_f32_e32 v42, v43, v42
	v_lshlrev_b32_e32 v43, 16, v36
	v_and_b32_e32 v45, 0xffff0000, v36
	v_max_f32_e64 v45, |v45|, |v45|
	v_max_f32_e64 v43, |v43|, |v43|
	v_max_f32_e32 v43, v43, v45
	v_max3_f32 v44, v44, v42, v43
	v_lshlrev_b32_e32 v42, 16, v35
	v_and_b32_e32 v43, 0xffff0000, v35
	v_max_f32_e64 v43, |v43|, |v43|
	v_max_f32_e64 v42, |v42|, |v42|
	s_mul_i32 s20, s0, 0x210
	v_max_f32_e32 v45, v42, v43
	v_lshlrev_b32_e32 v46, 16, v34
	v_and_b32_e32 v47, 0xffff0000, v34
	v_lshl_add_u64 v[42:43], v[6:7], 0, s[20:21]
	global_load_dword v59, v[42:43], off
	v_max_f32_e64 v42, |v47|, |v47|
	v_max_f32_e64 v43, |v46|, |v46|
	s_mul_i32 s20, s0, 0x214
	v_max_f32_e32 v46, v43, v42
	v_lshl_add_u64 v[42:43], v[6:7], 0, s[20:21]
	s_mul_i32 s20, s0, 0x218
	global_load_dword v60, v[42:43], off
	v_lshl_add_u64 v[42:43], v[6:7], 0, s[20:21]
	s_mul_i32 s20, s0, 0x21c
	v_max3_f32 v61, v44, v45, v46
	v_lshl_add_u64 v[44:45], v[6:7], 0, s[20:21]
	s_mul_i32 s20, s0, 0x220
	global_load_dword v62, v[42:43], off
	global_load_dword v63, v[44:45], off
	v_lshl_add_u64 v[42:43], v[6:7], 0, s[20:21]
	s_mul_i32 s20, s0, 0x224
	v_lshl_add_u64 v[44:45], v[6:7], 0, s[20:21]
	s_mul_i32 s20, s0, 0x228
	v_lshl_add_u64 v[46:47], v[6:7], 0, s[20:21]
	s_mul_i32 s20, s0, 0x22c
	global_load_dword v64, v[42:43], off
	global_load_dword v65, v[44:45], off
	v_lshl_add_u64 v[42:43], v[6:7], 0, s[20:21]
	s_mul_i32 s20, s0, 0x230
	v_lshl_add_u64 v[44:45], v[6:7], 0, s[20:21]
	s_mul_i32 s20, s0, 0x234
	v_lshl_add_u64 v[48:49], v[6:7], 0, s[20:21]
	s_mul_i32 s20, s0, 0x238
	v_lshl_add_u64 v[50:51], v[6:7], 0, s[20:21]
	s_mul_i32 s20, s0, 0x23c
	v_lshl_add_u64 v[52:53], v[6:7], 0, s[20:21]
	global_load_dword v46, v[46:47], off
	s_nop 0
	global_load_dword v47, v[42:43], off
	s_nop 0
	global_load_dword v44, v[44:45], off
	s_nop 0
	global_load_dword v45, v[48:49], off
	s_nop 0
	global_load_dword v48, v[50:51], off
	global_load_dword v49, v[52:53], off
	v_readlane_b32 s1, v56, 0
	v_readlane_b32 s20, v56, 32
	s_nop 0
	v_mov_b32_e32 v43, s1
	v_mov_b32_e32 v42, s20
	v_readlane_b32 s1, v56, 1
	v_readlane_b32 s20, v56, 33
	v_cndmask_b32_e32 v42, v42, v43, vcc
	v_mov_b32_e32 v50, s1
	v_mov_b32_e32 v43, s20
	v_readlane_b32 s1, v56, 2
	v_readlane_b32 s20, v56, 34
	v_cndmask_b32_e32 v43, v43, v50, vcc
	v_mov_b32_e32 v51, s1
	v_mov_b32_e32 v50, s20
	v_readlane_b32 s1, v56, 3
	v_readlane_b32 s20, v56, 35
	s_waitcnt vmcnt(0) lgkmcnt(0)
	v_mul_f32_e32 v42, v54, v42
	v_mul_f32_e32 v43, v57, v43
	v_cndmask_b32_e32 v50, v50, v51, vcc
	v_mov_b32_e32 v51, s20
	v_mov_b32_e32 v52, s1
	v_cndmask_b32_e32 v51, v51, v52, vcc
	v_cvt_pk_bf16_f32 v43, v42, v43
	v_readlane_b32 s1, v56, 4
	v_and_b32_e32 v42, 0xffff0000, v43
	v_lshlrev_b32_e32 v52, 16, v43
	v_mul_f32_e32 v50, v58, v50
	v_max_f32_e64 v42, |v42|, |v42|
	v_max_f32_e64 v52, |v52|, |v52|
	v_mul_f32_e32 v51, v55, v51
	v_max_f32_e32 v52, v52, v42
	v_cvt_pk_bf16_f32 v42, v50, v51
	v_readlane_b32 s20, v56, 36
	v_and_b32_e32 v50, 0xffff0000, v42
	v_lshlrev_b32_e32 v51, 16, v42
	v_max_f32_e64 v50, |v50|, |v50|
	v_max_f32_e64 v51, |v51|, |v51|
	v_max_f32_e32 v50, v51, v50
	v_max3_f32 v52, v61, v52, v50
	v_mov_b32_e32 v50, s20
	v_mov_b32_e32 v51, s1
	v_readlane_b32 s1, v56, 5
	v_readlane_b32 s20, v56, 37
	v_cndmask_b32_e32 v50, v50, v51, vcc
	v_mov_b32_e32 v53, s1
	v_mov_b32_e32 v51, s20
	v_readlane_b32 s1, v56, 6
	v_readlane_b32 s20, v56, 38
	v_cndmask_b32_e32 v51, v51, v53, vcc
	v_mov_b32_e32 v54, s1
	v_mov_b32_e32 v53, s20
	v_readlane_b32 s1, v56, 7
	v_readlane_b32 s20, v56, 39
	v_cndmask_b32_e32 v53, v53, v54, vcc
	v_mov_b32_e32 v55, s1
	v_mov_b32_e32 v54, s20
	v_readlane_b32 s1, v56, 8
	v_readlane_b32 s20, v56, 40
	v_cndmask_b32_e32 v54, v54, v55, vcc
	v_mov_b32_e32 v57, s1
	v_mov_b32_e32 v55, s20
	v_readlane_b32 s1, v56, 9
	v_readlane_b32 s20, v56, 41
	v_cndmask_b32_e32 v55, v55, v57, vcc
	v_mov_b32_e32 v58, s1
	v_mov_b32_e32 v57, s20
	v_readlane_b32 s1, v56, 10
	v_readlane_b32 s20, v56, 42
	v_mul_f32_e32 v50, v59, v50
	v_cndmask_b32_e32 v57, v57, v58, vcc
	v_mov_b32_e32 v58, s20
	v_mov_b32_e32 v59, s1
	v_cndmask_b32_e32 v58, v58, v59, vcc
	v_readlane_b32 s1, v56, 11
	v_readlane_b32 s20, v56, 43
	v_mul_f32_e32 v46, v46, v58
	v_mov_b32_e32 v59, s1
	v_mov_b32_e32 v58, s20
	v_cndmask_b32_e32 v58, v58, v59, vcc
	v_readlane_b32 s1, v56, 12
	v_readlane_b32 s20, v56, 44
	v_mul_f32_e32 v58, v47, v58
	v_mov_b32_e32 v59, s1
	v_mov_b32_e32 v47, s20
	v_cndmask_b32_e32 v47, v47, v59, vcc
	v_readlane_b32 s1, v56, 13
	v_readlane_b32 s20, v56, 45
	v_mul_f32_e32 v44, v44, v47
	v_mov_b32_e32 v59, s1
	v_mov_b32_e32 v47, s20
	v_cndmask_b32_e32 v47, v47, v59, vcc
	v_readlane_b32 s1, v56, 14
	v_readlane_b32 s20, v56, 46
	v_mul_f32_e32 v45, v45, v47
	v_mov_b32_e32 v59, s1
	v_mov_b32_e32 v47, s20
	v_cndmask_b32_e32 v47, v47, v59, vcc
	v_readlane_b32 s1, v56, 15
	v_readlane_b32 s20, v56, 47
	v_mul_f32_e32 v59, v48, v47
	v_mov_b32_e32 v48, s1
	v_mov_b32_e32 v47, s20
	v_cndmask_b32_e32 v47, v47, v48, vcc
	v_mul_f32_e32 v51, v60, v51
	v_mul_f32_e32 v60, v49, v47
	v_cvt_pk_bf16_f32 v49, v50, v51
	s_mul_i32 s20, s0, 0x240
	v_lshlrev_b32_e32 v47, 16, v49
	v_and_b32_e32 v48, 0xffff0000, v49
	v_mul_f32_e32 v53, v62, v53
	v_mul_f32_e32 v54, v63, v54
	v_mul_f32_e32 v55, v64, v55
	v_mul_f32_e32 v57, v65, v57
	v_max_f32_e64 v61, |v48|, |v48|
	v_max_f32_e64 v62, |v47|, |v47|
	v_cvt_pk_bf16_f32 v48, v53, v54
	v_cvt_pk_bf16_f32 v47, v55, v57
	v_cvt_pk_bf16_f32 v46, v46, v58
	v_cvt_pk_bf16_f32 v45, v44, v45
	v_cvt_pk_bf16_f32 v44, v59, v60
	v_lshl_add_u64 v[50:51], v[6:7], 0, s[20:21]
	s_mul_i32 s20, s0, 0x244
	global_load_dword v57, v[50:51], off
	v_lshlrev_b32_e32 v54, 16, v48
	v_and_b32_e32 v55, 0xffff0000, v48
	v_lshl_add_u64 v[50:51], v[6:7], 0, s[20:21]
	global_load_dword v68, v[50:51], off
	v_max_f32_e64 v50, |v55|, |v55|
	v_max_f32_e64 v51, |v54|, |v54|
	s_mul_i32 s20, s0, 0x248
	v_max_f32_e32 v53, v62, v61
	v_max_f32_e32 v54, v51, v50
	v_lshl_add_u64 v[50:51], v[6:7], 0, s[20:21]
	s_mul_i32 s20, s0, 0x24c
	global_load_dword v69, v[50:51], off
	v_max3_f32 v52, v52, v53, v54
	v_lshlrev_b32_e32 v53, 16, v47
	v_and_b32_e32 v54, 0xffff0000, v47
	v_lshl_add_u64 v[50:51], v[6:7], 0, s[20:21]
	global_load_dword v70, v[50:51], off
	v_max_f32_e64 v50, |v54|, |v54|
	v_max_f32_e64 v51, |v53|, |v53|
	v_max_f32_e32 v50, v51, v50
	v_lshlrev_b32_e32 v51, 16, v46
	v_and_b32_e32 v53, 0xffff0000, v46
	v_max_f32_e64 v53, |v53|, |v53|
	v_max_f32_e64 v51, |v51|, |v51|
	v_max_f32_e32 v51, v51, v53
	v_max3_f32 v52, v52, v50, v51
	v_lshlrev_b32_e32 v50, 16, v45
	v_and_b32_e32 v51, 0xffff0000, v45
	v_max_f32_e64 v51, |v51|, |v51|
	v_max_f32_e64 v50, |v50|, |v50|
	s_mul_i32 s20, s0, 0x250
	v_max_f32_e32 v53, v50, v51
	v_lshl_add_u64 v[50:51], v[6:7], 0, s[20:21]
	global_load_dword v71, v[50:51], off
	v_and_b32_e32 v50, 0xffff0000, v44
	v_lshlrev_b32_e32 v51, 16, v44
	v_max_f32_e64 v50, |v50|, |v50|
	v_max_f32_e64 v51, |v51|, |v51|
	s_mul_i32 s20, s0, 0x254
	v_max_f32_e32 v54, v51, v50
	v_lshl_add_u64 v[50:51], v[6:7], 0, s[20:21]
	global_load_dword v73, v[50:51], off
	s_mul_i32 s20, s0, 0x258
	v_lshl_add_u64 v[50:51], v[6:7], 0, s[20:21]
	s_mul_i32 s20, s0, 0x25c
	v_max3_f32 v75, v52, v53, v54
	v_lshl_add_u64 v[52:53], v[6:7], 0, s[20:21]
	global_load_dword v76, v[50:51], off
	global_load_dword v77, v[52:53], off
	s_mul_i32 s20, s0, 0x260
	v_lshl_add_u64 v[50:51], v[6:7], 0, s[20:21]
	s_mul_i32 s20, s0, 0x264
	v_lshl_add_u64 v[52:53], v[6:7], 0, s[20:21]
	s_mul_i32 s20, s0, 0x268
	v_lshl_add_u64 v[54:55], v[6:7], 0, s[20:21]
	s_mul_i32 s20, s0, 0x26c
	v_lshl_add_u64 v[58:59], v[6:7], 0, s[20:21]
	s_mul_i32 s20, s0, 0x270
	v_lshl_add_u64 v[60:61], v[6:7], 0, s[20:21]
	s_mul_i32 s20, s0, 0x274
	v_lshl_add_u64 v[62:63], v[6:7], 0, s[20:21]
	s_mul_i32 s20, s0, 0x278
	v_lshl_add_u64 v[64:65], v[6:7], 0, s[20:21]
	s_mul_i32 s20, s0, 0x27c
	v_lshl_add_u64 v[66:67], v[6:7], 0, s[20:21]
	global_load_dword v78, v[50:51], off
	global_load_dword v79, v[52:53], off
	s_nop 0
	global_load_dword v54, v[54:55], off
	s_nop 0
	global_load_dword v55, v[58:59], off
	s_nop 0
	global_load_dword v58, v[60:61], off
	global_load_dword v59, v[62:63], off
	s_nop 0
	global_load_dword v60, v[64:65], off
	global_load_dword v61, v[66:67], off
	v_readlane_b32 s1, v56, 16
	v_readlane_b32 s20, v56, 48
	s_nop 0
	v_mov_b32_e32 v51, s1
	v_mov_b32_e32 v50, s20
	v_readlane_b32 s1, v56, 17
	v_readlane_b32 s20, v56, 49
	v_cndmask_b32_e32 v50, v50, v51, vcc
	v_mov_b32_e32 v52, s1
	v_mov_b32_e32 v51, s20
	v_readlane_b32 s1, v56, 18
	v_readlane_b32 s20, v56, 50
	v_cndmask_b32_e32 v51, v51, v52, vcc
	v_mov_b32_e32 v53, s1
	v_mov_b32_e32 v52, s20
	v_readlane_b32 s1, v56, 19
	v_readlane_b32 s20, v56, 51
	s_waitcnt vmcnt(0) lgkmcnt(0)
	v_mul_f32_e32 v50, v57, v50
	v_mul_f32_e32 v51, v68, v51
	v_cndmask_b32_e32 v52, v52, v53, vcc
	v_mov_b32_e32 v53, s20
	v_mov_b32_e32 v57, s1
	v_cndmask_b32_e32 v53, v53, v57, vcc
	v_cvt_pk_bf16_f32 v51, v50, v51
	v_readlane_b32 s1, v56, 20
	v_and_b32_e32 v50, 0xffff0000, v51
	v_lshlrev_b32_e32 v57, 16, v51
	v_mul_f32_e32 v52, v69, v52
	v_max_f32_e64 v50, |v50|, |v50|
	v_max_f32_e64 v57, |v57|, |v57|
	v_max_f32_e32 v57, v57, v50
	v_mul_f32_e32 v53, v70, v53
	v_cvt_pk_bf16_f32 v50, v52, v53
	v_readlane_b32 s20, v56, 52
	v_and_b32_e32 v52, 0xffff0000, v50
	v_lshlrev_b32_e32 v53, 16, v50
	v_max_f32_e64 v52, |v52|, |v52|
	v_max_f32_e64 v53, |v53|, |v53|
	v_max_f32_e32 v52, v53, v52
	v_max3_f32 v62, v75, v57, v52
	v_mov_b32_e32 v52, s20
	v_mov_b32_e32 v53, s1
	v_readlane_b32 s1, v56, 21
	v_readlane_b32 s20, v56, 53
	v_cndmask_b32_e32 v52, v52, v53, vcc
	v_mov_b32_e32 v57, s1
	v_mov_b32_e32 v53, s20
	v_readlane_b32 s1, v56, 22
	v_readlane_b32 s20, v56, 54
	v_cndmask_b32_e32 v53, v53, v57, vcc
	v_mov_b32_e32 v63, s1
	v_mov_b32_e32 v57, s20
	v_readlane_b32 s1, v56, 23
	v_readlane_b32 s20, v56, 55
	v_mul_f32_e32 v52, v71, v52
	v_cndmask_b32_e32 v57, v57, v63, vcc
	v_mul_f32_e32 v53, v73, v53
	v_mov_b32_e32 v63, s20
	v_mov_b32_e32 v64, s1
	v_cndmask_b32_e32 v63, v63, v64, vcc
	v_cvt_pk_bf16_f32 v53, v52, v53
	v_mul_f32_e32 v57, v76, v57
	v_and_b32_e32 v52, 0xffff0000, v53
	v_mul_f32_e32 v63, v77, v63
	v_max_f32_e64 v64, |v52|, |v52|
	v_lshlrev_b32_e32 v52, 16, v53
	v_readlane_b32 s1, v56, 24
	v_readlane_b32 s20, v56, 56
	v_max_f32_e64 v65, |v52|, |v52|
	v_cvt_pk_bf16_f32 v52, v57, v63
	v_mov_b32_e32 v63, s1
	v_mov_b32_e32 v57, s20
	v_readlane_b32 s1, v56, 25
	v_readlane_b32 s20, v56, 57
	v_cndmask_b32_e32 v57, v57, v63, vcc
	v_mov_b32_e32 v66, s1
	v_mov_b32_e32 v63, s20
	v_readlane_b32 s1, v56, 26
	v_readlane_b32 s20, v56, 58
	v_cndmask_b32_e32 v63, v63, v66, vcc
	v_mov_b32_e32 v67, s1
	v_mov_b32_e32 v66, s20
	v_cndmask_b32_e32 v66, v66, v67, vcc
	v_readlane_b32 s1, v56, 27
	v_readlane_b32 s20, v56, 59
	v_mul_f32_e32 v54, v54, v66
	v_mov_b32_e32 v67, s1
	v_mov_b32_e32 v66, s20
	v_mul_f32_e32 v57, v78, v57
	v_mul_f32_e32 v63, v79, v63
	v_cndmask_b32_e32 v66, v66, v67, vcc
	v_readlane_b32 s1, v56, 28
	v_readlane_b32 s20, v56, 60
	v_mul_f32_e32 v66, v55, v66
	v_cvt_pk_bf16_f32 v55, v57, v63
	v_mov_b32_e32 v63, s1
	v_mov_b32_e32 v57, s20
	v_cndmask_b32_e32 v57, v57, v63, vcc
	v_readlane_b32 s1, v56, 29
	v_readlane_b32 s20, v56, 61
	v_mul_f32_e32 v57, v58, v57
	v_mov_b32_e32 v63, s1
	v_mov_b32_e32 v58, s20
	v_cndmask_b32_e32 v58, v58, v63, vcc
	v_readlane_b32 s1, v56, 30
	v_readlane_b32 s20, v56, 62
	v_mul_f32_e32 v58, v59, v58
	v_mov_b32_e32 v63, s1
	v_mov_b32_e32 v59, s20
	v_cndmask_b32_e32 v59, v59, v63, vcc
	v_readlane_b32 s1, v56, 31
	v_readlane_b32 s20, v56, 63
	v_mul_f32_e32 v59, v60, v59
	v_mov_b32_e32 v60, s1
	v_mov_b32_e32 v56, s20
	v_cndmask_b32_e32 v56, v56, v60, vcc
	v_mul_f32_e32 v56, v61, v56
	s_mul_i32 s20, s0, 0x300
	v_cvt_pk_bf16_f32 v54, v54, v66
	v_cvt_pk_bf16_f32 v57, v57, v58
	v_cvt_pk_bf16_f32 v56, v59, v56
	v_lshl_add_u64 v[58:59], v[6:7], 0, s[20:21]
	global_load_dword v73, v[58:59], off
	v_and_b32_e32 v58, 0xffff0000, v52
	s_mul_i32 s20, s0, 0x304
	v_max_f32_e64 v61, |v58|, |v58|
	v_lshl_add_u64 v[58:59], v[6:7], 0, s[20:21]
	global_load_dword v75, v[58:59], off
	v_lshlrev_b32_e32 v58, 16, v52
	v_max_f32_e64 v58, |v58|, |v58|
	s_mul_i32 s20, s0, 0x308
	v_max_f32_e32 v61, v58, v61
	v_lshl_add_u64 v[58:59], v[6:7], 0, s[20:21]
	v_max_f32_e32 v60, v65, v64
	global_load_dword v78, v[58:59], off
	v_and_b32_e32 v58, 0xffff0000, v55
	s_mul_i32 s20, s0, 0x30c
	v_max3_f32 v60, v62, v60, v61
	v_max_f32_e64 v61, |v58|, |v58|
	v_lshl_add_u64 v[58:59], v[6:7], 0, s[20:21]
	global_load_dword v79, v[58:59], off
	v_lshlrev_b32_e32 v58, 16, v55
	v_max_f32_e64 v58, |v58|, |v58|
	v_max_f32_e32 v58, v58, v61
	v_and_b32_e32 v59, 0xffff0000, v54
	v_lshlrev_b32_e32 v61, 16, v54
	v_max_f32_e64 v59, |v59|, |v59|
	v_max_f32_e64 v61, |v61|, |v61|
	v_max_f32_e32 v59, v61, v59
	v_max3_f32 v60, v60, v58, v59
	v_and_b32_e32 v58, 0xffff0000, v57
	v_lshlrev_b32_e32 v59, 16, v57
	v_max_f32_e64 v58, |v58|, |v58|
	v_max_f32_e64 v59, |v59|, |v59|
	v_max_f32_e32 v61, v59, v58
	v_and_b32_e32 v58, 0xffff0000, v56
	s_mul_i32 s20, s0, 0x310
	v_max_f32_e64 v62, |v58|, |v58|
	v_lshl_add_u64 v[58:59], v[6:7], 0, s[20:21]
	global_load_dword v80, v[58:59], off
	v_lshlrev_b32_e32 v58, 16, v56
	v_max_f32_e64 v58, |v58|, |v58|
	s_mul_i32 s20, s0, 0x314
	v_max_f32_e32 v62, v58, v62
	v_lshl_add_u64 v[58:59], v[6:7], 0, s[20:21]
	global_load_dword v81, v[58:59], off
	s_mul_i32 s20, s0, 0x318
	v_lshl_add_u64 v[58:59], v[6:7], 0, s[20:21]
	s_mul_i32 s20, s0, 0x31c
	v_max3_f32 v82, v60, v61, v62
	v_lshl_add_u64 v[60:61], v[6:7], 0, s[20:21]
	global_load_dword v83, v[58:59], off
	global_load_dword v84, v[60:61], off
	s_mul_i32 s20, s0, 0x320
	v_lshl_add_u64 v[58:59], v[6:7], 0, s[20:21]
	s_mul_i32 s20, s0, 0x324
	v_lshl_add_u64 v[60:61], v[6:7], 0, s[20:21]
	s_mul_i32 s20, s0, 0x328
	v_lshl_add_u64 v[62:63], v[6:7], 0, s[20:21]
	s_mul_i32 s20, s0, 0x32c
	v_lshl_add_u64 v[64:65], v[6:7], 0, s[20:21]
	s_mul_i32 s20, s0, 0x330
	v_lshl_add_u64 v[66:67], v[6:7], 0, s[20:21]
	s_mul_i32 s20, s0, 0x334
	v_lshl_add_u64 v[68:69], v[6:7], 0, s[20:21]
	s_mul_i32 s20, s0, 0x338
	v_lshl_add_u64 v[70:71], v[6:7], 0, s[20:21]
	s_mul_i32 s20, s0, 0x33c
	v_lshl_add_u64 v[76:77], v[6:7], 0, s[20:21]
	global_load_dword v85, v[58:59], off
	global_load_dword v86, v[60:61], off
	s_nop 0
	global_load_dword v62, v[62:63], off
	s_nop 0
	global_load_dword v63, v[64:65], off
	s_nop 0
	global_load_dword v64, v[66:67], off
	global_load_dword v65, v[68:69], off
	s_nop 0
	global_load_dword v66, v[70:71], off
	global_load_dword v67, v[76:77], off
	v_readlane_b32 s1, v72, 0
	v_readlane_b32 s20, v72, 32
	s_nop 0
	v_mov_b32_e32 v59, s1
	v_mov_b32_e32 v58, s20
	v_readlane_b32 s1, v72, 1
	v_readlane_b32 s20, v72, 33
	v_cndmask_b32_e32 v58, v58, v59, vcc
	v_mov_b32_e32 v60, s1
	v_mov_b32_e32 v59, s20
	v_readlane_b32 s1, v72, 2
	v_readlane_b32 s20, v72, 34
	v_cndmask_b32_e32 v59, v59, v60, vcc
	v_mov_b32_e32 v61, s1
	v_mov_b32_e32 v60, s20
	v_readlane_b32 s1, v72, 3
	v_readlane_b32 s20, v72, 35
	s_waitcnt vmcnt(0) lgkmcnt(0)
	v_mul_f32_e32 v58, v73, v58
	v_mul_f32_e32 v59, v75, v59
	v_cndmask_b32_e32 v60, v60, v61, vcc
	v_mov_b32_e32 v61, s20
	v_mov_b32_e32 v68, s1
	v_cndmask_b32_e32 v61, v61, v68, vcc
	v_cvt_pk_bf16_f32 v59, v58, v59
	v_readlane_b32 s1, v72, 4
	v_and_b32_e32 v58, 0xffff0000, v59
	v_lshlrev_b32_e32 v68, 16, v59
	v_mul_f32_e32 v60, v78, v60
	v_max_f32_e64 v58, |v58|, |v58|
	v_max_f32_e64 v68, |v68|, |v68|
	v_max_f32_e32 v68, v68, v58
	v_mul_f32_e32 v61, v79, v61
	v_cvt_pk_bf16_f32 v58, v60, v61
	v_readlane_b32 s20, v72, 36
	v_and_b32_e32 v60, 0xffff0000, v58
	v_lshlrev_b32_e32 v61, 16, v58
	v_max_f32_e64 v60, |v60|, |v60|
	v_max_f32_e64 v61, |v61|, |v61|
	v_max_f32_e32 v60, v61, v60
	v_max3_f32 v68, v82, v68, v60
	v_mov_b32_e32 v60, s20
	v_mov_b32_e32 v61, s1
	v_readlane_b32 s1, v72, 5
	v_readlane_b32 s20, v72, 37
	v_cndmask_b32_e32 v60, v60, v61, vcc
	v_mov_b32_e32 v69, s1
	v_mov_b32_e32 v61, s20
	v_readlane_b32 s1, v72, 6
	v_readlane_b32 s20, v72, 38
	v_cndmask_b32_e32 v61, v61, v69, vcc
	v_mov_b32_e32 v70, s1
	v_mov_b32_e32 v69, s20
	v_readlane_b32 s1, v72, 7
	v_readlane_b32 s20, v72, 39
	v_mul_f32_e32 v60, v80, v60
	v_cndmask_b32_e32 v69, v69, v70, vcc
	v_mul_f32_e32 v61, v81, v61
	v_mov_b32_e32 v70, s20
	v_mov_b32_e32 v71, s1
	v_cndmask_b32_e32 v70, v70, v71, vcc
	v_cvt_pk_bf16_f32 v61, v60, v61
	v_mul_f32_e32 v69, v83, v69
	v_and_b32_e32 v60, 0xffff0000, v61
	v_mul_f32_e32 v70, v84, v70
	v_max_f32_e64 v71, |v60|, |v60|
	v_lshlrev_b32_e32 v60, 16, v61
	v_readlane_b32 s1, v72, 8
	v_readlane_b32 s20, v72, 40
	v_max_f32_e64 v73, |v60|, |v60|
	v_cvt_pk_bf16_f32 v60, v69, v70
	v_mov_b32_e32 v70, s1
	v_mov_b32_e32 v69, s20
	v_readlane_b32 s1, v72, 9
	v_readlane_b32 s20, v72, 41
	v_cndmask_b32_e32 v69, v69, v70, vcc
	v_mov_b32_e32 v75, s1
	v_mov_b32_e32 v70, s20
	v_readlane_b32 s1, v72, 10
	v_readlane_b32 s20, v72, 42
	v_cndmask_b32_e32 v70, v70, v75, vcc
	v_mov_b32_e32 v76, s1
	v_mov_b32_e32 v75, s20
	v_cndmask_b32_e32 v75, v75, v76, vcc
	v_readlane_b32 s1, v72, 11
	v_readlane_b32 s20, v72, 43
	v_mul_f32_e32 v62, v62, v75
	v_mov_b32_e32 v76, s1
	v_mov_b32_e32 v75, s20
	v_mul_f32_e32 v69, v85, v69
	v_mul_f32_e32 v70, v86, v70
	v_cndmask_b32_e32 v75, v75, v76, vcc
	v_readlane_b32 s1, v72, 12
	v_readlane_b32 s20, v72, 44
	v_mul_f32_e32 v75, v63, v75
	v_cvt_pk_bf16_f32 v63, v69, v70
	v_mov_b32_e32 v70, s1
	v_mov_b32_e32 v69, s20
	v_cndmask_b32_e32 v69, v69, v70, vcc
	v_readlane_b32 s1, v72, 13
	v_readlane_b32 s20, v72, 45
	v_mul_f32_e32 v64, v64, v69
	v_mov_b32_e32 v70, s1
	v_mov_b32_e32 v69, s20
	v_cndmask_b32_e32 v69, v69, v70, vcc
	v_readlane_b32 s1, v72, 14
	v_readlane_b32 s20, v72, 46
	v_mul_f32_e32 v65, v65, v69
	v_mov_b32_e32 v70, s1
	v_mov_b32_e32 v69, s20
	v_cndmask_b32_e32 v69, v69, v70, vcc
	v_readlane_b32 s1, v72, 15
	v_readlane_b32 s20, v72, 47
	v_mul_f32_e32 v66, v66, v69
	v_mov_b32_e32 v70, s1
	v_mov_b32_e32 v69, s20
	v_cndmask_b32_e32 v69, v69, v70, vcc
	v_mul_f32_e32 v67, v67, v69
	s_mul_i32 s20, s0, 0x340
	v_cvt_pk_bf16_f32 v62, v62, v75
	v_cvt_pk_bf16_f32 v65, v64, v65
	v_cvt_pk_bf16_f32 v64, v66, v67
	v_lshl_add_u64 v[66:67], v[6:7], 0, s[20:21]
	global_load_dword v75, v[66:67], off
	v_and_b32_e32 v66, 0xffff0000, v60
	s_mul_i32 s20, s0, 0x344
	v_max_f32_e64 v70, |v66|, |v66|
	v_lshl_add_u64 v[66:67], v[6:7], 0, s[20:21]
	v_max_f32_e32 v69, v73, v71
	global_load_dword v73, v[66:67], off
	v_lshlrev_b32_e32 v66, 16, v60
	v_max_f32_e64 v66, |v66|, |v66|
	s_mul_i32 s20, s0, 0x348
	v_max_f32_e32 v70, v66, v70
	v_lshl_add_u64 v[66:67], v[6:7], 0, s[20:21]
	global_load_dword v86, v[66:67], off
	v_and_b32_e32 v66, 0xffff0000, v63
	s_mul_i32 s20, s0, 0x34c
	v_max3_f32 v68, v68, v69, v70
	v_max_f32_e64 v69, |v66|, |v66|
	v_lshl_add_u64 v[66:67], v[6:7], 0, s[20:21]
	global_load_dword v87, v[66:67], off
	v_lshlrev_b32_e32 v66, 16, v63
	v_max_f32_e64 v66, |v66|, |v66|
	v_max_f32_e32 v66, v66, v69
	v_and_b32_e32 v67, 0xffff0000, v62
	v_lshlrev_b32_e32 v69, 16, v62
	v_max_f32_e64 v67, |v67|, |v67|
	v_max_f32_e64 v69, |v69|, |v69|
	v_max_f32_e32 v67, v69, v67
	v_max3_f32 v68, v68, v66, v67
	v_and_b32_e32 v66, 0xffff0000, v65
	v_lshlrev_b32_e32 v67, 16, v65
	v_max_f32_e64 v66, |v66|, |v66|
	v_max_f32_e64 v67, |v67|, |v67|
	v_max_f32_e32 v69, v67, v66
	v_and_b32_e32 v66, 0xffff0000, v64
	s_mul_i32 s20, s0, 0x350
	v_max_f32_e64 v70, |v66|, |v66|
	v_lshl_add_u64 v[66:67], v[6:7], 0, s[20:21]
	global_load_dword v88, v[66:67], off
	v_lshlrev_b32_e32 v66, 16, v64
	v_max_f32_e64 v66, |v66|, |v66|
	s_mul_i32 s20, s0, 0x354
	v_max_f32_e32 v70, v66, v70
	v_lshl_add_u64 v[66:67], v[6:7], 0, s[20:21]
	global_load_dword v90, v[66:67], off
	s_mul_i32 s20, s0, 0x358
	v_lshl_add_u64 v[66:67], v[6:7], 0, s[20:21]
	s_mul_i32 s20, s0, 0x35c
	v_max3_f32 v91, v68, v69, v70
	v_lshl_add_u64 v[68:69], v[6:7], 0, s[20:21]
	global_load_dword v92, v[66:67], off
	global_load_dword v93, v[68:69], off
	s_mul_i32 s20, s0, 0x360
	v_lshl_add_u64 v[66:67], v[6:7], 0, s[20:21]
	s_mul_i32 s20, s0, 0x364
	v_lshl_add_u64 v[68:69], v[6:7], 0, s[20:21]
	s_mul_i32 s20, s0, 0x368
	v_lshl_add_u64 v[70:71], v[6:7], 0, s[20:21]
	s_mul_i32 s20, s0, 0x36c
	v_lshl_add_u64 v[76:77], v[6:7], 0, s[20:21]
	s_mul_i32 s20, s0, 0x370
	v_lshl_add_u64 v[78:79], v[6:7], 0, s[20:21]
	s_mul_i32 s20, s0, 0x374
	v_lshl_add_u64 v[80:81], v[6:7], 0, s[20:21]
	s_mul_i32 s20, s0, 0x378
	v_lshl_add_u64 v[82:83], v[6:7], 0, s[20:21]
	s_mul_i32 s20, s0, 0x37c
	v_lshl_add_u64 v[84:85], v[6:7], 0, s[20:21]
	global_load_dword v94, v[66:67], off
	global_load_dword v95, v[68:69], off
	s_nop 0
	global_load_dword v70, v[70:71], off
	s_nop 0
	global_load_dword v71, v[76:77], off
	s_nop 0
	global_load_dword v76, v[78:79], off
	global_load_dword v77, v[80:81], off
	s_nop 0
	global_load_dword v78, v[82:83], off
	global_load_dword v79, v[84:85], off
	v_readlane_b32 s1, v72, 16
	v_readlane_b32 s20, v72, 48
	s_nop 0
	v_mov_b32_e32 v67, s1
	v_mov_b32_e32 v66, s20
	v_readlane_b32 s1, v72, 17
	v_readlane_b32 s20, v72, 49
	v_cndmask_b32_e32 v66, v66, v67, vcc
	v_mov_b32_e32 v68, s1
	v_mov_b32_e32 v67, s20
	v_readlane_b32 s1, v72, 18
	v_readlane_b32 s20, v72, 50
	v_cndmask_b32_e32 v67, v67, v68, vcc
	v_mov_b32_e32 v69, s1
	v_mov_b32_e32 v68, s20
	v_readlane_b32 s1, v72, 19
	v_readlane_b32 s20, v72, 51
	s_waitcnt vmcnt(0) lgkmcnt(0)
	v_mul_f32_e32 v66, v75, v66
	v_cndmask_b32_e32 v68, v68, v69, vcc
	v_mul_f32_e32 v67, v73, v67
	v_mov_b32_e32 v69, s20
	v_mov_b32_e32 v73, s1
	v_cndmask_b32_e32 v69, v69, v73, vcc
	v_cvt_pk_bf16_f32 v67, v66, v67
	v_readlane_b32 s1, v72, 20
	v_and_b32_e32 v66, 0xffff0000, v67
	v_lshlrev_b32_e32 v73, 16, v67
	v_mul_f32_e32 v68, v86, v68
	v_max_f32_e64 v66, |v66|, |v66|
	v_max_f32_e64 v73, |v73|, |v73|
	v_max_f32_e32 v73, v73, v66
	v_mul_f32_e32 v69, v87, v69
	v_cvt_pk_bf16_f32 v66, v68, v69
	v_readlane_b32 s20, v72, 52
	v_and_b32_e32 v68, 0xffff0000, v66
	v_lshlrev_b32_e32 v69, 16, v66
	v_max_f32_e64 v68, |v68|, |v68|
	v_max_f32_e64 v69, |v69|, |v69|
	v_max_f32_e32 v68, v69, v68
	v_max3_f32 v75, v91, v73, v68
	v_mov_b32_e32 v68, s20
	v_mov_b32_e32 v69, s1
	v_readlane_b32 s1, v72, 21
	v_readlane_b32 s20, v72, 53
	v_cndmask_b32_e32 v68, v68, v69, vcc
	v_mov_b32_e32 v73, s1
	v_mov_b32_e32 v69, s20
	v_readlane_b32 s1, v72, 22
	v_readlane_b32 s20, v72, 54
	v_cndmask_b32_e32 v69, v69, v73, vcc
	v_mov_b32_e32 v80, s1
	v_mov_b32_e32 v73, s20
	v_readlane_b32 s1, v72, 23
	v_readlane_b32 s20, v72, 55
	v_mul_f32_e32 v68, v88, v68
	v_cndmask_b32_e32 v73, v73, v80, vcc
	v_mul_f32_e32 v69, v90, v69
	v_mov_b32_e32 v80, s20
	v_mov_b32_e32 v81, s1
	v_cndmask_b32_e32 v80, v80, v81, vcc
	v_cvt_pk_bf16_f32 v69, v68, v69
	v_mul_f32_e32 v73, v92, v73
	v_and_b32_e32 v68, 0xffff0000, v69
	v_mul_f32_e32 v80, v93, v80
	v_max_f32_e64 v81, |v68|, |v68|
	v_lshlrev_b32_e32 v68, 16, v69
	v_readlane_b32 s1, v72, 24
	v_readlane_b32 s20, v72, 56
	v_max_f32_e64 v82, |v68|, |v68|
	v_cvt_pk_bf16_f32 v68, v73, v80
	v_mov_b32_e32 v80, s1
	v_mov_b32_e32 v73, s20
	v_readlane_b32 s1, v72, 25
	v_readlane_b32 s20, v72, 57
	v_cndmask_b32_e32 v73, v73, v80, vcc
	v_mov_b32_e32 v83, s1
	v_mov_b32_e32 v80, s20
	v_readlane_b32 s1, v72, 26
	v_readlane_b32 s20, v72, 58
	v_cndmask_b32_e32 v80, v80, v83, vcc
	v_mov_b32_e32 v84, s1
	v_mov_b32_e32 v83, s20
	v_cndmask_b32_e32 v83, v83, v84, vcc
	v_readlane_b32 s1, v72, 27
	v_readlane_b32 s20, v72, 59
	v_mul_f32_e32 v70, v70, v83
	v_mov_b32_e32 v84, s1
	v_mov_b32_e32 v83, s20
	v_mul_f32_e32 v73, v94, v73
	v_mul_f32_e32 v80, v95, v80
	v_cndmask_b32_e32 v83, v83, v84, vcc
	v_readlane_b32 s1, v72, 28
	v_readlane_b32 s20, v72, 60
	v_mul_f32_e32 v83, v71, v83
	v_cvt_pk_bf16_f32 v71, v73, v80
	v_mov_b32_e32 v80, s1
	v_mov_b32_e32 v73, s20
	v_cndmask_b32_e32 v73, v73, v80, vcc
	v_readlane_b32 s1, v72, 29
	v_readlane_b32 s20, v72, 61
	v_mul_f32_e32 v73, v76, v73
	v_mov_b32_e32 v80, s1
	v_mov_b32_e32 v76, s20
	v_cndmask_b32_e32 v76, v76, v80, vcc
	v_readlane_b32 s1, v72, 30
	v_readlane_b32 s20, v72, 62
	v_mul_f32_e32 v76, v77, v76
	v_mov_b32_e32 v80, s1
	v_mov_b32_e32 v77, s20
	v_cndmask_b32_e32 v77, v77, v80, vcc
	v_readlane_b32 s1, v72, 31
	v_readlane_b32 s20, v72, 63
	v_mul_f32_e32 v77, v78, v77
	v_mov_b32_e32 v78, s1
	v_mov_b32_e32 v72, s20
	v_cndmask_b32_e32 v72, v72, v78, vcc
	v_mul_f32_e32 v72, v79, v72
	s_lshl_b32 s20, s0, 10
	v_cvt_pk_bf16_f32 v70, v70, v83
	v_cvt_pk_bf16_f32 v73, v73, v76
	v_cvt_pk_bf16_f32 v72, v77, v72
	v_lshl_add_u64 v[76:77], v[6:7], 0, s[20:21]
	global_load_dword v88, v[76:77], off
	v_and_b32_e32 v76, 0xffff0000, v68
	s_mul_i32 s20, s0, 0x404
	v_max_f32_e64 v79, |v76|, |v76|
	v_lshl_add_u64 v[76:77], v[6:7], 0, s[20:21]
	global_load_dword v94, v[76:77], off
	v_lshlrev_b32_e32 v76, 16, v68
	v_max_f32_e64 v76, |v76|, |v76|
	s_mul_i32 s20, s0, 0x408
	v_max_f32_e32 v79, v76, v79
	v_lshl_add_u64 v[76:77], v[6:7], 0, s[20:21]
	v_max_f32_e32 v78, v82, v81
	global_load_dword v95, v[76:77], off
	v_and_b32_e32 v76, 0xffff0000, v71
	s_mul_i32 s20, s0, 0x40c
	v_max3_f32 v75, v75, v78, v79
	v_max_f32_e64 v78, |v76|, |v76|
	v_lshl_add_u64 v[76:77], v[6:7], 0, s[20:21]
	global_load_dword v96, v[76:77], off
	v_lshlrev_b32_e32 v76, 16, v71
	v_max_f32_e64 v76, |v76|, |v76|
	v_max_f32_e32 v76, v76, v78
	v_and_b32_e32 v77, 0xffff0000, v70
	v_lshlrev_b32_e32 v78, 16, v70
	v_max_f32_e64 v77, |v77|, |v77|
	v_max_f32_e64 v78, |v78|, |v78|
	v_max_f32_e32 v77, v78, v77
	v_max3_f32 v75, v75, v76, v77
	v_and_b32_e32 v76, 0xffff0000, v73
	v_lshlrev_b32_e32 v77, 16, v73
	v_max_f32_e64 v76, |v76|, |v76|
	v_max_f32_e64 v77, |v77|, |v77|
	v_max_f32_e32 v78, v77, v76
	v_and_b32_e32 v76, 0xffff0000, v72
	s_mul_i32 s20, s0, 0x410
	v_max_f32_e64 v79, |v76|, |v76|
	v_lshl_add_u64 v[76:77], v[6:7], 0, s[20:21]
	global_load_dword v97, v[76:77], off
	v_lshlrev_b32_e32 v76, 16, v72
	v_max_f32_e64 v76, |v76|, |v76|
	s_mul_i32 s20, s0, 0x414
	v_max_f32_e32 v79, v76, v79
	v_lshl_add_u64 v[76:77], v[6:7], 0, s[20:21]
	global_load_dword v98, v[76:77], off
	s_mul_i32 s20, s0, 0x418
	v_lshl_add_u64 v[76:77], v[6:7], 0, s[20:21]
	s_mul_i32 s20, s0, 0x41c
	v_max3_f32 v99, v75, v78, v79
	v_lshl_add_u64 v[78:79], v[6:7], 0, s[20:21]
	global_load_dword v100, v[76:77], off
	global_load_dword v101, v[78:79], off
	s_mul_i32 s20, s0, 0x420
	v_lshl_add_u64 v[76:77], v[6:7], 0, s[20:21]
	s_mul_i32 s20, s0, 0x424
	v_lshl_add_u64 v[78:79], v[6:7], 0, s[20:21]
	s_mul_i32 s20, s0, 0x428
	v_lshl_add_u64 v[80:81], v[6:7], 0, s[20:21]
	s_mul_i32 s20, s0, 0x42c
	v_lshl_add_u64 v[82:83], v[6:7], 0, s[20:21]
	s_mul_i32 s20, s0, 0x430
	v_lshl_add_u64 v[84:85], v[6:7], 0, s[20:21]
	s_mul_i32 s20, s0, 0x434
	v_lshl_add_u64 v[86:87], v[6:7], 0, s[20:21]
	s_mul_i32 s20, s0, 0x438
	v_lshl_add_u64 v[90:91], v[6:7], 0, s[20:21]
	s_mul_i32 s20, s0, 0x43c
	v_lshl_add_u64 v[92:93], v[6:7], 0, s[20:21]
	global_load_dword v102, v[76:77], off
	s_nop 0
	global_load_dword v79, v[78:79], off
	s_nop 0
	global_load_dword v80, v[80:81], off
	s_nop 0
	global_load_dword v81, v[82:83], off
	s_nop 0
	global_load_dword v82, v[84:85], off
	global_load_dword v83, v[86:87], off
	s_nop 0
	global_load_dword v84, v[90:91], off
	global_load_dword v85, v[92:93], off
	v_readlane_b32 s1, v89, 0
	v_readlane_b32 s20, v89, 32
	s_nop 0
	v_mov_b32_e32 v76, s1
	v_mov_b32_e32 v75, s20
	v_readlane_b32 s1, v89, 1
	v_readlane_b32 s20, v89, 33
	v_cndmask_b32_e32 v75, v75, v76, vcc
	v_mov_b32_e32 v77, s1
	v_mov_b32_e32 v76, s20
	v_readlane_b32 s1, v89, 2
	v_readlane_b32 s20, v89, 34
	v_cndmask_b32_e32 v76, v76, v77, vcc
	v_mov_b32_e32 v78, s1
	v_mov_b32_e32 v77, s20
	v_readlane_b32 s1, v89, 3
	v_readlane_b32 s20, v89, 35
	s_waitcnt vmcnt(0) lgkmcnt(0)
	v_mul_f32_e32 v75, v88, v75
	v_mul_f32_e32 v76, v94, v76
	v_cndmask_b32_e32 v77, v77, v78, vcc
	v_mov_b32_e32 v78, s20
	v_mov_b32_e32 v86, s1
	v_cndmask_b32_e32 v78, v78, v86, vcc
	v_cvt_pk_bf16_f32 v76, v75, v76
	v_readlane_b32 s1, v89, 4
	v_and_b32_e32 v75, 0xffff0000, v76
	v_lshlrev_b32_e32 v86, 16, v76
	v_mul_f32_e32 v77, v95, v77
	v_max_f32_e64 v75, |v75|, |v75|
	v_max_f32_e64 v86, |v86|, |v86|
	v_max_f32_e32 v86, v86, v75
	v_mul_f32_e32 v78, v96, v78
	v_cvt_pk_bf16_f32 v75, v77, v78
	v_readlane_b32 s20, v89, 36
	v_and_b32_e32 v77, 0xffff0000, v75
	v_lshlrev_b32_e32 v78, 16, v75
	v_max_f32_e64 v77, |v77|, |v77|
	v_max_f32_e64 v78, |v78|, |v78|
	v_max_f32_e32 v77, v78, v77
	v_max3_f32 v86, v99, v86, v77
	v_mov_b32_e32 v77, s20
	v_mov_b32_e32 v78, s1
	v_readlane_b32 s1, v89, 5
	v_readlane_b32 s20, v89, 37
	v_cndmask_b32_e32 v77, v77, v78, vcc
	v_mov_b32_e32 v87, s1
	v_mov_b32_e32 v78, s20
	v_readlane_b32 s1, v89, 6
	v_readlane_b32 s20, v89, 38
	v_cndmask_b32_e32 v78, v78, v87, vcc
	v_mov_b32_e32 v88, s1
	v_mov_b32_e32 v87, s20
	v_readlane_b32 s1, v89, 7
	v_readlane_b32 s20, v89, 39
	v_mul_f32_e32 v77, v97, v77
	v_cndmask_b32_e32 v87, v87, v88, vcc
	v_mul_f32_e32 v78, v98, v78
	v_mov_b32_e32 v88, s20
	v_mov_b32_e32 v90, s1
	v_cndmask_b32_e32 v88, v88, v90, vcc
	v_cvt_pk_bf16_f32 v78, v77, v78
	v_mul_f32_e32 v87, v100, v87
	v_and_b32_e32 v77, 0xffff0000, v78
	v_mul_f32_e32 v88, v101, v88
	v_max_f32_e64 v90, |v77|, |v77|
	v_lshlrev_b32_e32 v77, 16, v78
	v_readlane_b32 s1, v89, 8
	v_readlane_b32 s20, v89, 40
	v_max_f32_e64 v91, |v77|, |v77|
	v_cvt_pk_bf16_f32 v77, v87, v88
	v_mov_b32_e32 v88, s1
	v_mov_b32_e32 v87, s20
	v_readlane_b32 s1, v89, 9
	v_readlane_b32 s20, v89, 41
	v_cndmask_b32_e32 v87, v87, v88, vcc
	v_mov_b32_e32 v92, s1
	v_mov_b32_e32 v88, s20
	v_cndmask_b32_e32 v88, v88, v92, vcc
	v_readlane_b32 s1, v89, 10
	v_readlane_b32 s20, v89, 42
	v_mul_f32_e32 v79, v79, v88
	v_mov_b32_e32 v92, s1
	v_mov_b32_e32 v88, s20
	v_cndmask_b32_e32 v88, v88, v92, vcc
	v_readlane_b32 s1, v89, 11
	v_readlane_b32 s20, v89, 43
	v_mul_f32_e32 v88, v80, v88
	v_mov_b32_e32 v92, s1
	v_mov_b32_e32 v80, s20
	v_cndmask_b32_e32 v80, v80, v92, vcc
	v_mul_f32_e32 v87, v102, v87
	v_mul_f32_e32 v81, v81, v80
	v_readlane_b32 s1, v89, 12
	v_readlane_b32 s20, v89, 44
	v_cvt_pk_bf16_f32 v80, v87, v79
	v_cvt_pk_bf16_f32 v79, v88, v81
	s_nop 0
	v_mov_b32_e32 v87, s1
	v_mov_b32_e32 v81, s20
	v_cndmask_b32_e32 v81, v81, v87, vcc
	v_readlane_b32 s1, v89, 13
	v_readlane_b32 s20, v89, 45
	v_mul_f32_e32 v81, v82, v81
	v_mov_b32_e32 v87, s1
	v_mov_b32_e32 v82, s20
	v_cndmask_b32_e32 v82, v82, v87, vcc
	v_readlane_b32 s1, v89, 14
	v_readlane_b32 s20, v89, 46
	v_mul_f32_e32 v82, v83, v82
	v_mov_b32_e32 v87, s1
	v_mov_b32_e32 v83, s20
	v_cndmask_b32_e32 v83, v83, v87, vcc
	v_readlane_b32 s1, v89, 15
	v_readlane_b32 s20, v89, 47
	v_mul_f32_e32 v83, v84, v83
	v_mov_b32_e32 v87, s1
	v_mov_b32_e32 v84, s20
	v_cndmask_b32_e32 v84, v84, v87, vcc
	v_mul_f32_e32 v84, v85, v84
	s_mul_i32 s20, s0, 0x440
	v_cvt_pk_bf16_f32 v82, v81, v82
	v_cvt_pk_bf16_f32 v81, v83, v84
	v_lshl_add_u64 v[84:85], v[6:7], 0, s[20:21]
	global_load_dword v83, v[84:85], off
	v_and_b32_e32 v84, 0xffff0000, v77
	s_mul_i32 s20, s0, 0x444
	v_max_f32_e64 v88, |v84|, |v84|
	v_lshl_add_u64 v[84:85], v[6:7], 0, s[20:21]
	global_load_dword v102, v[84:85], off
	v_lshlrev_b32_e32 v84, 16, v77
	v_max_f32_e64 v84, |v84|, |v84|
	s_mul_i32 s20, s0, 0x448
	v_max_f32_e32 v88, v84, v88
	v_lshl_add_u64 v[84:85], v[6:7], 0, s[20:21]
	v_max_f32_e32 v87, v91, v90
	global_load_dword v103, v[84:85], off
	v_and_b32_e32 v84, 0xffff0000, v80
	s_mul_i32 s20, s0, 0x44c
	v_max3_f32 v86, v86, v87, v88
	v_max_f32_e64 v87, |v84|, |v84|
	v_lshl_add_u64 v[84:85], v[6:7], 0, s[20:21]
	global_load_dword v88, v[84:85], off
	v_lshlrev_b32_e32 v84, 16, v80
	v_max_f32_e64 v84, |v84|, |v84|
	v_max_f32_e32 v84, v84, v87
	v_and_b32_e32 v85, 0xffff0000, v79
	v_lshlrev_b32_e32 v87, 16, v79
	v_max_f32_e64 v85, |v85|, |v85|
	v_max_f32_e64 v87, |v87|, |v87|
	v_max_f32_e32 v85, v87, v85
	v_max3_f32 v86, v86, v84, v85
	v_and_b32_e32 v84, 0xffff0000, v82
	v_lshlrev_b32_e32 v85, 16, v82
	v_max_f32_e64 v84, |v84|, |v84|
	v_max_f32_e64 v85, |v85|, |v85|
	v_max_f32_e32 v87, v85, v84
	v_and_b32_e32 v84, 0xffff0000, v81
	s_mul_i32 s20, s0, 0x450
	v_max_f32_e64 v90, |v84|, |v84|
	v_lshl_add_u64 v[84:85], v[6:7], 0, s[20:21]
	global_load_dword v104, v[84:85], off
	v_lshlrev_b32_e32 v84, 16, v81
	v_max_f32_e64 v84, |v84|, |v84|
	s_mul_i32 s20, s0, 0x454
	v_max_f32_e32 v90, v84, v90
	v_lshl_add_u64 v[84:85], v[6:7], 0, s[20:21]
	global_load_dword v105, v[84:85], off
	s_mul_i32 s20, s0, 0x458
	v_lshl_add_u64 v[84:85], v[6:7], 0, s[20:21]
	s_mul_i32 s20, s0, 0x45c
	v_max3_f32 v106, v86, v87, v90
	v_lshl_add_u64 v[86:87], v[6:7], 0, s[20:21]
	global_load_dword v107, v[84:85], off
	global_load_dword v108, v[86:87], off
	s_mul_i32 s20, s0, 0x460
	v_lshl_add_u64 v[84:85], v[6:7], 0, s[20:21]
	s_mul_i32 s20, s0, 0x464
	v_lshl_add_u64 v[86:87], v[6:7], 0, s[20:21]
	s_mul_i32 s20, s0, 0x468
	v_lshl_add_u64 v[90:91], v[6:7], 0, s[20:21]
	s_mul_i32 s20, s0, 0x46c
	v_lshl_add_u64 v[92:93], v[6:7], 0, s[20:21]
	s_mul_i32 s20, s0, 0x470
	v_lshl_add_u64 v[94:95], v[6:7], 0, s[20:21]
	s_mul_i32 s20, s0, 0x474
	v_lshl_add_u64 v[96:97], v[6:7], 0, s[20:21]
	s_mul_i32 s20, s0, 0x478
	v_lshl_add_u64 v[98:99], v[6:7], 0, s[20:21]
	s_mul_i32 s20, s0, 0x47c
	v_lshl_add_u64 v[100:101], v[6:7], 0, s[20:21]
	global_load_dword v109, v[84:85], off
	s_nop 0
	global_load_dword v87, v[86:87], off
	s_nop 0
	global_load_dword v90, v[90:91], off
	s_nop 0
	global_load_dword v91, v[92:93], off
	s_nop 0
	global_load_dword v92, v[94:95], off
	global_load_dword v93, v[96:97], off
	s_nop 0
	global_load_dword v94, v[98:99], off
	global_load_dword v95, v[100:101], off
	v_readlane_b32 s1, v89, 16
	v_readlane_b32 s20, v89, 48
	s_nop 0
	v_mov_b32_e32 v85, s1
	v_mov_b32_e32 v84, s20
	v_cndmask_b32_e32 v84, v84, v85, vcc
	v_readlane_b32 s1, v89, 17
	v_readlane_b32 s20, v89, 49
	s_waitcnt vmcnt(0) lgkmcnt(0)
	v_mul_f32_e32 v83, v83, v84
	v_mov_b32_e32 v84, s20
	v_mov_b32_e32 v85, s1
	v_readlane_b32 s1, v89, 18
	v_readlane_b32 s20, v89, 50
	v_cndmask_b32_e32 v84, v84, v85, vcc
	v_mov_b32_e32 v86, s1
	v_mov_b32_e32 v85, s20
	v_readlane_b32 s1, v89, 19
	v_readlane_b32 s20, v89, 51
	v_cndmask_b32_e32 v85, v85, v86, vcc
	v_mov_b32_e32 v96, s1
	v_mov_b32_e32 v86, s20
	v_mul_f32_e32 v84, v102, v84
	v_cndmask_b32_e32 v86, v86, v96, vcc
	v_cvt_pk_bf16_f32 v84, v83, v84
	v_mul_f32_e32 v85, v103, v85
	v_and_b32_e32 v83, 0xffff0000, v84
	v_mul_f32_e32 v86, v88, v86
	v_lshlrev_b32_e32 v88, 16, v84
	v_max_f32_e64 v83, |v83|, |v83|
	v_max_f32_e64 v88, |v88|, |v88|
	v_max_f32_e32 v88, v88, v83
	v_cvt_pk_bf16_f32 v83, v85, v86
	v_readlane_b32 s1, v89, 20
	v_and_b32_e32 v85, 0xffff0000, v83
	v_lshlrev_b32_e32 v86, 16, v83
	v_max_f32_e64 v85, |v85|, |v85|
	v_max_f32_e64 v86, |v86|, |v86|
	v_max_f32_e32 v85, v86, v85
	v_readlane_b32 s20, v89, 52
	v_max3_f32 v96, v106, v88, v85
	v_mov_b32_e32 v86, s1
	v_mov_b32_e32 v85, s20
	v_readlane_b32 s1, v89, 21
	v_readlane_b32 s20, v89, 53
	v_cndmask_b32_e32 v85, v85, v86, vcc
	v_mov_b32_e32 v88, s1
	v_mov_b32_e32 v86, s20
	v_readlane_b32 s1, v89, 22
	v_readlane_b32 s20, v89, 54
	v_cndmask_b32_e32 v86, v86, v88, vcc
	v_mov_b32_e32 v97, s1
	v_mov_b32_e32 v88, s20
	v_readlane_b32 s1, v89, 23
	v_readlane_b32 s20, v89, 55
	v_mul_f32_e32 v85, v104, v85
	v_mul_f32_e32 v86, v105, v86
	v_cndmask_b32_e32 v88, v88, v97, vcc
	v_mov_b32_e32 v97, s20
	v_mov_b32_e32 v98, s1
	v_cndmask_b32_e32 v97, v97, v98, vcc
	v_cvt_pk_bf16_f32 v86, v85, v86
	v_mul_f32_e32 v88, v107, v88
	v_and_b32_e32 v85, 0xffff0000, v86
	v_mul_f32_e32 v97, v108, v97
	v_max_f32_e64 v98, |v85|, |v85|
	v_lshlrev_b32_e32 v85, 16, v86
	v_readlane_b32 s1, v89, 24
	v_readlane_b32 s20, v89, 56
	v_max_f32_e64 v99, |v85|, |v85|
	v_cvt_pk_bf16_f32 v85, v88, v97
	v_mov_b32_e32 v97, s1
	v_mov_b32_e32 v88, s20
	v_readlane_b32 s1, v89, 25
	v_readlane_b32 s20, v89, 57
	v_cndmask_b32_e32 v88, v88, v97, vcc
	v_mov_b32_e32 v100, s1
	v_mov_b32_e32 v97, s20
	v_cndmask_b32_e32 v97, v97, v100, vcc
	v_readlane_b32 s1, v89, 26
	v_readlane_b32 s20, v89, 58
	v_mul_f32_e32 v87, v87, v97
	v_mov_b32_e32 v100, s1
	v_mov_b32_e32 v97, s20
	v_cndmask_b32_e32 v97, v97, v100, vcc
	v_readlane_b32 s1, v89, 27
	v_readlane_b32 s20, v89, 59
	v_mul_f32_e32 v90, v90, v97
	v_mov_b32_e32 v100, s1
	v_mov_b32_e32 v97, s20
	v_cndmask_b32_e32 v97, v97, v100, vcc
	v_mul_f32_e32 v88, v109, v88
	v_mul_f32_e32 v91, v91, v97
	v_readlane_b32 s1, v89, 28
	v_readlane_b32 s20, v89, 60
	v_cvt_pk_bf16_f32 v88, v88, v87
	v_cvt_pk_bf16_f32 v87, v90, v91
	s_nop 0
	v_mov_b32_e32 v91, s1
	v_mov_b32_e32 v90, s20
	v_cndmask_b32_e32 v90, v90, v91, vcc
	v_readlane_b32 s1, v89, 29
	v_readlane_b32 s20, v89, 61
	v_mul_f32_e32 v90, v92, v90
	v_mov_b32_e32 v92, s1
	v_mov_b32_e32 v91, s20
	v_cndmask_b32_e32 v91, v91, v92, vcc
	v_readlane_b32 s1, v89, 30
	v_readlane_b32 s20, v89, 62
	v_mul_f32_e32 v91, v93, v91
	v_mov_b32_e32 v93, s1
	v_mov_b32_e32 v92, s20
	v_readlane_b32 s1, v89, 31
	v_readlane_b32 s20, v89, 63
	v_cndmask_b32_e32 v92, v92, v93, vcc
	v_mov_b32_e32 v93, s1
	v_mov_b32_e32 v89, s20
	v_cndmask_b32_e32 v89, v89, v93, vcc
	v_mul_f32_e32 v92, v94, v92
	v_mul_f32_e32 v89, v95, v89
	s_mul_i32 s20, s0, 0x500
	v_cvt_pk_bf16_f32 v90, v90, v91
	v_cvt_pk_bf16_f32 v89, v92, v89
	v_lshl_add_u64 v[92:93], v[6:7], 0, s[20:21]
	global_load_dword v91, v[92:93], off
	v_and_b32_e32 v92, 0xffff0000, v85
	s_mul_i32 s20, s0, 0x504
	v_max_f32_e64 v95, |v92|, |v92|
	v_lshl_add_u64 v[92:93], v[6:7], 0, s[20:21]
	global_load_dword v108, v[92:93], off
	v_lshlrev_b32_e32 v92, 16, v85
	v_max_f32_e64 v92, |v92|, |v92|
	s_mul_i32 s20, s0, 0x508
	v_max_f32_e32 v95, v92, v95
	v_lshl_add_u64 v[92:93], v[6:7], 0, s[20:21]
	v_max_f32_e32 v94, v99, v98
	global_load_dword v109, v[92:93], off
	v_and_b32_e32 v92, 0xffff0000, v88
	s_mul_i32 s20, s0, 0x50c
	v_max3_f32 v94, v96, v94, v95
	v_max_f32_e64 v95, |v92|, |v92|
	v_lshl_add_u64 v[92:93], v[6:7], 0, s[20:21]
	global_load_dword v110, v[92:93], off
	v_lshlrev_b32_e32 v92, 16, v88
	v_max_f32_e64 v92, |v92|, |v92|
	v_max_f32_e32 v92, v92, v95
	v_and_b32_e32 v93, 0xffff0000, v87
	v_lshlrev_b32_e32 v95, 16, v87
	v_max_f32_e64 v93, |v93|, |v93|
	v_max_f32_e64 v95, |v95|, |v95|
	v_max_f32_e32 v93, v95, v93
	v_max3_f32 v94, v94, v92, v93
	v_and_b32_e32 v92, 0xffff0000, v90
	v_lshlrev_b32_e32 v93, 16, v90
	v_max_f32_e64 v92, |v92|, |v92|
	v_max_f32_e64 v93, |v93|, |v93|
	v_max_f32_e32 v95, v93, v92
	v_and_b32_e32 v92, 0xffff0000, v89
	s_mul_i32 s20, s0, 0x510
	v_max_f32_e64 v96, |v92|, |v92|
	v_lshl_add_u64 v[92:93], v[6:7], 0, s[20:21]
	global_load_dword v111, v[92:93], off
	v_lshlrev_b32_e32 v92, 16, v89
	v_max_f32_e64 v92, |v92|, |v92|
	s_mul_i32 s20, s0, 0x514
	v_max_f32_e32 v96, v92, v96
	v_lshl_add_u64 v[92:93], v[6:7], 0, s[20:21]
	global_load_dword v112, v[92:93], off
	s_mul_i32 s20, s0, 0x518
	v_lshl_add_u64 v[92:93], v[6:7], 0, s[20:21]
	s_mul_i32 s20, s0, 0x51c
	v_max3_f32 v113, v94, v95, v96
	v_lshl_add_u64 v[94:95], v[6:7], 0, s[20:21]
	global_load_dword v114, v[92:93], off
	global_load_dword v115, v[94:95], off
	s_mul_i32 s20, s0, 0x520
	v_lshl_add_u64 v[92:93], v[6:7], 0, s[20:21]
	s_mul_i32 s20, s0, 0x524
	v_lshl_add_u64 v[94:95], v[6:7], 0, s[20:21]
	s_mul_i32 s20, s0, 0x528
	v_lshl_add_u64 v[96:97], v[6:7], 0, s[20:21]
	s_mul_i32 s20, s0, 0x52c
	v_lshl_add_u64 v[98:99], v[6:7], 0, s[20:21]
	s_mul_i32 s20, s0, 0x530
	v_lshl_add_u64 v[100:101], v[6:7], 0, s[20:21]
	s_mul_i32 s20, s0, 0x534
	v_lshl_add_u64 v[102:103], v[6:7], 0, s[20:21]
	s_mul_i32 s20, s0, 0x538
	v_lshl_add_u64 v[104:105], v[6:7], 0, s[20:21]
	s_mul_i32 s20, s0, 0x53c
	v_lshl_add_u64 v[106:107], v[6:7], 0, s[20:21]
	global_load_dword v116, v[92:93], off
	s_nop 0
	global_load_dword v95, v[94:95], off
	s_nop 0
	global_load_dword v96, v[96:97], off
	s_nop 0
	global_load_dword v97, v[98:99], off
	s_nop 0
	global_load_dword v98, v[100:101], off
	global_load_dword v99, v[102:103], off
	s_nop 0
	global_load_dword v100, v[104:105], off
	global_load_dword v101, v[106:107], off
	v_readlane_b32 s1, v74, 0
	v_readlane_b32 s20, v74, 32
	s_nop 0
	v_mov_b32_e32 v93, s1
	v_mov_b32_e32 v92, s20
	v_cndmask_b32_e32 v92, v92, v93, vcc
	v_readlane_b32 s1, v74, 1
	v_readlane_b32 s20, v74, 33
	s_waitcnt vmcnt(0) lgkmcnt(0)
	v_mul_f32_e32 v91, v91, v92
	v_mov_b32_e32 v92, s20
	v_mov_b32_e32 v93, s1
	v_readlane_b32 s1, v74, 2
	v_readlane_b32 s20, v74, 34
	v_cndmask_b32_e32 v92, v92, v93, vcc
	v_mov_b32_e32 v94, s1
	v_mov_b32_e32 v93, s20
	v_readlane_b32 s1, v74, 3
	v_readlane_b32 s20, v74, 35
	v_mul_f32_e32 v92, v108, v92
	v_cndmask_b32_e32 v93, v93, v94, vcc
	v_mov_b32_e32 v94, s20
	v_mov_b32_e32 v102, s1
	v_cndmask_b32_e32 v94, v94, v102, vcc
	v_cvt_pk_bf16_f32 v92, v91, v92
	v_mul_f32_e32 v93, v109, v93
	v_and_b32_e32 v91, 0xffff0000, v92
	v_lshlrev_b32_e32 v102, 16, v92
	v_mul_f32_e32 v94, v110, v94
	v_max_f32_e64 v91, |v91|, |v91|
	v_max_f32_e64 v102, |v102|, |v102|
	v_max_f32_e32 v102, v102, v91
	v_cvt_pk_bf16_f32 v91, v93, v94
	v_readlane_b32 s1, v74, 4
	v_and_b32_e32 v93, 0xffff0000, v91
	v_lshlrev_b32_e32 v94, 16, v91
	v_max_f32_e64 v93, |v93|, |v93|
	v_max_f32_e64 v94, |v94|, |v94|
	v_max_f32_e32 v93, v94, v93
	v_readlane_b32 s20, v74, 36
	v_max3_f32 v102, v113, v102, v93
	v_mov_b32_e32 v94, s1
	v_mov_b32_e32 v93, s20
	v_readlane_b32 s1, v74, 5
	v_readlane_b32 s20, v74, 37
	v_cndmask_b32_e32 v93, v93, v94, vcc
	v_mov_b32_e32 v103, s1
	v_mov_b32_e32 v94, s20
	v_readlane_b32 s1, v74, 6
	v_readlane_b32 s20, v74, 38
	v_cndmask_b32_e32 v94, v94, v103, vcc
	v_mov_b32_e32 v104, s1
	v_mov_b32_e32 v103, s20
	v_readlane_b32 s1, v74, 7
	v_readlane_b32 s20, v74, 39
	v_mul_f32_e32 v93, v111, v93
	v_mul_f32_e32 v94, v112, v94
	v_cndmask_b32_e32 v103, v103, v104, vcc
	v_mov_b32_e32 v104, s20
	v_mov_b32_e32 v105, s1
	v_cndmask_b32_e32 v104, v104, v105, vcc
	v_cvt_pk_bf16_f32 v94, v93, v94
	v_mul_f32_e32 v103, v114, v103
	v_and_b32_e32 v93, 0xffff0000, v94
	v_mul_f32_e32 v104, v115, v104
	v_max_f32_e64 v105, |v93|, |v93|
	v_lshlrev_b32_e32 v93, 16, v94
	v_readlane_b32 s1, v74, 8
	v_readlane_b32 s20, v74, 40
	v_max_f32_e64 v106, |v93|, |v93|
	v_cvt_pk_bf16_f32 v93, v103, v104
	v_mov_b32_e32 v104, s1
	v_mov_b32_e32 v103, s20
	v_readlane_b32 s1, v74, 9
	v_readlane_b32 s20, v74, 41
	v_cndmask_b32_e32 v103, v103, v104, vcc
	v_mov_b32_e32 v107, s1
	v_mov_b32_e32 v104, s20
	v_cndmask_b32_e32 v104, v104, v107, vcc
	v_readlane_b32 s1, v74, 10
	v_readlane_b32 s20, v74, 42
	v_mul_f32_e32 v95, v95, v104
	v_mov_b32_e32 v107, s1
	v_mov_b32_e32 v104, s20
	v_cndmask_b32_e32 v104, v104, v107, vcc
	v_readlane_b32 s1, v74, 11
	v_readlane_b32 s20, v74, 43
	v_mul_f32_e32 v104, v96, v104
	v_mov_b32_e32 v107, s1
	v_mov_b32_e32 v96, s20
	v_cndmask_b32_e32 v96, v96, v107, vcc
	v_mul_f32_e32 v103, v116, v103
	v_mul_f32_e32 v97, v97, v96
	v_readlane_b32 s1, v74, 12
	v_readlane_b32 s20, v74, 44
	v_cvt_pk_bf16_f32 v96, v103, v95
	v_cvt_pk_bf16_f32 v95, v104, v97
	s_nop 0
	v_mov_b32_e32 v103, s1
	v_mov_b32_e32 v97, s20
	v_cndmask_b32_e32 v97, v97, v103, vcc
	v_readlane_b32 s1, v74, 13
	v_readlane_b32 s20, v74, 45
	v_mul_f32_e32 v97, v98, v97
	v_mov_b32_e32 v103, s1
	v_mov_b32_e32 v98, s20
	v_cndmask_b32_e32 v98, v98, v103, vcc
	v_readlane_b32 s1, v74, 14
	v_readlane_b32 s20, v74, 46
	v_mul_f32_e32 v98, v99, v98
	v_mov_b32_e32 v103, s1
	v_mov_b32_e32 v99, s20
	v_cndmask_b32_e32 v99, v99, v103, vcc
	v_readlane_b32 s1, v74, 15
	v_readlane_b32 s20, v74, 47
	v_mul_f32_e32 v99, v100, v99
	v_mov_b32_e32 v103, s1
	v_mov_b32_e32 v100, s20
	v_cndmask_b32_e32 v100, v100, v103, vcc
	v_mul_f32_e32 v100, v101, v100
	s_mul_i32 s20, s0, 0x540
	v_cvt_pk_bf16_f32 v98, v97, v98
	v_cvt_pk_bf16_f32 v97, v99, v100
	v_lshl_add_u64 v[100:101], v[6:7], 0, s[20:21]
	global_load_dword v99, v[100:101], off
	v_and_b32_e32 v100, 0xffff0000, v93
	s_mul_i32 s20, s0, 0x544
	v_max_f32_e64 v104, |v100|, |v100|
	v_lshl_add_u64 v[100:101], v[6:7], 0, s[20:21]
	global_load_dword v116, v[100:101], off
	v_lshlrev_b32_e32 v100, 16, v93
	v_max_f32_e64 v100, |v100|, |v100|
	s_mul_i32 s20, s0, 0x548
	v_max_f32_e32 v104, v100, v104
	v_lshl_add_u64 v[100:101], v[6:7], 0, s[20:21]
	v_max_f32_e32 v103, v106, v105
	global_load_dword v117, v[100:101], off
	v_and_b32_e32 v100, 0xffff0000, v96
	s_mul_i32 s20, s0, 0x54c
	v_max3_f32 v102, v102, v103, v104
	v_max_f32_e64 v103, |v100|, |v100|
	v_lshl_add_u64 v[100:101], v[6:7], 0, s[20:21]
	global_load_dword v118, v[100:101], off
	v_lshlrev_b32_e32 v100, 16, v96
	v_max_f32_e64 v100, |v100|, |v100|
	v_max_f32_e32 v100, v100, v103
	v_and_b32_e32 v101, 0xffff0000, v95
	v_lshlrev_b32_e32 v103, 16, v95
	v_max_f32_e64 v101, |v101|, |v101|
	v_max_f32_e64 v103, |v103|, |v103|
	v_max_f32_e32 v101, v103, v101
	v_max3_f32 v102, v102, v100, v101
	v_and_b32_e32 v100, 0xffff0000, v98
	v_lshlrev_b32_e32 v101, 16, v98
	v_max_f32_e64 v100, |v100|, |v100|
	v_max_f32_e64 v101, |v101|, |v101|
	v_max_f32_e32 v103, v101, v100
	v_and_b32_e32 v100, 0xffff0000, v97
	s_mul_i32 s20, s0, 0x550
	v_max_f32_e64 v104, |v100|, |v100|
	v_lshl_add_u64 v[100:101], v[6:7], 0, s[20:21]
	global_load_dword v119, v[100:101], off
	v_lshlrev_b32_e32 v100, 16, v97
	v_max_f32_e64 v100, |v100|, |v100|
	s_mul_i32 s20, s0, 0x554
	v_max_f32_e32 v104, v100, v104
	v_lshl_add_u64 v[100:101], v[6:7], 0, s[20:21]
	global_load_dword v120, v[100:101], off
	s_mul_i32 s20, s0, 0x558
	v_lshl_add_u64 v[100:101], v[6:7], 0, s[20:21]
	s_mul_i32 s20, s0, 0x55c
	v_max3_f32 v121, v102, v103, v104
	v_lshl_add_u64 v[102:103], v[6:7], 0, s[20:21]
	global_load_dword v122, v[100:101], off
	global_load_dword v123, v[102:103], off
	s_mul_i32 s20, s0, 0x560
	v_lshl_add_u64 v[100:101], v[6:7], 0, s[20:21]
	s_mul_i32 s20, s0, 0x564
	v_lshl_add_u64 v[102:103], v[6:7], 0, s[20:21]
	s_mul_i32 s20, s0, 0x568
	v_lshl_add_u64 v[104:105], v[6:7], 0, s[20:21]
	s_mul_i32 s20, s0, 0x56c
	v_lshl_add_u64 v[106:107], v[6:7], 0, s[20:21]
	s_mul_i32 s20, s0, 0x570
	v_lshl_add_u64 v[108:109], v[6:7], 0, s[20:21]
	s_mul_i32 s20, s0, 0x574
	v_lshl_add_u64 v[110:111], v[6:7], 0, s[20:21]
	s_mul_i32 s20, s0, 0x578
	v_lshl_add_u64 v[112:113], v[6:7], 0, s[20:21]
	s_mul_i32 s20, s0, 0x57c
	v_lshl_add_u64 v[114:115], v[6:7], 0, s[20:21]
	global_load_dword v124, v[100:101], off
	s_nop 0
	global_load_dword v103, v[102:103], off
	s_nop 0
	global_load_dword v104, v[104:105], off
	s_nop 0
	global_load_dword v105, v[106:107], off
	s_nop 0
	global_load_dword v106, v[108:109], off
	global_load_dword v107, v[110:111], off
	s_nop 0
	global_load_dword v108, v[112:113], off
	global_load_dword v109, v[114:115], off
	v_readlane_b32 s1, v74, 16
	v_readlane_b32 s20, v74, 48
	s_nop 0
	v_mov_b32_e32 v101, s1
	v_mov_b32_e32 v100, s20
	v_cndmask_b32_e32 v100, v100, v101, vcc
	v_readlane_b32 s1, v74, 17
	v_readlane_b32 s20, v74, 49
	s_waitcnt vmcnt(0) lgkmcnt(0)
	v_mul_f32_e32 v99, v99, v100
	v_mov_b32_e32 v100, s20
	v_mov_b32_e32 v101, s1
	v_readlane_b32 s1, v74, 18
	v_readlane_b32 s20, v74, 50
	v_cndmask_b32_e32 v100, v100, v101, vcc
	v_mov_b32_e32 v102, s1
	v_mov_b32_e32 v101, s20
	v_readlane_b32 s1, v74, 19
	v_readlane_b32 s20, v74, 51
	v_mul_f32_e32 v100, v116, v100
	v_cndmask_b32_e32 v101, v101, v102, vcc
	v_mov_b32_e32 v102, s20
	v_mov_b32_e32 v110, s1
	v_cndmask_b32_e32 v102, v102, v110, vcc
	v_cvt_pk_bf16_f32 v100, v99, v100
	v_mul_f32_e32 v101, v117, v101
	v_and_b32_e32 v99, 0xffff0000, v100
	v_lshlrev_b32_e32 v110, 16, v100
	v_mul_f32_e32 v102, v118, v102
	v_max_f32_e64 v99, |v99|, |v99|
	v_max_f32_e64 v110, |v110|, |v110|
	v_max_f32_e32 v110, v110, v99
	v_cvt_pk_bf16_f32 v99, v101, v102
	v_readlane_b32 s1, v74, 20
	v_and_b32_e32 v101, 0xffff0000, v99
	v_lshlrev_b32_e32 v102, 16, v99
	v_max_f32_e64 v101, |v101|, |v101|
	v_max_f32_e64 v102, |v102|, |v102|
	v_max_f32_e32 v101, v102, v101
	v_readlane_b32 s20, v74, 52
	v_max3_f32 v110, v121, v110, v101
	v_mov_b32_e32 v102, s1
	v_mov_b32_e32 v101, s20
	v_readlane_b32 s1, v74, 21
	v_readlane_b32 s20, v74, 53
	v_cndmask_b32_e32 v101, v101, v102, vcc
	v_mov_b32_e32 v111, s1
	v_mov_b32_e32 v102, s20
	v_readlane_b32 s1, v74, 22
	v_readlane_b32 s20, v74, 54
	v_cndmask_b32_e32 v102, v102, v111, vcc
	v_mov_b32_e32 v112, s1
	v_mov_b32_e32 v111, s20
	v_readlane_b32 s1, v74, 23
	v_readlane_b32 s20, v74, 55
	v_mul_f32_e32 v101, v119, v101
	v_mul_f32_e32 v102, v120, v102
	v_cndmask_b32_e32 v111, v111, v112, vcc
	v_mov_b32_e32 v112, s20
	v_mov_b32_e32 v113, s1
	v_cndmask_b32_e32 v112, v112, v113, vcc
	v_cvt_pk_bf16_f32 v102, v101, v102
	v_mul_f32_e32 v111, v122, v111
	v_and_b32_e32 v101, 0xffff0000, v102
	v_mul_f32_e32 v112, v123, v112
	v_max_f32_e64 v113, |v101|, |v101|
	v_lshlrev_b32_e32 v101, 16, v102
	v_readlane_b32 s1, v74, 24
	v_readlane_b32 s20, v74, 56
	v_max_f32_e64 v114, |v101|, |v101|
	v_cvt_pk_bf16_f32 v101, v111, v112
	v_mov_b32_e32 v112, s1
	v_mov_b32_e32 v111, s20
	v_readlane_b32 s1, v74, 25
	v_readlane_b32 s20, v74, 57
	v_cndmask_b32_e32 v111, v111, v112, vcc
	v_mov_b32_e32 v115, s1
	v_mov_b32_e32 v112, s20
	v_cndmask_b32_e32 v112, v112, v115, vcc
	v_readlane_b32 s1, v74, 26
	v_readlane_b32 s20, v74, 58
	v_mul_f32_e32 v103, v103, v112
	v_mov_b32_e32 v115, s1
	v_mov_b32_e32 v112, s20
	v_cndmask_b32_e32 v112, v112, v115, vcc
	v_readlane_b32 s1, v74, 27
	v_readlane_b32 s20, v74, 59
	v_mul_f32_e32 v112, v104, v112
	v_mov_b32_e32 v115, s1
	v_mov_b32_e32 v104, s20
	v_cndmask_b32_e32 v104, v104, v115, vcc
	v_mul_f32_e32 v111, v124, v111
	v_mul_f32_e32 v105, v105, v104
	v_readlane_b32 s1, v74, 28
	v_readlane_b32 s20, v74, 60
	v_cvt_pk_bf16_f32 v104, v111, v103
	v_cvt_pk_bf16_f32 v103, v112, v105
	s_nop 0
	v_mov_b32_e32 v111, s1
	v_mov_b32_e32 v105, s20
	v_cndmask_b32_e32 v105, v105, v111, vcc
	v_readlane_b32 s1, v74, 29
	v_readlane_b32 s20, v74, 61
	v_mul_f32_e32 v105, v106, v105
	v_mov_b32_e32 v111, s1
	v_mov_b32_e32 v106, s20
	v_cndmask_b32_e32 v106, v106, v111, vcc
	v_readlane_b32 s1, v74, 30
	v_readlane_b32 s20, v74, 62
	v_mul_f32_e32 v106, v107, v106
	v_mov_b32_e32 v111, s1
	v_mov_b32_e32 v107, s20
	v_cndmask_b32_e32 v107, v107, v111, vcc
	v_readlane_b32 s1, v74, 31
	v_readlane_b32 s20, v74, 63
	v_mul_f32_e32 v107, v108, v107
	v_mov_b32_e32 v108, s1
	v_mov_b32_e32 v74, s20
	v_cndmask_b32_e32 v74, v74, v108, vcc
	v_mul_f32_e32 v74, v109, v74
	s_mul_i32 s20, s0, 0x600
	v_cvt_pk_bf16_f32 v105, v105, v106
	v_cvt_pk_bf16_f32 v74, v107, v74
	v_lshl_add_u64 v[106:107], v[6:7], 0, s[20:21]
	global_load_dword v122, v[106:107], off
	v_and_b32_e32 v106, 0xffff0000, v101
	s_mul_i32 s20, s0, 0x604
	v_max_f32_e64 v109, |v106|, |v106|
	v_lshl_add_u64 v[106:107], v[6:7], 0, s[20:21]
	global_load_dword v123, v[106:107], off
	v_lshlrev_b32_e32 v106, 16, v101
	v_max_f32_e64 v106, |v106|, |v106|
	s_mul_i32 s20, s0, 0x608
	v_max_f32_e32 v109, v106, v109
	v_lshl_add_u64 v[106:107], v[6:7], 0, s[20:21]
	v_max_f32_e32 v108, v114, v113
	global_load_dword v124, v[106:107], off
	v_and_b32_e32 v106, 0xffff0000, v104
	s_mul_i32 s20, s0, 0x60c
	v_max3_f32 v108, v110, v108, v109
	v_max_f32_e64 v109, |v106|, |v106|
	v_lshl_add_u64 v[106:107], v[6:7], 0, s[20:21]
	global_load_dword v125, v[106:107], off
	v_lshlrev_b32_e32 v106, 16, v104
	v_max_f32_e64 v106, |v106|, |v106|
	v_max_f32_e32 v106, v106, v109
	v_and_b32_e32 v107, 0xffff0000, v103
	v_lshlrev_b32_e32 v109, 16, v103
	v_max_f32_e64 v107, |v107|, |v107|
	v_max_f32_e64 v109, |v109|, |v109|
	v_max_f32_e32 v107, v109, v107
	v_max3_f32 v108, v108, v106, v107
	v_and_b32_e32 v106, 0xffff0000, v105
	v_lshlrev_b32_e32 v107, 16, v105
	v_max_f32_e64 v106, |v106|, |v106|
	v_max_f32_e64 v107, |v107|, |v107|
	v_max_f32_e32 v109, v107, v106
	v_and_b32_e32 v106, 0xffff0000, v74
	s_mul_i32 s20, s0, 0x610
	v_max_f32_e64 v110, |v106|, |v106|
	v_lshl_add_u64 v[106:107], v[6:7], 0, s[20:21]
	global_load_dword v126, v[106:107], off
	v_lshlrev_b32_e32 v106, 16, v74
	v_max_f32_e64 v106, |v106|, |v106|
	s_mul_i32 s20, s0, 0x614
	v_max_f32_e32 v110, v106, v110
	v_lshl_add_u64 v[106:107], v[6:7], 0, s[20:21]
	global_load_dword v127, v[106:107], off
	s_mul_i32 s20, s0, 0x618
	v_lshl_add_u64 v[106:107], v[6:7], 0, s[20:21]
	s_mul_i32 s20, s0, 0x61c
	v_max3_f32 v128, v108, v109, v110
	v_lshl_add_u64 v[108:109], v[6:7], 0, s[20:21]
	global_load_dword v129, v[106:107], off
	global_load_dword v130, v[108:109], off
	s_mul_i32 s20, s0, 0x620
	v_lshl_add_u64 v[106:107], v[6:7], 0, s[20:21]
	s_mul_i32 s20, s0, 0x624
	v_lshl_add_u64 v[108:109], v[6:7], 0, s[20:21]
	s_mul_i32 s20, s0, 0x628
	v_lshl_add_u64 v[110:111], v[6:7], 0, s[20:21]
	s_mul_i32 s20, s0, 0x62c
	v_lshl_add_u64 v[112:113], v[6:7], 0, s[20:21]
	s_mul_i32 s20, s0, 0x630
	v_lshl_add_u64 v[114:115], v[6:7], 0, s[20:21]
	s_mul_i32 s20, s0, 0x634
	v_lshl_add_u64 v[116:117], v[6:7], 0, s[20:21]
	s_mul_i32 s20, s0, 0x638
	v_lshl_add_u64 v[118:119], v[6:7], 0, s[20:21]
	s_mul_i32 s20, s0, 0x63c
	v_lshl_add_u64 v[120:121], v[6:7], 0, s[20:21]
	global_load_dword v131, v[106:107], off
	global_load_dword v132, v[108:109], off
	s_nop 0
	global_load_dword v110, v[110:111], off
	s_nop 0
	global_load_dword v111, v[112:113], off
	s_nop 0
	global_load_dword v112, v[114:115], off
	global_load_dword v113, v[116:117], off
	s_nop 0
	global_load_dword v114, v[118:119], off
	global_load_dword v115, v[120:121], off
	v_readlane_b32 s1, v5, 0
	v_readlane_b32 s20, v5, 32
	s_nop 0
	v_mov_b32_e32 v107, s1
	v_mov_b32_e32 v106, s20
	v_readlane_b32 s1, v5, 1
	v_readlane_b32 s20, v5, 33
	v_cndmask_b32_e32 v106, v106, v107, vcc
	v_mov_b32_e32 v108, s1
	v_mov_b32_e32 v107, s20
	v_readlane_b32 s1, v5, 2
	v_readlane_b32 s20, v5, 34
	v_cndmask_b32_e32 v107, v107, v108, vcc
	v_mov_b32_e32 v109, s1
	v_mov_b32_e32 v108, s20
	v_readlane_b32 s1, v5, 3
	v_readlane_b32 s20, v5, 35
	s_waitcnt vmcnt(0) lgkmcnt(0)
	v_mul_f32_e32 v106, v122, v106
	v_mul_f32_e32 v107, v123, v107
	v_cndmask_b32_e32 v108, v108, v109, vcc
	v_mov_b32_e32 v109, s20
	v_mov_b32_e32 v116, s1
	v_cndmask_b32_e32 v109, v109, v116, vcc
	v_cvt_pk_bf16_f32 v107, v106, v107
	v_readlane_b32 s1, v5, 4
	v_and_b32_e32 v106, 0xffff0000, v107
	v_lshlrev_b32_e32 v116, 16, v107
	v_mul_f32_e32 v108, v124, v108
	v_max_f32_e64 v106, |v106|, |v106|
	v_max_f32_e64 v116, |v116|, |v116|
	v_max_f32_e32 v116, v116, v106
	v_mul_f32_e32 v109, v125, v109
	v_cvt_pk_bf16_f32 v106, v108, v109
	v_readlane_b32 s20, v5, 36
	v_and_b32_e32 v108, 0xffff0000, v106
	v_lshlrev_b32_e32 v109, 16, v106
	v_max_f32_e64 v108, |v108|, |v108|
	v_max_f32_e64 v109, |v109|, |v109|
	v_max_f32_e32 v108, v109, v108
	v_max3_f32 v116, v128, v116, v108
	v_mov_b32_e32 v108, s20
	v_mov_b32_e32 v109, s1
	v_readlane_b32 s1, v5, 5
	v_readlane_b32 s20, v5, 37
	v_cndmask_b32_e32 v108, v108, v109, vcc
	v_mov_b32_e32 v117, s1
	v_mov_b32_e32 v109, s20
	v_readlane_b32 s1, v5, 6
	v_readlane_b32 s20, v5, 38
	v_cndmask_b32_e32 v109, v109, v117, vcc
	v_mov_b32_e32 v118, s1
	v_mov_b32_e32 v117, s20
	v_readlane_b32 s1, v5, 7
	v_readlane_b32 s20, v5, 39
	v_mul_f32_e32 v108, v126, v108
	v_cndmask_b32_e32 v117, v117, v118, vcc
	v_mul_f32_e32 v109, v127, v109
	v_mov_b32_e32 v118, s20
	v_mov_b32_e32 v119, s1
	v_cndmask_b32_e32 v118, v118, v119, vcc
	v_cvt_pk_bf16_f32 v109, v108, v109
	v_mul_f32_e32 v117, v129, v117
	v_and_b32_e32 v108, 0xffff0000, v109
	v_mul_f32_e32 v118, v130, v118
	v_max_f32_e64 v119, |v108|, |v108|
	v_lshlrev_b32_e32 v108, 16, v109
	v_readlane_b32 s1, v5, 8
	v_readlane_b32 s20, v5, 40
	v_max_f32_e64 v120, |v108|, |v108|
	v_cvt_pk_bf16_f32 v108, v117, v118
	v_mov_b32_e32 v118, s1
	v_mov_b32_e32 v117, s20
	v_readlane_b32 s1, v5, 9
	v_readlane_b32 s20, v5, 41
	v_cndmask_b32_e32 v117, v117, v118, vcc
	v_mov_b32_e32 v121, s1
	v_mov_b32_e32 v118, s20
	v_readlane_b32 s1, v5, 10
	v_readlane_b32 s20, v5, 42
	v_cndmask_b32_e32 v118, v118, v121, vcc
	v_mov_b32_e32 v122, s1
	v_mov_b32_e32 v121, s20
	v_cndmask_b32_e32 v121, v121, v122, vcc
	v_readlane_b32 s1, v5, 11
	v_readlane_b32 s20, v5, 43
	v_mul_f32_e32 v110, v110, v121
	v_mov_b32_e32 v122, s1
	v_mov_b32_e32 v121, s20
	v_mul_f32_e32 v117, v131, v117
	v_mul_f32_e32 v118, v132, v118
	v_cndmask_b32_e32 v121, v121, v122, vcc
	v_readlane_b32 s1, v5, 12
	v_readlane_b32 s20, v5, 44
	v_mul_f32_e32 v121, v111, v121
	v_cvt_pk_bf16_f32 v111, v117, v118
	v_mov_b32_e32 v118, s1
	v_mov_b32_e32 v117, s20
	v_cndmask_b32_e32 v117, v117, v118, vcc
	v_readlane_b32 s1, v5, 13
	v_readlane_b32 s20, v5, 45
	v_mul_f32_e32 v112, v112, v117
	v_mov_b32_e32 v118, s1
	v_mov_b32_e32 v117, s20
	v_cndmask_b32_e32 v117, v117, v118, vcc
	v_readlane_b32 s1, v5, 14
	v_readlane_b32 s20, v5, 46
	v_mul_f32_e32 v113, v113, v117
	v_mov_b32_e32 v118, s1
	v_mov_b32_e32 v117, s20
	v_cndmask_b32_e32 v117, v117, v118, vcc
	v_readlane_b32 s1, v5, 15
	v_readlane_b32 s20, v5, 47
	v_mul_f32_e32 v114, v114, v117
	v_mov_b32_e32 v118, s1
	v_mov_b32_e32 v117, s20
	v_cndmask_b32_e32 v117, v117, v118, vcc
	v_mul_f32_e32 v115, v115, v117
	s_mul_i32 s20, s0, 0x640
	v_cvt_pk_bf16_f32 v110, v110, v121
	v_cvt_pk_bf16_f32 v113, v112, v113
	v_cvt_pk_bf16_f32 v112, v114, v115
	v_lshl_add_u64 v[114:115], v[6:7], 0, s[20:21]
	global_load_dword v130, v[114:115], off
	v_and_b32_e32 v114, 0xffff0000, v108
	s_mul_i32 s20, s0, 0x644
	v_max_f32_e64 v118, |v114|, |v114|
	v_lshl_add_u64 v[114:115], v[6:7], 0, s[20:21]
	global_load_dword v131, v[114:115], off
	v_lshlrev_b32_e32 v114, 16, v108
	v_max_f32_e64 v114, |v114|, |v114|
	s_mul_i32 s20, s0, 0x648
	v_max_f32_e32 v118, v114, v118
	v_lshl_add_u64 v[114:115], v[6:7], 0, s[20:21]
	v_max_f32_e32 v117, v120, v119
	global_load_dword v132, v[114:115], off
	v_and_b32_e32 v114, 0xffff0000, v111
	s_mul_i32 s20, s0, 0x64c
	v_max3_f32 v116, v116, v117, v118
	v_max_f32_e64 v117, |v114|, |v114|
	v_lshl_add_u64 v[114:115], v[6:7], 0, s[20:21]
	global_load_dword v133, v[114:115], off
	v_lshlrev_b32_e32 v114, 16, v111
	v_max_f32_e64 v114, |v114|, |v114|
	v_max_f32_e32 v114, v114, v117
	v_and_b32_e32 v115, 0xffff0000, v110
	v_lshlrev_b32_e32 v117, 16, v110
	v_max_f32_e64 v115, |v115|, |v115|
	v_max_f32_e64 v117, |v117|, |v117|
	v_max_f32_e32 v115, v117, v115
	v_max3_f32 v116, v116, v114, v115
	v_and_b32_e32 v114, 0xffff0000, v113
	v_lshlrev_b32_e32 v115, 16, v113
	v_max_f32_e64 v114, |v114|, |v114|
	v_max_f32_e64 v115, |v115|, |v115|
	v_max_f32_e32 v117, v115, v114
	v_and_b32_e32 v114, 0xffff0000, v112
	s_mul_i32 s20, s0, 0x650
	v_max_f32_e64 v118, |v114|, |v114|
	v_lshl_add_u64 v[114:115], v[6:7], 0, s[20:21]
	global_load_dword v134, v[114:115], off
	v_lshlrev_b32_e32 v114, 16, v112
	v_max_f32_e64 v114, |v114|, |v114|
	s_mul_i32 s20, s0, 0x654
	v_max_f32_e32 v118, v114, v118
	v_lshl_add_u64 v[114:115], v[6:7], 0, s[20:21]
	global_load_dword v135, v[114:115], off
	s_mul_i32 s20, s0, 0x658
	v_lshl_add_u64 v[114:115], v[6:7], 0, s[20:21]
	s_mul_i32 s20, s0, 0x65c
	v_max3_f32 v136, v116, v117, v118
	v_lshl_add_u64 v[116:117], v[6:7], 0, s[20:21]
	global_load_dword v137, v[114:115], off
	global_load_dword v138, v[116:117], off
	s_mul_i32 s20, s0, 0x660
	v_lshl_add_u64 v[114:115], v[6:7], 0, s[20:21]
	s_mul_i32 s20, s0, 0x664
	v_lshl_add_u64 v[116:117], v[6:7], 0, s[20:21]
	s_mul_i32 s20, s0, 0x668
	v_lshl_add_u64 v[118:119], v[6:7], 0, s[20:21]
	s_mul_i32 s20, s0, 0x66c
	v_lshl_add_u64 v[120:121], v[6:7], 0, s[20:21]
	s_mul_i32 s20, s0, 0x670
	v_lshl_add_u64 v[122:123], v[6:7], 0, s[20:21]
	s_mul_i32 s20, s0, 0x674
	v_lshl_add_u64 v[124:125], v[6:7], 0, s[20:21]
	s_mul_i32 s20, s0, 0x678
	v_lshl_add_u64 v[126:127], v[6:7], 0, s[20:21]
	s_mul_i32 s20, s0, 0x67c
	v_lshl_add_u64 v[128:129], v[6:7], 0, s[20:21]
	global_load_dword v139, v[114:115], off
	global_load_dword v140, v[116:117], off
	s_nop 0
	global_load_dword v118, v[118:119], off
	s_nop 0
	global_load_dword v119, v[120:121], off
	s_nop 0
	global_load_dword v120, v[122:123], off
	global_load_dword v121, v[124:125], off
	s_nop 0
	global_load_dword v122, v[126:127], off
	global_load_dword v123, v[128:129], off
	v_readlane_b32 s1, v5, 16
	v_readlane_b32 s20, v5, 48
	s_nop 0
	v_mov_b32_e32 v115, s1
	v_mov_b32_e32 v114, s20
	v_readlane_b32 s1, v5, 17
	v_readlane_b32 s20, v5, 49
	v_cndmask_b32_e32 v114, v114, v115, vcc
	v_mov_b32_e32 v116, s1
	v_mov_b32_e32 v115, s20
	v_readlane_b32 s1, v5, 18
	v_readlane_b32 s20, v5, 50
	v_cndmask_b32_e32 v115, v115, v116, vcc
	v_mov_b32_e32 v117, s1
	v_mov_b32_e32 v116, s20
	v_readlane_b32 s1, v5, 19
	v_readlane_b32 s20, v5, 51
	s_waitcnt vmcnt(0) lgkmcnt(0)
	v_mul_f32_e32 v114, v130, v114
	v_mul_f32_e32 v115, v131, v115
	v_cndmask_b32_e32 v116, v116, v117, vcc
	v_mov_b32_e32 v117, s20
	v_mov_b32_e32 v124, s1
	v_cndmask_b32_e32 v117, v117, v124, vcc
	v_cvt_pk_bf16_f32 v115, v114, v115
	v_readlane_b32 s1, v5, 20
	v_and_b32_e32 v114, 0xffff0000, v115
	v_lshlrev_b32_e32 v124, 16, v115
	v_mul_f32_e32 v116, v132, v116
	v_max_f32_e64 v114, |v114|, |v114|
	v_max_f32_e64 v124, |v124|, |v124|
	v_max_f32_e32 v124, v124, v114
	v_mul_f32_e32 v117, v133, v117
	v_cvt_pk_bf16_f32 v114, v116, v117
	v_readlane_b32 s20, v5, 52
	v_and_b32_e32 v116, 0xffff0000, v114
	v_lshlrev_b32_e32 v117, 16, v114
	v_max_f32_e64 v116, |v116|, |v116|
	v_max_f32_e64 v117, |v117|, |v117|
	v_max_f32_e32 v116, v117, v116
	v_max3_f32 v124, v136, v124, v116
	v_mov_b32_e32 v116, s20
	v_mov_b32_e32 v117, s1
	v_readlane_b32 s1, v5, 21
	v_readlane_b32 s20, v5, 53
	v_cndmask_b32_e32 v116, v116, v117, vcc
	v_mov_b32_e32 v125, s1
	v_mov_b32_e32 v117, s20
	v_readlane_b32 s1, v5, 22
	v_readlane_b32 s20, v5, 54
	v_cndmask_b32_e32 v117, v117, v125, vcc
	v_mov_b32_e32 v126, s1
	v_mov_b32_e32 v125, s20
	v_readlane_b32 s1, v5, 23
	v_readlane_b32 s20, v5, 55
	v_mul_f32_e32 v116, v134, v116
	v_cndmask_b32_e32 v125, v125, v126, vcc
	v_mul_f32_e32 v117, v135, v117
	v_mov_b32_e32 v126, s20
	v_mov_b32_e32 v127, s1
	v_cndmask_b32_e32 v126, v126, v127, vcc
	v_cvt_pk_bf16_f32 v117, v116, v117
	v_mul_f32_e32 v125, v137, v125
	v_and_b32_e32 v116, 0xffff0000, v117
	v_mul_f32_e32 v126, v138, v126
	v_max_f32_e64 v127, |v116|, |v116|
	v_lshlrev_b32_e32 v116, 16, v117
	v_readlane_b32 s1, v5, 24
	v_readlane_b32 s20, v5, 56
	v_max_f32_e64 v128, |v116|, |v116|
	v_cvt_pk_bf16_f32 v116, v125, v126
	v_mov_b32_e32 v126, s1
	v_mov_b32_e32 v125, s20
	v_readlane_b32 s1, v5, 25
	v_readlane_b32 s20, v5, 57
	v_cndmask_b32_e32 v125, v125, v126, vcc
	v_mov_b32_e32 v129, s1
	v_mov_b32_e32 v126, s20
	v_readlane_b32 s1, v5, 26
	v_readlane_b32 s20, v5, 58
	v_cndmask_b32_e32 v126, v126, v129, vcc
	v_mov_b32_e32 v130, s1
	v_mov_b32_e32 v129, s20
	v_cndmask_b32_e32 v129, v129, v130, vcc
	v_readlane_b32 s1, v5, 27
	v_readlane_b32 s20, v5, 59
	v_mul_f32_e32 v118, v118, v129
	v_mov_b32_e32 v130, s1
	v_mov_b32_e32 v129, s20
	v_mul_f32_e32 v125, v139, v125
	v_mul_f32_e32 v126, v140, v126
	v_cndmask_b32_e32 v129, v129, v130, vcc
	v_readlane_b32 s1, v5, 28
	v_readlane_b32 s20, v5, 60
	v_mul_f32_e32 v129, v119, v129
	v_cvt_pk_bf16_f32 v119, v125, v126
	v_mov_b32_e32 v126, s1
	v_mov_b32_e32 v125, s20
	v_cndmask_b32_e32 v125, v125, v126, vcc
	v_readlane_b32 s1, v5, 29
	v_readlane_b32 s20, v5, 61
	v_mul_f32_e32 v120, v120, v125
	v_mov_b32_e32 v126, s1
	v_mov_b32_e32 v125, s20
	v_cndmask_b32_e32 v125, v125, v126, vcc
	v_readlane_b32 s1, v5, 30
	v_readlane_b32 s20, v5, 62
	v_mul_f32_e32 v121, v121, v125
	v_mov_b32_e32 v126, s1
	v_mov_b32_e32 v125, s20
	v_cndmask_b32_e32 v125, v125, v126, vcc
	v_readlane_b32 s1, v5, 31
	v_readlane_b32 s20, v5, 63
	v_mul_f32_e32 v122, v122, v125
	v_mov_b32_e32 v125, s1
	v_mov_b32_e32 v5, s20
	v_cndmask_b32_e32 v5, v5, v125, vcc
	s_mul_i32 s20, s0, 0x700
	v_cvt_pk_bf16_f32 v118, v118, v129
	v_mul_f32_e32 v5, v123, v5
	v_cvt_pk_bf16_f32 v121, v120, v121
	v_cvt_pk_bf16_f32 v120, v122, v5
	v_lshl_add_u64 v[122:123], v[6:7], 0, s[20:21]
	global_load_dword v5, v[122:123], off
	v_and_b32_e32 v122, 0xffff0000, v116
	s_mul_i32 s20, s0, 0x704
	v_max_f32_e64 v126, |v122|, |v122|
	v_lshl_add_u64 v[122:123], v[6:7], 0, s[20:21]
	global_load_dword v138, v[122:123], off
	v_lshlrev_b32_e32 v122, 16, v116
	v_max_f32_e64 v122, |v122|, |v122|
	s_mul_i32 s20, s0, 0x708
	v_max_f32_e32 v126, v122, v126
	v_lshl_add_u64 v[122:123], v[6:7], 0, s[20:21]
	v_max_f32_e32 v125, v128, v127
	global_load_dword v139, v[122:123], off
	v_and_b32_e32 v122, 0xffff0000, v119
	s_mul_i32 s20, s0, 0x70c
	v_max3_f32 v124, v124, v125, v126
	v_max_f32_e64 v125, |v122|, |v122|
	v_lshl_add_u64 v[122:123], v[6:7], 0, s[20:21]
	global_load_dword v140, v[122:123], off
	v_lshlrev_b32_e32 v122, 16, v119
	v_max_f32_e64 v122, |v122|, |v122|
	v_max_f32_e32 v122, v122, v125
	v_and_b32_e32 v123, 0xffff0000, v118
	v_lshlrev_b32_e32 v125, 16, v118
	v_max_f32_e64 v123, |v123|, |v123|
	v_max_f32_e64 v125, |v125|, |v125|
	v_max_f32_e32 v123, v125, v123
	v_max3_f32 v124, v124, v122, v123
	v_and_b32_e32 v122, 0xffff0000, v121
	v_lshlrev_b32_e32 v123, 16, v121
	v_max_f32_e64 v122, |v122|, |v122|
	v_max_f32_e64 v123, |v123|, |v123|
	v_max_f32_e32 v125, v123, v122
	v_and_b32_e32 v122, 0xffff0000, v120
	s_mul_i32 s20, s0, 0x710
	v_max_f32_e64 v126, |v122|, |v122|
	v_lshl_add_u64 v[122:123], v[6:7], 0, s[20:21]
	global_load_dword v141, v[122:123], off
	v_lshlrev_b32_e32 v122, 16, v120
	v_max_f32_e64 v122, |v122|, |v122|
	s_mul_i32 s20, s0, 0x714
	v_max_f32_e32 v126, v122, v126
	v_lshl_add_u64 v[122:123], v[6:7], 0, s[20:21]
	global_load_dword v142, v[122:123], off
	s_mul_i32 s20, s0, 0x718
	v_lshl_add_u64 v[122:123], v[6:7], 0, s[20:21]
	s_mul_i32 s20, s0, 0x71c
	v_max3_f32 v143, v124, v125, v126
	v_lshl_add_u64 v[124:125], v[6:7], 0, s[20:21]
	global_load_dword v144, v[122:123], off
	global_load_dword v145, v[124:125], off
	s_mul_i32 s20, s0, 0x720
	v_lshl_add_u64 v[122:123], v[6:7], 0, s[20:21]
	s_mul_i32 s20, s0, 0x724
	v_lshl_add_u64 v[124:125], v[6:7], 0, s[20:21]
	s_mul_i32 s20, s0, 0x728
	v_lshl_add_u64 v[126:127], v[6:7], 0, s[20:21]
	s_mul_i32 s20, s0, 0x72c
	v_lshl_add_u64 v[128:129], v[6:7], 0, s[20:21]
	s_mul_i32 s20, s0, 0x730
	v_lshl_add_u64 v[130:131], v[6:7], 0, s[20:21]
	s_mul_i32 s20, s0, 0x734
	v_lshl_add_u64 v[132:133], v[6:7], 0, s[20:21]
	s_mul_i32 s20, s0, 0x738
	v_lshl_add_u64 v[134:135], v[6:7], 0, s[20:21]
	s_mul_i32 s20, s0, 0x73c
	v_lshl_add_u64 v[136:137], v[6:7], 0, s[20:21]
	global_load_dword v146, v[122:123], off
	global_load_dword v147, v[124:125], off
	s_nop 0
	global_load_dword v126, v[126:127], off
	s_nop 0
	global_load_dword v127, v[128:129], off
	s_nop 0
	global_load_dword v128, v[130:131], off
	global_load_dword v129, v[132:133], off
	s_nop 0
	global_load_dword v130, v[134:135], off
	global_load_dword v131, v[136:137], off
	v_readlane_b32 s1, v0, 0
	v_readlane_b32 s20, v0, 32
	s_nop 0
	v_mov_b32_e32 v123, s1
	v_mov_b32_e32 v122, s20
	v_cndmask_b32_e32 v122, v122, v123, vcc
	v_readlane_b32 s1, v0, 1
	v_readlane_b32 s20, v0, 33
	s_waitcnt vmcnt(0) lgkmcnt(0)
	v_mul_f32_e32 v5, v5, v122
	v_mov_b32_e32 v122, s20
	v_mov_b32_e32 v123, s1
	v_readlane_b32 s1, v0, 2
	v_readlane_b32 s20, v0, 34
	v_cndmask_b32_e32 v122, v122, v123, vcc
	v_mov_b32_e32 v124, s1
	v_mov_b32_e32 v123, s20
	v_cndmask_b32_e32 v123, v123, v124, vcc
	v_readlane_b32 s1, v0, 3
	v_readlane_b32 s20, v0, 35
	v_mul_f32_e32 v122, v138, v122
	v_mul_f32_e32 v124, v139, v123
	v_mov_b32_e32 v123, s20
	v_mov_b32_e32 v125, s1
	v_cndmask_b32_e32 v123, v123, v125, vcc
	v_readlane_b32 s1, v0, 4
	v_readlane_b32 s20, v0, 36
	v_mul_f32_e32 v125, v140, v123
	v_cvt_pk_bf16_f32 v123, v5, v122
	s_nop 0
	v_and_b32_e32 v5, 0xffff0000, v123
	v_lshlrev_b32_e32 v122, 16, v123
	v_max_f32_e64 v5, |v5|, |v5|
	v_max_f32_e64 v122, |v122|, |v122|
	v_max_f32_e32 v5, v122, v5
	v_cvt_pk_bf16_f32 v122, v124, v125
	s_nop 0
	v_and_b32_e32 v124, 0xffff0000, v122
	v_lshlrev_b32_e32 v125, 16, v122
	v_max_f32_e64 v124, |v124|, |v124|
	v_max_f32_e64 v125, |v125|, |v125|
	v_max_f32_e32 v124, v125, v124
	v_max3_f32 v5, v143, v5, v124
	v_mov_b32_e32 v124, s20
	v_mov_b32_e32 v125, s1
	v_readlane_b32 s1, v0, 5
	v_readlane_b32 s20, v0, 37
	v_cndmask_b32_e32 v124, v124, v125, vcc
	v_mov_b32_e32 v132, s1
	v_mov_b32_e32 v125, s20
	v_readlane_b32 s1, v0, 6
	v_readlane_b32 s20, v0, 38
	v_cndmask_b32_e32 v125, v125, v132, vcc
	v_mov_b32_e32 v133, s1
	v_mov_b32_e32 v132, s20
	v_readlane_b32 s1, v0, 7
	v_readlane_b32 s20, v0, 39
	v_mul_f32_e32 v124, v141, v124
	v_mul_f32_e32 v125, v142, v125
	v_cndmask_b32_e32 v132, v132, v133, vcc
	v_mov_b32_e32 v133, s20
	v_mov_b32_e32 v134, s1
	v_cndmask_b32_e32 v133, v133, v134, vcc
	v_cvt_pk_bf16_f32 v125, v124, v125
	v_mul_f32_e32 v132, v144, v132
	v_and_b32_e32 v124, 0xffff0000, v125
	v_mul_f32_e32 v133, v145, v133
	v_max_f32_e64 v134, |v124|, |v124|
	v_lshlrev_b32_e32 v124, 16, v125
	v_readlane_b32 s1, v0, 8
	v_readlane_b32 s20, v0, 40
	v_max_f32_e64 v135, |v124|, |v124|
	v_cvt_pk_bf16_f32 v124, v132, v133
	v_mov_b32_e32 v133, s1
	v_mov_b32_e32 v132, s20
	v_readlane_b32 s1, v0, 9
	v_readlane_b32 s20, v0, 41
	v_cndmask_b32_e32 v132, v132, v133, vcc
	v_mov_b32_e32 v136, s1
	v_mov_b32_e32 v133, s20
	v_readlane_b32 s1, v0, 10
	v_readlane_b32 s20, v0, 42
	v_cndmask_b32_e32 v133, v133, v136, vcc
	v_mov_b32_e32 v137, s1
	v_mov_b32_e32 v136, s20
	v_cndmask_b32_e32 v136, v136, v137, vcc
	v_readlane_b32 s1, v0, 11
	v_readlane_b32 s20, v0, 43
	v_mul_f32_e32 v126, v126, v136
	v_mov_b32_e32 v137, s1
	v_mov_b32_e32 v136, s20
	v_mul_f32_e32 v132, v146, v132
	v_mul_f32_e32 v133, v147, v133
	v_cndmask_b32_e32 v136, v136, v137, vcc
	v_readlane_b32 s1, v0, 12
	v_readlane_b32 s20, v0, 44
	v_mul_f32_e32 v136, v127, v136
	v_cvt_pk_bf16_f32 v127, v132, v133
	v_mov_b32_e32 v133, s1
	v_mov_b32_e32 v132, s20
	v_cndmask_b32_e32 v132, v132, v133, vcc
	v_readlane_b32 s1, v0, 13
	v_readlane_b32 s20, v0, 45
	v_mul_f32_e32 v128, v128, v132
	v_mov_b32_e32 v133, s1
	v_mov_b32_e32 v132, s20
	v_cndmask_b32_e32 v132, v132, v133, vcc
	v_readlane_b32 s1, v0, 14
	v_readlane_b32 s20, v0, 46
	v_mul_f32_e32 v129, v129, v132
	v_mov_b32_e32 v133, s1
	v_mov_b32_e32 v132, s20
	v_cndmask_b32_e32 v132, v132, v133, vcc
	v_readlane_b32 s1, v0, 15
	v_readlane_b32 s20, v0, 47
	v_mul_f32_e32 v130, v130, v132
	v_mov_b32_e32 v133, s1
	v_mov_b32_e32 v132, s20
	v_cndmask_b32_e32 v132, v132, v133, vcc
	v_mul_f32_e32 v131, v131, v132
	s_mul_i32 s20, s0, 0x740
	v_cvt_pk_bf16_f32 v126, v126, v136
	v_cvt_pk_bf16_f32 v129, v128, v129
	v_cvt_pk_bf16_f32 v128, v130, v131
	v_lshl_add_u64 v[130:131], v[6:7], 0, s[20:21]
	global_load_dword v144, v[130:131], off
	v_and_b32_e32 v130, 0xffff0000, v124
	s_mul_i32 s20, s0, 0x744
	v_max_f32_e64 v133, |v130|, |v130|
	v_lshl_add_u64 v[130:131], v[6:7], 0, s[20:21]
	global_load_dword v145, v[130:131], off
	v_lshlrev_b32_e32 v130, 16, v124
	v_max_f32_e64 v130, |v130|, |v130|
	s_mul_i32 s20, s0, 0x748
	v_max_f32_e32 v133, v130, v133
	v_lshl_add_u64 v[130:131], v[6:7], 0, s[20:21]
	v_max_f32_e32 v132, v135, v134
	global_load_dword v146, v[130:131], off
	v_and_b32_e32 v130, 0xffff0000, v127
	s_mul_i32 s20, s0, 0x74c
	v_max3_f32 v5, v5, v132, v133
	v_max_f32_e64 v132, |v130|, |v130|
	v_lshl_add_u64 v[130:131], v[6:7], 0, s[20:21]
	global_load_dword v147, v[130:131], off
	v_lshlrev_b32_e32 v130, 16, v127
	v_max_f32_e64 v130, |v130|, |v130|
	v_max_f32_e32 v130, v130, v132
	v_and_b32_e32 v131, 0xffff0000, v126
	v_lshlrev_b32_e32 v132, 16, v126
	v_max_f32_e64 v131, |v131|, |v131|
	v_max_f32_e64 v132, |v132|, |v132|
	v_max_f32_e32 v131, v132, v131
	v_max3_f32 v5, v5, v130, v131
	v_and_b32_e32 v130, 0xffff0000, v129
	v_lshlrev_b32_e32 v131, 16, v129
	v_max_f32_e64 v130, |v130|, |v130|
	v_max_f32_e64 v131, |v131|, |v131|
	v_max_f32_e32 v132, v131, v130
	v_and_b32_e32 v130, 0xffff0000, v128
	s_mul_i32 s20, s0, 0x750
	v_max_f32_e64 v133, |v130|, |v130|
	v_lshl_add_u64 v[130:131], v[6:7], 0, s[20:21]
	global_load_dword v148, v[130:131], off
	v_lshlrev_b32_e32 v130, 16, v128
	v_max_f32_e64 v130, |v130|, |v130|
	s_mul_i32 s20, s0, 0x754
	v_max_f32_e32 v133, v130, v133
	v_lshl_add_u64 v[130:131], v[6:7], 0, s[20:21]
	global_load_dword v149, v[130:131], off
	s_mul_i32 s20, s0, 0x758
	v_lshl_add_u64 v[130:131], v[6:7], 0, s[20:21]
	s_mul_i32 s20, s0, 0x75c
	v_max3_f32 v5, v5, v132, v133
	v_lshl_add_u64 v[132:133], v[6:7], 0, s[20:21]
	global_load_dword v150, v[130:131], off
	global_load_dword v151, v[132:133], off
	s_mul_i32 s20, s0, 0x760
	v_lshl_add_u64 v[130:131], v[6:7], 0, s[20:21]
	s_mul_i32 s20, s0, 0x764
	v_lshl_add_u64 v[132:133], v[6:7], 0, s[20:21]
	s_mul_i32 s20, s0, 0x768
	v_lshl_add_u64 v[134:135], v[6:7], 0, s[20:21]
	s_mul_i32 s20, s0, 0x76c
	v_lshl_add_u64 v[136:137], v[6:7], 0, s[20:21]
	s_mul_i32 s20, s0, 0x770
	v_lshl_add_u64 v[138:139], v[6:7], 0, s[20:21]
	s_mul_i32 s20, s0, 0x774
	v_lshl_add_u64 v[140:141], v[6:7], 0, s[20:21]
	s_mul_i32 s20, s0, 0x778
	v_lshl_add_u64 v[142:143], v[6:7], 0, s[20:21]
	s_mul_i32 s20, s0, 0x77c
	v_lshl_add_u64 v[6:7], v[6:7], 0, s[20:21]
	global_load_dword v152, v[130:131], off
	s_nop 0
	global_load_dword v132, v[132:133], off
	s_nop 0
	global_load_dword v133, v[134:135], off
	s_nop 0
	global_load_dword v134, v[136:137], off
	global_load_dword v135, v[138:139], off
	s_nop 0
	global_load_dword v136, v[140:141], off
	global_load_dword v137, v[142:143], off
	global_load_dword v138, v[6:7], off
	v_readlane_b32 s0, v0, 16
	v_readlane_b32 s1, v0, 48
	s_nop 0
	v_mov_b32_e32 v7, s0
	v_mov_b32_e32 v6, s1
	v_readlane_b32 s0, v0, 17
	v_readlane_b32 s1, v0, 49
	v_cndmask_b32_e32 v6, v6, v7, vcc
	v_mov_b32_e32 v130, s0
	v_mov_b32_e32 v7, s1
	v_readlane_b32 s0, v0, 18
	v_readlane_b32 s1, v0, 50
	v_cndmask_b32_e32 v7, v7, v130, vcc
	v_mov_b32_e32 v131, s0
	v_mov_b32_e32 v130, s1
	v_readlane_b32 s0, v0, 19
	v_readlane_b32 s1, v0, 51
	s_waitcnt vmcnt(0) lgkmcnt(0)
	v_mul_f32_e32 v6, v144, v6
	v_mul_f32_e32 v7, v145, v7
	v_cndmask_b32_e32 v130, v130, v131, vcc
	v_mov_b32_e32 v131, s1
	v_mov_b32_e32 v139, s0
	v_cndmask_b32_e32 v131, v131, v139, vcc
	v_cvt_pk_bf16_f32 v7, v6, v7
	v_readlane_b32 s0, v0, 20
	v_and_b32_e32 v6, 0xffff0000, v7
	v_lshlrev_b32_e32 v139, 16, v7
	v_mul_f32_e32 v130, v146, v130
	v_max_f32_e64 v6, |v6|, |v6|
	v_max_f32_e64 v139, |v139|, |v139|
	v_max_f32_e32 v139, v139, v6
	v_mul_f32_e32 v131, v147, v131
	v_cvt_pk_bf16_f32 v6, v130, v131
	v_readlane_b32 s1, v0, 52
	v_and_b32_e32 v130, 0xffff0000, v6
	v_lshlrev_b32_e32 v131, 16, v6
	v_max_f32_e64 v130, |v130|, |v130|
	v_max_f32_e64 v131, |v131|, |v131|
	v_max_f32_e32 v130, v131, v130
	v_max3_f32 v5, v5, v139, v130
	v_mov_b32_e32 v130, s1
	v_mov_b32_e32 v131, s0
	v_readlane_b32 s0, v0, 21
	v_readlane_b32 s1, v0, 53
	v_cndmask_b32_e32 v130, v130, v131, vcc
	v_mov_b32_e32 v139, s0
	v_mov_b32_e32 v131, s1
	v_readlane_b32 s0, v0, 22
	v_readlane_b32 s1, v0, 54
	v_cndmask_b32_e32 v131, v131, v139, vcc
	v_mov_b32_e32 v140, s0
	v_mov_b32_e32 v139, s1
	v_readlane_b32 s0, v0, 23
	v_readlane_b32 s1, v0, 55
	v_mul_f32_e32 v130, v148, v130
	v_cndmask_b32_e32 v139, v139, v140, vcc
	v_mul_f32_e32 v131, v149, v131
	v_mov_b32_e32 v140, s1
	v_mov_b32_e32 v141, s0
	v_cndmask_b32_e32 v140, v140, v141, vcc
	v_cvt_pk_bf16_f32 v131, v130, v131
	v_mul_f32_e32 v139, v150, v139
	v_and_b32_e32 v130, 0xffff0000, v131
	v_lshlrev_b32_e32 v141, 16, v131
	v_mul_f32_e32 v140, v151, v140
	v_max_f32_e64 v130, |v130|, |v130|
	v_max_f32_e64 v141, |v141|, |v141|
	v_max_f32_e32 v141, v141, v130
	v_cvt_pk_bf16_f32 v130, v139, v140
	v_readlane_b32 s0, v0, 24
	v_and_b32_e32 v139, 0xffff0000, v130
	v_lshlrev_b32_e32 v140, 16, v130
	v_max_f32_e64 v139, |v139|, |v139|
	v_max_f32_e64 v140, |v140|, |v140|
	v_max_f32_e32 v139, v140, v139
	v_readlane_b32 s1, v0, 56
	v_max3_f32 v5, v5, v141, v139
	v_mov_b32_e32 v140, s0
	v_mov_b32_e32 v139, s1
	v_readlane_b32 s0, v0, 25
	v_readlane_b32 s1, v0, 57
	v_cndmask_b32_e32 v139, v139, v140, vcc
	v_mov_b32_e32 v141, s0
	v_mov_b32_e32 v140, s1
	v_cndmask_b32_e32 v140, v140, v141, vcc
	v_readlane_b32 s0, v0, 26
	v_readlane_b32 s1, v0, 58
	v_mul_f32_e32 v132, v132, v140
	v_mov_b32_e32 v141, s0
	v_mov_b32_e32 v140, s1
	v_cndmask_b32_e32 v140, v140, v141, vcc
	v_readlane_b32 s0, v0, 27
	v_readlane_b32 s1, v0, 59
	v_mul_f32_e32 v140, v133, v140
	v_mov_b32_e32 v141, s0
	v_mov_b32_e32 v133, s1
	v_mul_f32_e32 v139, v152, v139
	v_cndmask_b32_e32 v133, v133, v141, vcc
	v_mul_f32_e32 v134, v134, v133
	v_cvt_pk_bf16_f32 v133, v139, v132
	v_readlane_b32 s0, v0, 28
	v_and_b32_e32 v132, 0xffff0000, v133
	v_lshlrev_b32_e32 v139, 16, v133
	v_max_f32_e64 v132, |v132|, |v132|
	v_max_f32_e64 v139, |v139|, |v139|
	v_max_f32_e32 v139, v139, v132
	v_cvt_pk_bf16_f32 v132, v140, v134
	v_readlane_b32 s1, v0, 60
	v_and_b32_e32 v134, 0xffff0000, v132
	v_lshlrev_b32_e32 v140, 16, v132
	v_max_f32_e64 v134, |v134|, |v134|
	v_max_f32_e64 v140, |v140|, |v140|
	v_max_f32_e32 v134, v140, v134
	v_max3_f32 v5, v5, v139, v134
	v_mov_b32_e32 v134, s1
	v_mov_b32_e32 v139, s0
	v_cndmask_b32_e32 v134, v134, v139, vcc
	v_readlane_b32 s0, v0, 29
	v_readlane_b32 s1, v0, 61
	v_mul_f32_e32 v134, v135, v134
	v_mov_b32_e32 v139, s0
	v_mov_b32_e32 v135, s1
	v_cndmask_b32_e32 v135, v135, v139, vcc
	v_readlane_b32 s0, v0, 30
	v_readlane_b32 s1, v0, 62
	v_mul_f32_e32 v135, v136, v135
	v_mov_b32_e32 v139, s0
	v_mov_b32_e32 v136, s1
	v_cndmask_b32_e32 v136, v136, v139, vcc
	v_readlane_b32 s0, v0, 31
	v_readlane_b32 s1, v0, 63
	v_mul_f32_e32 v136, v137, v136
	v_mov_b32_e32 v137, s0
	v_mov_b32_e32 v0, s1
	v_cndmask_b32_e32 v0, v0, v137, vcc
	v_cvt_pk_bf16_f32 v135, v134, v135
	v_mul_f32_e32 v0, v138, v0
	v_and_b32_e32 v134, 0xffff0000, v135
	v_lshlrev_b32_e32 v137, 16, v135
	v_max_f32_e64 v134, |v134|, |v134|
	v_max_f32_e64 v137, |v137|, |v137|
	v_max_f32_e32 v137, v137, v134
	v_cvt_pk_bf16_f32 v134, v136, v0
	v_cmp_gt_i32_e32 vcc, 32, v2
	v_and_b32_e32 v0, 0xffff0000, v134
	v_lshlrev_b32_e32 v136, 16, v134
	v_max_f32_e64 v0, |v0|, |v0|
	v_max_f32_e64 v136, |v136|, |v136|
	v_max_f32_e32 v0, v136, v0
	v_max3_f32 v0, v5, v137, v0
	v_mov_b32_e32 v5, v0
	s_nop 1
	v_permlane32_swap_b32_e32 v0, v5
	s_and_saveexec_b64 s[0:1], vcc
	v_max_f32_e32 v0, v0, v0
	v_max_f32_e32 v5, v5, v5
	v_max_f32_e32 v0, v0, v5
	v_lshl_add_u32 v5, v2, 2, s27
	ds_write_b32 v5, v0
	s_or_b64 exec, exec, s[0:1]
	v_lshl_add_u32 v0, v9, 2, 0
	v_add_u32_e32 v0, 0x20000, v0
	s_waitcnt lgkmcnt(0)
	s_waitcnt lgkmcnt(0)
	s_barrier
	ds_read2_b32 v[136:137], v0 offset1:32
	ds_read2_b32 v[138:139], v0 offset0:64 offset1:96
	ds_read2_b32 v[140:141], v0 offset0:128 offset1:160
	ds_read2_b32 v[142:143], v0 offset0:192 offset1:224
	s_and_b64 s[0:1], s[30:31], vcc
	s_waitcnt lgkmcnt(3)
	v_max3_f32 v0, v136, 0, v137
	s_waitcnt lgkmcnt(2)
	v_max3_f32 v0, v0, v138, v139
	s_waitcnt lgkmcnt(1)
	v_max3_f32 v0, v0, v140, v141
	s_waitcnt lgkmcnt(0)
	v_max3_f32 v0, v0, v142, v143
	s_and_saveexec_b64 s[54:55], s[0:1]
	s_cbranch_execz .LBB0_34
	s_and_b64 s[0:1], s[52:53], exec
	s_cselect_b32 s1, s61, 0x6ce00000
	s_cselect_b32 s0, s23, 0xd000
	s_add_u32 s1, s16, s1
	s_addc_u32 s20, s17, 0
	s_mul_hi_i32 s28, s0, s50
	s_mul_i32 s0, s0, s50
	s_add_u32 s0, s1, s0
	s_addc_u32 s1, s20, s28
	v_ashrrev_i32_e32 v5, 31, v4
	v_mul_f32_e32 v136, 0x3c010204, v0
	v_lshl_add_u64 v[4:5], v[4:5], 2, s[0:1]
	global_store_dword v[4:5], v136, off
	s_branch .LBB0_34

.LBB0_256:
	s_lshl_b32 s8, s89, 5
	v_lshlrev_b32_e32 v132, 1, v0
	s_mul_hi_i32 s9, s66, s8
	s_mul_i32 s8, s66, s8
	v_and_b32_e32 v132, 24, v132
	v_and_b32_e32 v133, 16, v0
	s_lshl_b64 s[8:9], s[8:9], 2
	v_add_u32_e32 v0, s58, v0
	s_add_u32 s8, s10, s8
	v_and_or_b32 v0, v0, s37, v132
	s_addc_u32 s9, s11, s9
	v_lshl_or_b32 v0, v0, 2, v133
	v_lshl_add_u64 v[132:133], s[8:9], 0, v[0:1]
	s_lshl_b32 s70, s66, 2
	global_load_dword v218, v[132:133], off
	v_lshl_add_u64 v[132:133], v[132:133], 0, s[70:71]
	global_load_dword v219, v[132:133], off
	v_lshl_add_u64 v[132:133], v[132:133], 0, s[70:71]
	global_load_dword v220, v[132:133], off
	v_lshl_add_u64 v[132:133], v[132:133], 0, s[70:71]
	global_load_dword v221, v[132:133], off
	v_lshl_add_u64 v[132:133], v[132:133], 0, s[70:71]
	global_load_dword v222, v[132:133], off
	v_lshl_add_u64 v[132:133], v[132:133], 0, s[70:71]
	global_load_dword v223, v[132:133], off
	v_lshl_add_u64 v[132:133], v[132:133], 0, s[70:71]
	global_load_dword v224, v[132:133], off
	v_lshl_add_u64 v[132:133], v[132:133], 0, s[70:71]
	global_load_dword v225, v[132:133], off
	v_lshl_add_u64 v[132:133], v[132:133], 0, s[70:71]
	global_load_dword v226, v[132:133], off
	v_lshl_add_u64 v[132:133], v[132:133], 0, s[70:71]
	global_load_dword v227, v[132:133], off
	v_lshl_add_u64 v[132:133], v[132:133], 0, s[70:71]
	global_load_dword v228, v[132:133], off
	v_lshl_add_u64 v[132:133], v[132:133], 0, s[70:71]
	global_load_dword v229, v[132:133], off
	v_lshl_add_u64 v[132:133], v[132:133], 0, s[70:71]
	global_load_dword v230, v[132:133], off
	v_lshl_add_u64 v[132:133], v[132:133], 0, s[70:71]
	global_load_dword v231, v[132:133], off
	v_lshl_add_u64 v[132:133], v[132:133], 0, s[70:71]
	global_load_dword v232, v[132:133], off
	v_lshl_add_u64 v[132:133], v[132:133], 0, s[70:71]
	global_load_dword v233, v[132:133], off
	v_lshl_add_u64 v[132:133], v[132:133], 0, s[70:71]
	global_load_dword v234, v[132:133], off
	v_lshl_add_u64 v[132:133], v[132:133], 0, s[70:71]
	global_load_dword v235, v[132:133], off
	v_lshl_add_u64 v[132:133], v[132:133], 0, s[70:71]
	global_load_dword v236, v[132:133], off
	v_lshl_add_u64 v[132:133], v[132:133], 0, s[70:71]
	global_load_dword v237, v[132:133], off
	v_lshl_add_u64 v[132:133], v[132:133], 0, s[70:71]
	global_load_dword v238, v[132:133], off
	v_lshl_add_u64 v[132:133], v[132:133], 0, s[70:71]
	global_load_dword v239, v[132:133], off
	v_lshl_add_u64 v[132:133], v[132:133], 0, s[70:71]
	global_load_dword v240, v[132:133], off
	v_lshl_add_u64 v[132:133], v[132:133], 0, s[70:71]
	global_load_dword v241, v[132:133], off
	v_lshl_add_u64 v[132:133], v[132:133], 0, s[70:71]
	global_load_dword v242, v[132:133], off
	v_lshl_add_u64 v[132:133], v[132:133], 0, s[70:71]
	global_load_dword v243, v[132:133], off
	v_lshl_add_u64 v[132:133], v[132:133], 0, s[70:71]
	global_load_dword v244, v[132:133], off
	v_lshl_add_u64 v[132:133], v[132:133], 0, s[70:71]
	global_load_dword v245, v[132:133], off
	v_lshl_add_u64 v[132:133], v[132:133], 0, s[70:71]
	global_load_dword v246, v[132:133], off
	v_lshl_add_u64 v[132:133], v[132:133], 0, s[70:71]
	global_load_dword v247, v[132:133], off
	v_lshl_add_u64 v[132:133], v[132:133], 0, s[70:71]
	global_load_dword v248, v[132:133], off
	v_lshl_add_u64 v[132:133], v[132:133], 0, s[70:71]
	global_load_dword v249, v[132:133], off

.LBB0_331:
	s_lshl_b32 s12, s21, 5
	s_lshl_b32 s9, s28, 6
	s_mul_hi_i32 s13, s42, s12
	s_mul_i32 s12, s42, s12
	s_and_b32 s22, s21, 1
	s_lshl_b64 s[12:13], s[12:13], 2
	v_add_u32_e32 v0, s9, v8
	s_add_u32 s12, s14, s12
	v_and_or_b32 v0, v0, s34, v9
	s_addc_u32 s13, s15, s13
	v_lshl_or_b32 v0, v0, 2, v10
	v_lshl_add_u64 v[12:13], s[12:13], 0, v[0:1]
	s_lshl_b32 s70, s42, 2
	v_lshl_add_u64 v[14:15], v[12:13], 0, s[70:71]
	v_lshl_add_u64 v[16:17], v[14:15], 0, s[70:71]
	v_lshl_add_u64 v[18:19], v[16:17], 0, s[70:71]
	v_lshl_add_u64 v[20:21], v[18:19], 0, s[70:71]
	v_lshl_add_u64 v[22:23], v[20:21], 0, s[70:71]
	v_lshl_add_u64 v[24:25], v[22:23], 0, s[70:71]
	v_lshl_add_u64 v[26:27], v[24:25], 0, s[70:71]
	v_lshl_add_u64 v[28:29], v[26:27], 0, s[70:71]
	v_lshl_add_u64 v[30:31], v[28:29], 0, s[70:71]
	v_lshl_add_u64 v[32:33], v[30:31], 0, s[70:71]
	v_lshl_add_u64 v[36:37], v[32:33], 0, s[70:71]
	v_lshl_add_u64 v[38:39], v[36:37], 0, s[70:71]
	v_lshl_add_u64 v[40:41], v[38:39], 0, s[70:71]
	v_lshl_add_u64 v[42:43], v[40:41], 0, s[70:71]
	v_lshl_add_u64 v[44:45], v[42:43], 0, s[70:71]
	v_lshl_add_u64 v[46:47], v[44:45], 0, s[70:71]
	v_lshl_add_u64 v[48:49], v[46:47], 0, s[70:71]
	v_lshl_add_u64 v[50:51], v[48:49], 0, s[70:71]
	v_lshl_add_u64 v[52:53], v[50:51], 0, s[70:71]
	v_lshl_add_u64 v[54:55], v[52:53], 0, s[70:71]
	v_lshl_add_u64 v[56:57], v[54:55], 0, s[70:71]
	v_lshl_add_u64 v[58:59], v[56:57], 0, s[70:71]
	v_lshl_add_u64 v[60:61], v[58:59], 0, s[70:71]
	v_lshl_add_u64 v[62:63], v[60:61], 0, s[70:71]
	v_lshl_add_u64 v[64:65], v[62:63], 0, s[70:71]
	v_lshl_add_u64 v[66:67], v[64:65], 0, s[70:71]
	v_lshl_add_u64 v[68:69], v[66:67], 0, s[70:71]
	v_lshl_add_u64 v[70:71], v[68:69], 0, s[70:71]
	v_lshl_add_u64 v[72:73], v[70:71], 0, s[70:71]
	v_lshl_add_u64 v[74:75], v[72:73], 0, s[70:71]
	v_lshl_add_u64 v[76:77], v[74:75], 0, s[70:71]
	global_load_dword v35, v[12:13], off
	s_nop 0
	global_load_dword v14, v[14:15], off
	s_nop 0
	global_load_dword v15, v[16:17], off
	global_load_dword v78, v[18:19], off
	global_load_dword v79, v[20:21], off
	s_nop 0
	global_load_dword v22, v[22:23], off
	s_nop 0
	global_load_dword v23, v[24:25], off
	s_nop 0
	global_load_dword v24, v[26:27], off
	global_load_dword v25, v[28:29], off
	s_nop 0
	global_load_dword v26, v[30:31], off
	global_load_dword v27, v[32:33], off
	global_load_dword v28, v[36:37], off
	global_load_dword v29, v[38:39], off
	s_nop 0
	global_load_dword v30, v[40:41], off
	global_load_dword v31, v[42:43], off
	global_load_dword v32, v[44:45], off
	global_load_dword v33, v[46:47], off
	global_load_dword v36, v[48:49], off
	global_load_dword v37, v[50:51], off
	global_load_dword v38, v[52:53], off
	global_load_dword v39, v[54:55], off
	global_load_dword v40, v[56:57], off
	global_load_dword v41, v[58:59], off
	global_load_dword v42, v[60:61], off
	global_load_dword v43, v[62:63], off
	global_load_dword v44, v[64:65], off
	global_load_dword v45, v[66:67], off
	global_load_dword v46, v[68:69], off
	global_load_dword v47, v[70:71], off
	global_load_dword v48, v[72:73], off
	global_load_dword v49, v[74:75], off
	global_load_dword v50, v[76:77], off
	v_mov_b64_e32 v[12:13], s[10:11]
	s_lshr_b32 s11, s28, 2
	s_and_b32 s9, s9, 0xc0
	v_mov_b32_e32 v0, s11
	v_add_u32_e32 v16, s9, v8
	s_ashr_i32 s10, s21, 1
	v_mad_u64_u32 v[12:13], s[8:9], s8, v0, v[12:13]
	v_lshlrev_b32_e32 v0, 7, v16
	v_lshrrev_b32_e32 v16, 3, v16
	s_ashr_i32 s11, s10, 31
	v_and_or_b32 v16, v16, 14, s22
	s_lshl_b64 s[8:9], s[10:11], 15
	v_and_b32_e32 v0, 0xffffc000, v0
	v_lshlrev_b32_e32 v16, 10, v16
	v_lshl_add_u64 v[12:13], v[12:13], 0, s[8:9]
	v_or3_b32 v0, v16, v0, v11
	v_lshl_add_u64 v[12:13], v[12:13], 0, v[0:1]
	v_lshl_add_u64 v[16:17], v[12:13], 0, v[2:3]
	v_lshl_add_u64 v[18:19], v[12:13], 0, v[4:5]
	v_lshl_add_u64 v[20:21], v[12:13], 0, v[6:7]
	s_add_i32 s31, s31, 1
	s_addk_i32 s20, 0x800
	s_cmp_lt_i32 s20, s75
	s_waitcnt vmcnt(0) lgkmcnt(0)
	v_cvt_pk_bf16_f32 v12, v35, v14
	v_cvt_pk_bf16_f32 v13, v15, v78
	v_cvt_pk_bf16_f32 v14, v79, v22
	v_cvt_pk_bf16_f32 v15, v23, v24
	global_store_dwordx4 v[16:17], v[12:15], off
	s_nop 1
	v_cvt_pk_bf16_f32 v12, v25, v26
	v_cvt_pk_bf16_f32 v13, v27, v28
	v_cvt_pk_bf16_f32 v14, v29, v30
	v_cvt_pk_bf16_f32 v15, v31, v32
	global_store_dwordx4 v[16:17], v[12:15], off offset:16
	s_nop 1
	v_cvt_pk_bf16_f32 v12, v33, v36
	v_cvt_pk_bf16_f32 v13, v37, v38
	v_cvt_pk_bf16_f32 v14, v39, v40
	v_cvt_pk_bf16_f32 v15, v41, v42
	global_store_dwordx4 v[18:19], v[12:15], off
	s_nop 1
	v_cvt_pk_bf16_f32 v12, v43, v44
	v_cvt_pk_bf16_f32 v13, v45, v46
	v_cvt_pk_bf16_f32 v14, v47, v48
	v_cvt_pk_bf16_f32 v15, v49, v50
	global_store_dwordx4 v[20:21], v[12:15], off offset:16
	s_cbranch_scc0 .LBB0_349

.LBB0_407:
	s_ashr_i32 s10, s49, 7
	s_ashr_i32 s11, s10, 31
	s_lshl_b32 s8, s49, 6
	s_lshl_b64 s[14:15], s[10:11], 11
	s_and_b32 s51, s8, 0x7c0
	s_or_b32 s14, s14, s51
	s_mul_i32 s8, s15, 0x6800
	s_mul_hi_u32 s9, s14, 0x6800
	s_bfe_u32 s28, s49, 0x20005
	s_add_i32 s9, s9, s8
	s_mul_i32 s8, s14, 0x6800
	s_add_u32 s8, s16, s8
	s_addc_u32 s9, s17, s9
	s_lshl_b32 s11, s28, 10
	s_add_u32 s8, s8, s11
	s_addc_u32 s9, s9, 0
	s_mul_hi_i32 s11, s10, 0x3400000
	s_mul_i32 s10, s10, 0x3400000
	s_add_u32 s10, s16, s10
	s_addc_u32 s11, s17, s11
	s_lshl_b32 s12, s28, 8
	s_add_u32 s12, s10, s12
	s_addc_u32 s13, s11, 0
	s_add_u32 s10, s12, 0x1000
	s_addc_u32 s11, s13, 0
	s_mov_b32 s20, -1
	s_add_u32 s12, s12, 0x1400
	s_addc_u32 s13, s13, 0
	v_mbcnt_lo_u32_b32 v0, s20, 0
	v_mbcnt_hi_u32_b32 v0, s20, v0
	s_add_i32 s20, s51, 0xffffff80
	s_lshr_b32 s20, s20, 6
	s_cmpk_gt_u32 s51, 0x80
	s_cselect_b32 s20, s20, 0
	s_add_i32 s21, s51, 0xbf
	s_lshr_b32 s21, s21, 6
	s_min_u32 s27, s21, 31
	s_add_i32 s50, s27, 1
	s_lshl_b32 s21, s28, 4
	s_add_u32 s34, s42, s21
	v_add_u32_e32 v174, s76, v0
	s_addc_u32 s35, s43, 0
	v_mov_b64_e32 v[2:3], s[34:35]
	v_ashrrev_i32_e32 v182, 4, v174
	global_load_dword v67, v[2:3], off
	v_and_b32_e32 v3, 0xfffff0, v182
	v_lshlrev_b32_e32 v4, 1, v182
	v_lshlrev_b32_e32 v0, 3, v174
	v_and_or_b32 v3, v4, 8, v3
	v_lshrrev_b32_e32 v3, 1, v3
	v_bfe_u32 v5, v0, 5, 2
	v_and_b32_e32 v2, 0x78, v0
	v_or_b32_e32 v0, v3, v5
	v_lshrrev_b32_e32 v4, 1, v182
	v_lshlrev_b32_e32 v3, 9, v0
	v_and_b32_e32 v0, 3, v182
	v_and_or_b32 v0, v4, 4, v0
	v_lshlrev_b32_e32 v10, 6, v0
	v_lshlrev_b32_e32 v0, 1, v2
	v_add_u32_e32 v2, 32, v182
	v_and_b32_e32 v4, 0xfffff0, v2
	v_lshlrev_b32_e32 v6, 1, v2
	v_and_or_b32 v4, v6, 8, v4
	v_lshrrev_b32_e32 v4, 1, v4
	v_or_b32_e32 v4, v4, v5
	v_and_b32_e32 v11, 48, v0
	v_lshlrev_b32_e32 v4, 9, v4
	s_lshl_b32 s58, s20, 6
	v_or3_b32 v12, v4, v10, v11
	v_add_u32_e32 v8, s58, v182
	v_mov_b64_e32 v[4:5], s[12:13]
	v_add_u32_e32 v9, s58, v2
	v_mad_i64_i32 v[6:7], s[34:35], v8, s72, v[4:5]
	v_mad_i64_i32 v[4:5], s[34:35], v9, s72, v[4:5]
	v_lshl_add_u64 v[6:7], v[6:7], 0, v[0:1]
	v_lshl_add_u64 v[4:5], v[4:5], 0, v[0:1]
	global_load_dwordx4 v[50:53], v[6:7], off
	global_load_dwordx4 v[54:57], v[4:5], off
	v_mov_b64_e32 v[4:5], s[10:11]
	v_mad_i64_i32 v[6:7], s[34:35], v8, s72, v[4:5]
	v_mad_i64_i32 v[4:5], s[34:35], v9, s72, v[4:5]
	v_and_b32_e32 v176, 31, v174
	v_lshl_add_u64 v[6:7], v[6:7], 0, v[0:1]
	v_lshl_add_u64 v[4:5], v[4:5], 0, v[0:1]
	global_load_dwordx4 v[58:61], v[6:7], off
	global_load_dwordx4 v[62:65], v[4:5], off
	v_or_b32_e32 v4, s60, v176
	v_mul_u32_u24_e32 v4, 0x3400, v4
	v_lshlrev_b32_e32 v4, 1, v4
	v_mov_b32_e32 v5, v1
	v_bfe_u32 v175, v174, 5, 1
	v_lshl_add_u64 v[4:5], s[8:9], 0, v[4:5]
	v_lshl_add_u64 v[4:5], s[74:75], 1, v[4:5]
	v_lshlrev_b32_e32 v170, 4, v175
	v_mov_b32_e32 v171, v1
	v_lshl_add_u64 v[8:9], v[4:5], 0, v[170:171]
	global_load_dwordx4 v[4:7], v[8:9], off
	v_and_b32_e32 v177, 63, v174
	v_lshlrev_b32_e32 v66, 4, v177
	v_add_u32_e32 v180, s62, v66
	v_and_b32_e32 v13, 0x70, v174
	v_or3_b32 v3, v3, v10, v11
	s_sub_i32 s54, s50, s20
	v_add_u32_e32 v186, 0, v3
	v_add_u32_e32 v187, 0, v12
	s_waitcnt vmcnt(0)
	ds_write_b128 v180, v[4:7]
	global_load_dwordx4 v[4:7], v[8:9], off offset:32
	s_waitcnt vmcnt(0)
	ds_write_b128 v180, v[4:7] offset:1024
	global_load_dwordx4 v[4:7], v[8:9], off offset:64
	s_waitcnt vmcnt(0)
	ds_write_b128 v180, v[4:7] offset:2048
	global_load_dwordx4 v[4:7], v[8:9], off offset:96
	s_waitcnt vmcnt(0)
	ds_write_b128 v180, v[4:7] offset:3072
	global_load_dwordx4 v[4:7], v[8:9], off offset:128
	s_waitcnt vmcnt(0)
	ds_write_b128 v180, v[4:7] offset:4096
	global_load_dwordx4 v[4:7], v[8:9], off offset:160
	s_waitcnt vmcnt(0)
	ds_write_b128 v180, v[4:7] offset:5120
	global_load_dwordx4 v[4:7], v[8:9], off offset:192
	s_waitcnt vmcnt(0)
	ds_write_b128 v180, v[4:7] offset:6144
	global_load_dwordx4 v[4:7], v[8:9], off offset:224
	s_waitcnt vmcnt(0)
	ds_write_b128 v180, v[4:7] offset:7168
	v_lshlrev_b32_e32 v4, 8, v182
	s_waitcnt vmcnt(0)
	v_bitop3_b32 v4, v0, v4, v13 bitop3:0xde
	v_add_u32_e32 v185, 0, v4
	ds_write_b128 v185, v[58:61] offset:32768
	ds_write_b128 v185, v[62:65] offset:40960
	s_waitcnt lgkmcnt(0)
	s_barrier
	ds_write_b128 v186, v[50:53]
	ds_write_b128 v187, v[54:57]
	s_cmp_gt_i32 s54, 1
	s_cselect_b64 s[20:21], -1, 0
	s_cmp_lt_i32 s54, 2
	s_cbranch_scc1 .LBB0_409
	s_add_i32 s34, s58, 64
	v_add_u32_e32 v8, s34, v182
	v_mov_b64_e32 v[4:5], s[12:13]
	v_add_u32_e32 v9, s34, v2
	v_mad_i64_i32 v[6:7], s[8:9], v8, s72, v[4:5]
	v_mad_i64_i32 v[2:3], s[8:9], v9, s72, v[4:5]
	v_lshl_add_u64 v[6:7], v[6:7], 0, v[0:1]
	v_lshl_add_u64 v[2:3], v[2:3], 0, v[0:1]
	global_load_dwordx4 v[50:53], v[6:7], off
	global_load_dwordx4 v[54:57], v[2:3], off
	v_mov_b64_e32 v[2:3], s[10:11]
	v_mad_i64_i32 v[4:5], s[8:9], v8, s72, v[2:3]
	v_lshl_add_u64 v[4:5], v[4:5], 0, v[0:1]
	v_mad_i64_i32 v[2:3], s[8:9], v9, s72, v[2:3]
	v_lshl_add_u64 v[2:3], v[2:3], 0, v[0:1]
	global_load_dwordx4 v[58:61], v[4:5], off
	global_load_dwordx4 v[62:65], v[2:3], off

.LBB0_710:
	s_lshl_b32 s21, s31, 11
	s_add_i32 s21, s21, s26
	s_cmp_lt_i32 s21, 0
	v_mov_b32_e32 v196, v35
	v_mov_b32_e32 v0, v35
	s_cselect_b64 s[50:51], -1, 0
	s_cmp_gt_i32 s21, -1
	s_cbranch_scc1 .LBB0_712
	s_add_i32 s34, s21, 0x5a00
	s_mul_hi_i32 s34, s34, 0x2e8ba2e9
	s_lshr_b32 s35, s34, 31
	s_ashr_i32 s34, s34, 13
	s_add_i32 s34, s34, s35
	v_mov_b32_e32 v4, s21
	v_mad_i32_i24 v4, s34, v215, v4
	s_mul_hi_i32 s35, s34, 0xac00000
	s_mul_i32 s34, s34, 0xac00000
	s_add_u32 s52, s14, s34
	v_readfirstlane_b32 s34, v4
	s_addc_u32 s53, s15, s35
	s_ashr_i32 s34, s34, 1
	s_andn2_b32 s34, s34, 31
	v_lshlrev_b32_e32 v3, 1, v0
	s_ashr_i32 s35, s34, 31
	v_and_b32_e32 v2, 16, v0
	v_and_b32_e32 v3, 24, v3
	s_lshl_b64 s[34:35], s[34:35], 14
	v_add_u32_e32 v0, s97, v0
	s_add_u32 s34, s52, s34
	v_and_or_b32 v0, v0, s37, v3
	s_addc_u32 s35, s53, s35
	v_lshl_or_b32 v0, v0, 2, v2
	v_lshl_add_u64 v[164:165], s[34:35], 0, v[0:1]
	v_add_co_u32_e32 v4, vcc, s78, v164
	s_mov_b32 s34, 0x8000
	s_nop 0
	v_addc_co_u32_e32 v5, vcc, 0, v165, vcc
	global_load_dword v2, v[164:165], off
	global_load_dword v3, v[4:5], off
	v_add_co_u32_e32 v4, vcc, s34, v164
	s_mov_b32 s34, 0xc000
	s_nop 0
	v_addc_co_u32_e32 v5, vcc, 0, v165, vcc
	v_add_co_u32_e32 v6, vcc, s34, v164
	s_mov_b32 s34, 0x10000
	s_nop 0
	v_addc_co_u32_e32 v7, vcc, 0, v165, vcc
	global_load_dword v4, v[4:5], off
	s_nop 0
	global_load_dword v5, v[6:7], off
	v_add_co_u32_e32 v6, vcc, s34, v164
	s_mov_b32 s34, 0x14000
	s_nop 0
	v_addc_co_u32_e32 v7, vcc, 0, v165, vcc
	v_add_co_u32_e32 v8, vcc, s34, v164
	s_mov_b32 s34, 0x18000
	s_nop 0
	v_addc_co_u32_e32 v9, vcc, 0, v165, vcc
	global_load_dword v6, v[6:7], off
	s_nop 0
	global_load_dword v7, v[8:9], off
	v_add_co_u32_e32 v8, vcc, s34, v164
	s_mov_b32 s34, 0x1c000
	s_nop 0
	v_addc_co_u32_e32 v9, vcc, 0, v165, vcc
	v_add_co_u32_e32 v10, vcc, s34, v164
	global_load_dword v8, v[8:9], off
	s_nop 0
	v_addc_co_u32_e32 v11, vcc, 0, v165, vcc
	global_load_dword v9, v[10:11], off
	v_add_co_u32_e32 v10, vcc, s68, v164
	s_mov_b32 s34, 0x24000
	s_nop 0
	v_addc_co_u32_e32 v11, vcc, 0, v165, vcc
	v_add_co_u32_e32 v12, vcc, s34, v164
	s_mov_b32 s34, 0x28000
	s_nop 0
	v_addc_co_u32_e32 v13, vcc, 0, v165, vcc
	global_load_dword v10, v[10:11], off
	s_nop 0
	global_load_dword v11, v[12:13], off
	v_add_co_u32_e32 v12, vcc, s34, v164
	s_mov_b32 s34, 0x2c000
	s_nop 0
	v_addc_co_u32_e32 v13, vcc, 0, v165, vcc
	v_add_co_u32_e32 v14, vcc, s34, v164
	s_mov_b32 s34, 0x30000
	s_nop 0
	v_addc_co_u32_e32 v15, vcc, 0, v165, vcc
	global_load_dword v12, v[12:13], off
	s_nop 0
	global_load_dword v13, v[14:15], off
	v_add_co_u32_e32 v14, vcc, s34, v164
	s_mov_b32 s34, 0x34000
	s_nop 0
	v_addc_co_u32_e32 v15, vcc, 0, v165, vcc
	v_add_co_u32_e32 v16, vcc, s34, v164
	s_mov_b32 s34, 0x38000
	s_nop 0
	v_addc_co_u32_e32 v17, vcc, 0, v165, vcc
	global_load_dword v14, v[14:15], off
	s_nop 0
	global_load_dword v15, v[16:17], off
	v_add_co_u32_e32 v16, vcc, s34, v164
	s_mov_b32 s34, 0x3c000
	s_nop 0
	v_addc_co_u32_e32 v17, vcc, 0, v165, vcc
	v_add_co_u32_e32 v18, vcc, s34, v164
	s_mov_b32 s34, 0x40000
	s_nop 0
	v_addc_co_u32_e32 v19, vcc, 0, v165, vcc
	global_load_dword v16, v[16:17], off
	s_nop 0
	global_load_dword v17, v[18:19], off
	v_add_co_u32_e32 v18, vcc, s34, v164
	s_mov_b32 s34, 0x44000
	s_nop 0
	v_addc_co_u32_e32 v19, vcc, 0, v165, vcc
	v_add_co_u32_e32 v20, vcc, s34, v164
	s_mov_b32 s34, 0x48000
	s_nop 0
	v_addc_co_u32_e32 v21, vcc, 0, v165, vcc
	global_load_dword v18, v[18:19], off
	s_nop 0
	global_load_dword v19, v[20:21], off
	v_add_co_u32_e32 v20, vcc, s34, v164
	s_mov_b32 s34, 0x4c000
	s_nop 0
	v_addc_co_u32_e32 v21, vcc, 0, v165, vcc
	v_add_co_u32_e32 v22, vcc, s34, v164
	s_mov_b32 s34, 0x50000
	s_nop 0
	v_addc_co_u32_e32 v23, vcc, 0, v165, vcc
	global_load_dword v20, v[20:21], off
	s_nop 0
	global_load_dword v21, v[22:23], off
	v_add_co_u32_e32 v22, vcc, s34, v164
	s_mov_b32 s34, 0x54000
	s_nop 0
	v_addc_co_u32_e32 v23, vcc, 0, v165, vcc
	v_add_co_u32_e32 v24, vcc, s34, v164
	s_mov_b32 s34, 0x58000
	s_nop 0
	v_addc_co_u32_e32 v25, vcc, 0, v165, vcc
	global_load_dword v22, v[22:23], off
	s_nop 0
	global_load_dword v23, v[24:25], off
	v_add_co_u32_e32 v24, vcc, s34, v164
	s_mov_b32 s34, 0x5c000
	s_nop 0
	v_addc_co_u32_e32 v25, vcc, 0, v165, vcc
	v_add_co_u32_e32 v26, vcc, s34, v164
	s_mov_b32 s34, 0x60000
	s_nop 0
	v_addc_co_u32_e32 v27, vcc, 0, v165, vcc
	global_load_dword v24, v[24:25], off
	s_nop 0
	global_load_dword v25, v[26:27], off
	v_add_co_u32_e32 v26, vcc, s34, v164
	s_mov_b32 s34, 0x64000
	s_nop 0
	v_addc_co_u32_e32 v27, vcc, 0, v165, vcc
	v_add_co_u32_e32 v28, vcc, s34, v164
	s_mov_b32 s34, 0x68000
	s_nop 0
	v_addc_co_u32_e32 v29, vcc, 0, v165, vcc
	global_load_dword v26, v[26:27], off
	s_nop 0
	global_load_dword v27, v[28:29], off
	v_add_co_u32_e32 v28, vcc, s34, v164
	s_mov_b32 s34, 0x6c000
	s_nop 0
	v_addc_co_u32_e32 v29, vcc, 0, v165, vcc
	v_add_co_u32_e32 v30, vcc, s34, v164
	s_mov_b32 s34, 0x70000
	s_nop 0
	v_addc_co_u32_e32 v31, vcc, 0, v165, vcc
	global_load_dword v28, v[28:29], off
	s_nop 0
	global_load_dword v29, v[30:31], off
	v_add_co_u32_e32 v30, vcc, s34, v164
	s_nop 1
	v_addc_co_u32_e32 v31, vcc, 0, v165, vcc
	v_add_co_u32_e32 v32, vcc, 0x74000, v164
	global_load_dword v30, v[30:31], off
	s_nop 0
	v_addc_co_u32_e32 v33, vcc, 0, v165, vcc
	global_load_dword v31, v[32:33], off
	v_add_co_u32_e32 v32, vcc, 0x78000, v164
	s_nop 1
	v_addc_co_u32_e32 v33, vcc, 0, v165, vcc
	v_add_co_u32_e32 v164, vcc, 0x7c000, v164
	global_load_dword v32, v[32:33], off
	s_nop 0
	v_addc_co_u32_e32 v165, vcc, 0, v165, vcc
	global_load_dword v33, v[164:165], off
.LBB0_712:
	s_lshl_b32 s35, s58, 8
	v_ashrrev_i32_e32 v0, 1, v196
	s_or_b32 s35, s35, s77
	v_and_b32_e32 v0, -8, v0
	v_add_u32_e32 v192, s35, v0
	v_ashrrev_i32_e32 v193, 31, v192
	v_lshl_add_u64 v[164:165], v[192:193], 2, s[18:19]
	global_load_dwordx4 v[176:179], v[164:165], off
	global_load_dwordx4 v[172:175], v[164:165], off offset:16
	global_load_dwordx4 v[168:171], v[164:165], off offset:512
	s_nop 0
	global_load_dwordx4 v[164:167], v[164:165], off offset:528
	s_lshl_b32 s34, s48, 8
	s_add_i32 s34, s34, s3
	v_and_or_b32 v200, v196, 15, s34
	v_ashrrev_i32_e32 v201, 31, v200
	v_lshlrev_b64 v[194:195], 12, v[200:201]
	v_lshl_add_u64 v[194:195], s[16:17], 0, v[194:195]
	v_lshlrev_b64 v[198:199], 1, v[192:193]
	v_lshl_add_u64 v[196:197], v[194:195], 0, v[198:199]
	s_mov_b64 s[34:35], 0x80000
	s_waitcnt vmcnt(0) lgkmcnt(0)
	v_pk_mul_f32 v[162:163], v[162:163], v[178:179]
	v_pk_mul_f32 v[160:161], v[160:161], v[176:177]
	v_pk_mul_f32 v[192:193], v[158:159], v[174:175]
	v_pk_mul_f32 v[158:159], v[156:157], v[172:173]
	v_cvt_pk_bf16_f32 v156, v160, v161
	v_cvt_pk_bf16_f32 v157, v162, v163
	v_pk_mul_f32 v[152:153], v[152:153], v[168:169]
	v_cvt_pk_bf16_f32 v158, v158, v159
	v_cvt_pk_bf16_f32 v159, v192, v193
	global_store_dwordx4 v[196:197], v[156:159], off
	v_pk_mul_f32 v[154:155], v[154:155], v[170:171]
	v_pk_mul_f32 v[146:147], v[146:147], v[178:179]
	v_pk_mul_f32 v[156:157], v[150:151], v[166:167]
	v_pk_mul_f32 v[150:151], v[148:149], v[164:165]
	v_cvt_pk_bf16_f32 v148, v152, v153
	v_cvt_pk_bf16_f32 v149, v154, v155
	v_pk_mul_f32 v[144:145], v[144:145], v[176:177]
	v_cvt_pk_bf16_f32 v150, v150, v151
	v_cvt_pk_bf16_f32 v151, v156, v157
	global_store_dwordx4 v[196:197], v[148:151], off offset:256
	v_pk_mul_f32 v[136:137], v[136:137], v[168:169]
	v_pk_mul_f32 v[138:139], v[138:139], v[170:171]
	v_or_b32_e32 v148, 16, v200
	v_ashrrev_i32_e32 v149, 31, v148
	v_lshlrev_b64 v[148:149], 12, v[148:149]
	v_lshl_add_u64 v[148:149], s[16:17], 0, v[148:149]
	v_lshl_add_u64 v[148:149], v[148:149], 0, v[198:199]
	v_pk_mul_f32 v[150:151], v[142:143], v[174:175]
	v_pk_mul_f32 v[142:143], v[140:141], v[172:173]
	v_cvt_pk_bf16_f32 v140, v144, v145
	v_cvt_pk_bf16_f32 v141, v146, v147
	v_pk_mul_f32 v[130:131], v[130:131], v[178:179]
	v_cvt_pk_bf16_f32 v142, v142, v143
	v_cvt_pk_bf16_f32 v143, v150, v151
	global_store_dwordx4 v[148:149], v[140:143], off
	v_pk_mul_f32 v[128:129], v[128:129], v[176:177]
	v_pk_mul_f32 v[120:121], v[120:121], v[168:169]
	v_pk_mul_f32 v[140:141], v[134:135], v[166:167]
	v_pk_mul_f32 v[134:135], v[132:133], v[164:165]
	v_cvt_pk_bf16_f32 v132, v136, v137
	v_cvt_pk_bf16_f32 v133, v138, v139
	v_pk_mul_f32 v[122:123], v[122:123], v[170:171]
	v_cvt_pk_bf16_f32 v134, v134, v135
	v_cvt_pk_bf16_f32 v135, v140, v141
	global_store_dwordx4 v[148:149], v[132:135], off offset:256
	v_pk_mul_f32 v[114:115], v[114:115], v[178:179]
	v_pk_mul_f32 v[112:113], v[112:113], v[176:177]
	v_or_b32_e32 v132, 32, v200
	v_ashrrev_i32_e32 v133, 31, v132
	v_lshlrev_b64 v[132:133], 12, v[132:133]
	v_lshl_add_u64 v[132:133], s[16:17], 0, v[132:133]
	v_lshl_add_u64 v[132:133], v[132:133], 0, v[198:199]
	v_pk_mul_f32 v[134:135], v[126:127], v[174:175]
	v_pk_mul_f32 v[126:127], v[124:125], v[172:173]
	v_cvt_pk_bf16_f32 v124, v128, v129
	v_cvt_pk_bf16_f32 v125, v130, v131
	v_pk_mul_f32 v[106:107], v[106:107], v[170:171]
	v_cvt_pk_bf16_f32 v126, v126, v127
	v_cvt_pk_bf16_f32 v127, v134, v135
	global_store_dwordx4 v[132:133], v[124:127], off
	v_pk_mul_f32 v[104:105], v[104:105], v[168:169]
	v_pk_mul_f32 v[96:97], v[96:97], v[176:177]
	v_pk_mul_f32 v[124:125], v[118:119], v[166:167]
	v_pk_mul_f32 v[118:119], v[116:117], v[164:165]
	v_cvt_pk_bf16_f32 v116, v120, v121
	v_cvt_pk_bf16_f32 v117, v122, v123
	v_pk_mul_f32 v[98:99], v[98:99], v[178:179]
	v_cvt_pk_bf16_f32 v118, v118, v119
	v_cvt_pk_bf16_f32 v119, v124, v125
	global_store_dwordx4 v[132:133], v[116:119], off offset:256
	v_pk_mul_f32 v[90:91], v[90:91], v[170:171]
	v_pk_mul_f32 v[88:89], v[88:89], v[168:169]
	v_or_b32_e32 v116, 48, v200
	v_ashrrev_i32_e32 v117, 31, v116
	v_lshlrev_b64 v[116:117], 12, v[116:117]
	v_lshl_add_u64 v[116:117], s[16:17], 0, v[116:117]
	v_lshl_add_u64 v[116:117], v[116:117], 0, v[198:199]
	v_pk_mul_f32 v[118:119], v[110:111], v[174:175]
	v_pk_mul_f32 v[110:111], v[108:109], v[172:173]
	v_cvt_pk_bf16_f32 v108, v112, v113
	v_cvt_pk_bf16_f32 v109, v114, v115
	v_pk_mul_f32 v[84:85], v[84:85], v[176:177]
	v_cvt_pk_bf16_f32 v110, v110, v111
	v_cvt_pk_bf16_f32 v111, v118, v119
	global_store_dwordx4 v[116:117], v[108:111], off
	v_pk_mul_f32 v[74:75], v[74:75], v[170:171]
	v_pk_mul_f32 v[72:73], v[72:73], v[168:169]
	v_pk_mul_f32 v[108:109], v[102:103], v[166:167]
	v_pk_mul_f32 v[102:103], v[100:101], v[164:165]
	v_cvt_pk_bf16_f32 v100, v104, v105
	v_cvt_pk_bf16_f32 v101, v106, v107
	v_pk_mul_f32 v[68:69], v[68:69], v[176:177]
	v_cvt_pk_bf16_f32 v102, v102, v103
	v_cvt_pk_bf16_f32 v103, v108, v109
	global_store_dwordx4 v[116:117], v[100:103], off offset:256
	v_pk_mul_f32 v[58:59], v[58:59], v[170:171]
	v_pk_mul_f32 v[56:57], v[56:57], v[168:169]
	v_lshl_add_u64 v[100:101], v[196:197], 0, s[34:35]
	s_mov_b32 s34, 0x80000
	v_pk_mul_f32 v[102:103], v[94:95], v[174:175]
	v_pk_mul_f32 v[94:95], v[92:93], v[172:173]
	v_cvt_pk_bf16_f32 v92, v96, v97
	v_add_co_u32_e32 v96, vcc, s34, v196
	v_cvt_pk_bf16_f32 v93, v98, v99
	v_cvt_pk_bf16_f32 v94, v94, v95
	v_cvt_pk_bf16_f32 v95, v102, v103
	s_mov_b64 s[34:35], 0x90000
	s_nop 0
	v_addc_co_u32_e32 v97, vcc, 0, v197, vcc
	global_store_dwordx4 v[96:97], v[92:95], off
	v_pk_mul_f32 v[52:53], v[52:53], v[176:177]
	v_pk_mul_f32 v[42:43], v[42:43], v[170:171]
	v_pk_mul_f32 v[92:93], v[82:83], v[166:167]
	v_pk_mul_f32 v[82:83], v[80:81], v[164:165]
	v_cvt_pk_bf16_f32 v80, v88, v89
	v_cvt_pk_bf16_f32 v81, v90, v91
	v_pk_mul_f32 v[40:41], v[40:41], v[168:169]
	v_cvt_pk_bf16_f32 v82, v82, v83
	v_cvt_pk_bf16_f32 v83, v92, v93
	global_store_dwordx4 v[100:101], v[80:83], off offset:256
	s_nop 1
	v_lshl_add_u64 v[80:81], v[196:197], 0, s[34:35]
	v_pk_mul_f32 v[82:83], v[86:87], v[178:179]
	s_mov_b32 s34, 0x90000
	v_pk_mul_f32 v[86:87], v[78:79], v[174:175]
	v_pk_mul_f32 v[78:79], v[76:77], v[172:173]
	v_cvt_pk_bf16_f32 v76, v84, v85
	v_cvt_pk_bf16_f32 v77, v82, v83
	v_add_co_u32_e32 v82, vcc, s34, v196
	v_cvt_pk_bf16_f32 v78, v78, v79
	v_cvt_pk_bf16_f32 v79, v86, v87
	s_mov_b64 s[34:35], 0xa0000
	s_nop 0
	v_addc_co_u32_e32 v83, vcc, 0, v197, vcc
	global_store_dwordx4 v[82:83], v[76:79], off
	s_nop 1
	v_pk_mul_f32 v[76:77], v[66:67], v[166:167]
	v_pk_mul_f32 v[66:67], v[64:65], v[164:165]
	v_cvt_pk_bf16_f32 v64, v72, v73
	v_cvt_pk_bf16_f32 v65, v74, v75
	s_nop 0
	v_cvt_pk_bf16_f32 v66, v66, v67
	v_cvt_pk_bf16_f32 v67, v76, v77
	global_store_dwordx4 v[80:81], v[64:67], off offset:256
	s_nop 1
	v_lshl_add_u64 v[64:65], v[196:197], 0, s[34:35]
	v_pk_mul_f32 v[66:67], v[70:71], v[178:179]
	s_mov_b32 s34, 0xa0000
	v_pk_mul_f32 v[70:71], v[62:63], v[174:175]
	v_pk_mul_f32 v[62:63], v[60:61], v[172:173]
	v_cvt_pk_bf16_f32 v60, v68, v69
	v_cvt_pk_bf16_f32 v61, v66, v67
	v_add_co_u32_e32 v66, vcc, s34, v196
	v_cvt_pk_bf16_f32 v62, v62, v63
	v_cvt_pk_bf16_f32 v63, v70, v71
	s_mov_b64 s[34:35], 0xb0000
	s_nop 0
	v_addc_co_u32_e32 v67, vcc, 0, v197, vcc
	global_store_dwordx4 v[66:67], v[60:63], off
	s_nop 1
	v_pk_mul_f32 v[60:61], v[50:51], v[166:167]
	v_pk_mul_f32 v[50:51], v[48:49], v[164:165]
	v_cvt_pk_bf16_f32 v48, v56, v57
	v_cvt_pk_bf16_f32 v49, v58, v59
	s_nop 0
	v_cvt_pk_bf16_f32 v50, v50, v51
	v_cvt_pk_bf16_f32 v51, v60, v61
	global_store_dwordx4 v[64:65], v[48:51], off offset:256
	s_nop 1
	v_lshl_add_u64 v[48:49], v[196:197], 0, s[34:35]
	v_pk_mul_f32 v[50:51], v[54:55], v[178:179]
	s_mov_b32 s34, 0xb0000
	v_pk_mul_f32 v[54:55], v[46:47], v[174:175]
	v_pk_mul_f32 v[46:47], v[44:45], v[172:173]
	v_cvt_pk_bf16_f32 v44, v52, v53
	v_cvt_pk_bf16_f32 v45, v50, v51
	v_add_co_u32_e32 v50, vcc, s34, v196
	v_cvt_pk_bf16_f32 v46, v46, v47
	v_cvt_pk_bf16_f32 v47, v54, v55
	s_nop 1
	v_addc_co_u32_e32 v51, vcc, 0, v197, vcc
	global_store_dwordx4 v[50:51], v[44:47], off
	s_andn2_b64 vcc, exec, s[50:51]
	s_nop 0
	v_pk_mul_f32 v[44:45], v[38:39], v[166:167]
	v_pk_mul_f32 v[38:39], v[36:37], v[164:165]
	v_cvt_pk_bf16_f32 v36, v40, v41
	v_cvt_pk_bf16_f32 v37, v42, v43
	s_nop 0
	v_cvt_pk_bf16_f32 v38, v38, v39
	v_cvt_pk_bf16_f32 v39, v44, v45
	global_store_dwordx4 v[48:49], v[36:39], off offset:256
	s_nop 1
	v_mov_b32_e32 v36, v35
	s_cbranch_vccnz .LBB0_714
	s_add_i32 s34, s21, 0x5a00
	s_mul_hi_i32 s34, s34, 0x2e8ba2e9
	s_lshr_b32 s35, s34, 31
	s_ashr_i32 s34, s34, 13
	s_add_i32 s34, s34, s35
	v_mov_b32_e32 v38, s21
	v_mad_i32_i24 v38, s34, v215, v38
	s_mul_hi_i32 s21, s34, 0x11200000
	s_mul_i32 s34, s34, 0x11200000
	s_add_u32 s34, s12, s34
	s_addc_u32 s21, s13, s21
	v_readlane_b32 s35, v255, 2
	s_add_u32 s48, s34, s35
	v_readfirstlane_b32 s34, v38
	s_addc_u32 s21, s21, 0
	s_ashr_i32 s34, s34, 7
	s_ashr_i32 s35, s34, 31
	s_lshl_b64 s[34:35], s[34:35], 15
	s_add_u32 s34, s48, s34
	s_addc_u32 s35, s21, s35
	v_readlane_b32 s21, v254, 33
	v_lshlrev_b32_e32 v0, 2, v36
	v_lshlrev_b32_e32 v37, 6, v36
	v_add_u32_e32 v36, s21, v36
	v_lshlrev_b32_e32 v38, 7, v36
	v_lshrrev_b32_e32 v36, 3, v36
	v_readlane_b32 s21, v254, 30
	v_and_b32_e32 v37, 0x3c0, v37
	v_and_b32_e32 v38, 0xffffc000, v38
	v_and_or_b32 v36, v36, 14, s21
	v_lshlrev_b32_e32 v36, 10, v36
	v_or3_b32 v42, v36, v38, v37
	v_mov_b32_e32 v43, v1
	v_lshl_add_u64 v[42:43], s[34:35], 0, v[42:43]
	s_mov_b64 s[34:35], 0xb800000
	v_and_b32_e32 v40, 32, v0
	v_mov_b32_e32 v41, v1
	v_lshl_add_u64 v[42:43], v[42:43], 0, s[34:35]
	v_bitop3_b32 v0, v0, 32, v0 bitop3:0xc
	v_cvt_pk_bf16_f32 v36, v2, v3
	v_cvt_pk_bf16_f32 v37, v4, v5
	v_cvt_pk_bf16_f32 v38, v6, v7
	v_cvt_pk_bf16_f32 v39, v8, v9
	v_lshl_add_u64 v[44:45], v[42:43], 0, v[40:41]
	global_store_dwordx4 v[44:45], v[36:39], off
	s_nop 1
	v_cvt_pk_bf16_f32 v36, v10, v11
	v_cvt_pk_bf16_f32 v37, v12, v13
	v_cvt_pk_bf16_f32 v38, v14, v15
	v_cvt_pk_bf16_f32 v39, v16, v17
	global_store_dwordx4 v[44:45], v[36:39], off offset:16
	v_lshl_add_u64 v[44:45], v[42:43], 0, v[0:1]
	v_xor_b32_e32 v0, 32, v40
	v_cvt_pk_bf16_f32 v36, v18, v19
	v_cvt_pk_bf16_f32 v37, v20, v21
	v_cvt_pk_bf16_f32 v38, v22, v23
	v_cvt_pk_bf16_f32 v39, v24, v25
	v_lshl_add_u64 v[40:41], v[42:43], 0, v[0:1]
	global_store_dwordx4 v[44:45], v[36:39], off
	s_nop 1
	v_cvt_pk_bf16_f32 v36, v26, v27
	v_cvt_pk_bf16_f32 v37, v28, v29
	v_cvt_pk_bf16_f32 v38, v30, v31
	v_cvt_pk_bf16_f32 v39, v32, v33
	global_store_dwordx4 v[40:41], v[36:39], off offset:16

.LBB0_791:
	s_lshl_b32 s15, s31, 11
	s_add_i32 s15, s15, s26
	s_cmp_lt_i32 s15, 0
	s_cselect_b64 s[48:49], -1, 0
	v_mov_b32_e32 v136, v35
	v_mov_b32_e32 v0, v35
	s_and_b64 vcc, exec, s[48:49]
	s_mov_b32 s37, 0x3fffffe3
	s_cbranch_vccz .LBB0_793
	s_add_i32 s34, s15, 0x5a00
	s_mul_hi_i32 s34, s34, 0x2e8ba2e9
	s_lshr_b32 s35, s34, 31
	s_ashr_i32 s34, s34, 13
	s_add_i32 s34, s34, s35
	v_mov_b32_e32 v137, s15
	v_mad_i32_i24 v137, s34, v215, v137
	s_mul_hi_i32 s35, s34, 0xac00000
	s_mul_i32 s34, s34, 0xac00000
	s_add_u32 s51, s16, s34
	v_readfirstlane_b32 s34, v137
	s_addc_u32 s52, s17, s35
	s_ashr_i32 s34, s34, 1
	s_andn2_b32 s34, s34, 31
	v_lshlrev_b32_e32 v3, 1, v0
	s_ashr_i32 s35, s34, 31
	v_and_b32_e32 v2, 16, v0
	v_and_b32_e32 v3, 24, v3
	s_lshl_b64 s[34:35], s[34:35], 14
	v_add_u32_e32 v0, s97, v0
	s_add_u32 s34, s51, s34
	v_and_or_b32 v0, v0, s37, v3
	s_addc_u32 s35, s52, s35
	v_lshl_or_b32 v0, v0, 2, v2
	v_lshl_add_u64 v[2:3], s[34:35], 0, v[0:1]
	v_add_co_u32_e32 v138, vcc, s78, v2
	s_mov_b32 s34, 0x8000
	s_nop 0
	v_addc_co_u32_e32 v139, vcc, 0, v3, vcc
	s_waitcnt vmcnt(0)
	global_load_dword v200, v[2:3], off
	global_load_dword v201, v[138:139], off
	v_add_co_u32_e32 v138, vcc, s34, v2
	s_mov_b32 s34, 0xc000
	s_nop 0
	v_addc_co_u32_e32 v139, vcc, 0, v3, vcc
	global_load_dword v202, v[138:139], off
	v_add_co_u32_e32 v138, vcc, s34, v2
	s_mov_b32 s34, 0x10000
	s_nop 0
	v_addc_co_u32_e32 v139, vcc, 0, v3, vcc
	global_load_dword v203, v[138:139], off
	v_add_co_u32_e32 v138, vcc, s34, v2
	s_mov_b32 s34, 0x14000
	s_nop 0
	v_addc_co_u32_e32 v139, vcc, 0, v3, vcc
	global_load_dword v204, v[138:139], off
	v_add_co_u32_e32 v138, vcc, s34, v2
	s_mov_b32 s34, 0x18000
	s_nop 0
	v_addc_co_u32_e32 v139, vcc, 0, v3, vcc
	global_load_dword v205, v[138:139], off
	v_add_co_u32_e32 v138, vcc, s34, v2
	s_mov_b32 s34, 0x1c000
	s_nop 0
	v_addc_co_u32_e32 v139, vcc, 0, v3, vcc
	global_load_dword v206, v[138:139], off
	v_add_co_u32_e32 v138, vcc, s34, v2
	s_mov_b32 s34, 0x24000
	s_nop 0
	v_addc_co_u32_e32 v139, vcc, 0, v3, vcc
	global_load_dword v207, v[138:139], off
	v_add_co_u32_e32 v138, vcc, s94, v2
	s_nop 1
	v_addc_co_u32_e32 v139, vcc, 0, v3, vcc
	global_load_dword v216, v[138:139], off
	v_add_co_u32_e32 v138, vcc, s34, v2
	s_mov_b32 s34, 0x28000
	s_nop 0
	v_addc_co_u32_e32 v139, vcc, 0, v3, vcc
	global_load_dword v217, v[138:139], off
	v_add_co_u32_e32 v138, vcc, s34, v2
	s_mov_b32 s34, 0x2c000
	s_nop 0
	v_addc_co_u32_e32 v139, vcc, 0, v3, vcc
	global_load_dword v218, v[138:139], off
	v_add_co_u32_e32 v138, vcc, s34, v2
	s_mov_b32 s34, 0x30000
	s_nop 0
	v_addc_co_u32_e32 v139, vcc, 0, v3, vcc
	global_load_dword v219, v[138:139], off
	v_add_co_u32_e32 v138, vcc, s34, v2
	s_mov_b32 s34, 0x34000
	s_nop 0
	v_addc_co_u32_e32 v139, vcc, 0, v3, vcc
	global_load_dword v220, v[138:139], off
	v_add_co_u32_e32 v138, vcc, s34, v2
	s_mov_b32 s34, 0x38000
	s_nop 0
	v_addc_co_u32_e32 v139, vcc, 0, v3, vcc
	global_load_dword v221, v[138:139], off
	v_add_co_u32_e32 v138, vcc, s34, v2
	s_mov_b32 s34, 0x3c000
	s_nop 0
	v_addc_co_u32_e32 v139, vcc, 0, v3, vcc
	global_load_dword v222, v[138:139], off
	v_add_co_u32_e32 v138, vcc, s34, v2
	s_mov_b32 s34, 0x40000
	s_nop 0
	v_addc_co_u32_e32 v139, vcc, 0, v3, vcc
	global_load_dword v223, v[138:139], off
	v_add_co_u32_e32 v138, vcc, s34, v2
	s_mov_b32 s34, 0x44000
	s_nop 0
	v_addc_co_u32_e32 v139, vcc, 0, v3, vcc
	global_load_dword v224, v[138:139], off
	v_add_co_u32_e32 v138, vcc, s34, v2
	s_mov_b32 s34, 0x48000
	s_nop 0
	v_addc_co_u32_e32 v139, vcc, 0, v3, vcc
	global_load_dword v225, v[138:139], off
	v_add_co_u32_e32 v138, vcc, s34, v2
	s_mov_b32 s34, 0x4c000
	s_nop 0
	v_addc_co_u32_e32 v139, vcc, 0, v3, vcc
	global_load_dword v226, v[138:139], off
	v_add_co_u32_e32 v138, vcc, s34, v2
	s_mov_b32 s34, 0x50000
	s_nop 0
	v_addc_co_u32_e32 v139, vcc, 0, v3, vcc
	global_load_dword v227, v[138:139], off
	v_add_co_u32_e32 v138, vcc, s34, v2
	s_mov_b32 s34, 0x54000
	s_nop 0
	v_addc_co_u32_e32 v139, vcc, 0, v3, vcc
	global_load_dword v228, v[138:139], off
	v_add_co_u32_e32 v138, vcc, s34, v2
	s_mov_b32 s34, 0x58000
	s_nop 0
	v_addc_co_u32_e32 v139, vcc, 0, v3, vcc
	global_load_dword v229, v[138:139], off
	v_add_co_u32_e32 v138, vcc, s34, v2
	s_mov_b32 s34, 0x5c000
	s_nop 0
	v_addc_co_u32_e32 v139, vcc, 0, v3, vcc
	global_load_dword v230, v[138:139], off
	v_add_co_u32_e32 v138, vcc, s34, v2
	s_mov_b32 s34, 0x60000
	s_nop 0
	v_addc_co_u32_e32 v139, vcc, 0, v3, vcc
	global_load_dword v231, v[138:139], off
	v_add_co_u32_e32 v138, vcc, s34, v2
	s_mov_b32 s34, 0x64000
	s_nop 0
	v_addc_co_u32_e32 v139, vcc, 0, v3, vcc
	global_load_dword v232, v[138:139], off
	v_add_co_u32_e32 v138, vcc, s34, v2
	s_mov_b32 s34, 0x68000
	s_nop 0
	v_addc_co_u32_e32 v139, vcc, 0, v3, vcc
	global_load_dword v233, v[138:139], off
	v_add_co_u32_e32 v138, vcc, s34, v2
	s_mov_b32 s34, 0x6c000
	s_nop 0
	v_addc_co_u32_e32 v139, vcc, 0, v3, vcc
	global_load_dword v234, v[138:139], off
	v_add_co_u32_e32 v138, vcc, s34, v2
	s_nop 1
	v_addc_co_u32_e32 v139, vcc, 0, v3, vcc
	global_load_dword v235, v[138:139], off
	v_add_co_u32_e32 v138, vcc, 0x70000, v2
	s_nop 1
	v_addc_co_u32_e32 v139, vcc, 0, v3, vcc
	global_load_dword v236, v[138:139], off
	v_add_co_u32_e32 v138, vcc, 0x74000, v2
	s_nop 1
	v_addc_co_u32_e32 v139, vcc, 0, v3, vcc
	global_load_dword v237, v[138:139], off
	v_add_co_u32_e32 v138, vcc, 0x78000, v2
	s_nop 1
	v_addc_co_u32_e32 v139, vcc, 0, v3, vcc
	v_add_co_u32_e32 v2, vcc, 0x7c000, v2
	global_load_dword v238, v[138:139], off
	s_nop 0
	v_addc_co_u32_e32 v3, vcc, 0, v3, vcc
	global_load_dword v239, v[2:3], off

.LBB0_880:
	s_lshl_b32 s28, s31, 11
	s_add_i32 s28, s28, s26
	s_cmp_lt_i32 s28, 0
	s_cselect_b64 s[60:61], -1, 0
	v_mov_b32_e32 v134, v35
	v_mov_b32_e32 v0, v35
	s_and_b64 vcc, exec, s[60:61]
	s_cbranch_vccz .LBB0_882
	s_add_i32 s13, s28, 0x5a00
	s_mul_hi_i32 s13, s13, 0x2e8ba2e9
	s_lshr_b32 s34, s13, 31
	s_ashr_i32 s13, s13, 13
	s_add_i32 s13, s13, s34
	v_mov_b32_e32 v135, s28
	v_mad_i32_i24 v135, s13, v215, v135
	s_mul_hi_i32 s34, s13, 0xac00000
	s_mul_i32 s13, s13, 0xac00000
	s_add_u32 s13, s18, s13
	s_addc_u32 s49, s19, s34
	v_readfirstlane_b32 s34, v135
	s_ashr_i32 s34, s34, 1
	s_andn2_b32 s34, s34, 31
	v_lshlrev_b32_e32 v133, 1, v0
	s_ashr_i32 s35, s34, 31
	v_and_b32_e32 v132, 16, v0
	v_and_b32_e32 v133, 24, v133
	s_lshl_b64 s[34:35], s[34:35], 14
	v_add_u32_e32 v0, s97, v0
	s_add_u32 s34, s13, s34
	v_and_or_b32 v0, v0, s37, v133
	s_addc_u32 s35, s49, s35
	v_lshl_or_b32 v0, v0, 2, v132
	v_lshl_add_u64 v[132:133], s[34:35], 0, v[0:1]
	v_add_co_u32_e32 v136, vcc, s78, v132
	s_mov_b32 s13, 0x8000
	s_nop 0
	v_addc_co_u32_e32 v137, vcc, 0, v133, vcc
	s_waitcnt vmcnt(0)
	global_load_dword v190, v[132:133], off
	global_load_dword v191, v[136:137], off
	v_add_co_u32_e32 v136, vcc, s13, v132
	s_mov_b32 s13, 0xc000
	s_nop 0
	v_addc_co_u32_e32 v137, vcc, 0, v133, vcc
	global_load_dword v196, v[136:137], off
	v_add_co_u32_e32 v136, vcc, s13, v132
	s_mov_b32 s13, 0x10000
	s_nop 0
	v_addc_co_u32_e32 v137, vcc, 0, v133, vcc
	global_load_dword v197, v[136:137], off
	v_add_co_u32_e32 v136, vcc, s13, v132
	s_mov_b32 s13, 0x14000
	s_nop 0
	v_addc_co_u32_e32 v137, vcc, 0, v133, vcc
	global_load_dword v198, v[136:137], off
	v_add_co_u32_e32 v136, vcc, s13, v132
	s_mov_b32 s13, 0x18000
	s_nop 0
	v_addc_co_u32_e32 v137, vcc, 0, v133, vcc
	global_load_dword v199, v[136:137], off
	v_add_co_u32_e32 v136, vcc, s13, v132
	s_mov_b32 s13, 0x1c000
	s_nop 0
	v_addc_co_u32_e32 v137, vcc, 0, v133, vcc
	global_load_dword v200, v[136:137], off
	v_add_co_u32_e32 v136, vcc, s13, v132
	s_mov_b32 s13, 0x24000
	s_nop 0
	v_addc_co_u32_e32 v137, vcc, 0, v133, vcc
	global_load_dword v201, v[136:137], off
	v_add_co_u32_e32 v136, vcc, s77, v132
	s_nop 1
	v_addc_co_u32_e32 v137, vcc, 0, v133, vcc
	global_load_dword v202, v[136:137], off
	v_add_co_u32_e32 v136, vcc, s13, v132
	s_mov_b32 s13, 0x28000
	s_nop 0
	v_addc_co_u32_e32 v137, vcc, 0, v133, vcc
	global_load_dword v203, v[136:137], off
	v_add_co_u32_e32 v136, vcc, s13, v132
	s_mov_b32 s13, 0x2c000
	s_nop 0
	v_addc_co_u32_e32 v137, vcc, 0, v133, vcc
	global_load_dword v204, v[136:137], off
	v_add_co_u32_e32 v136, vcc, s13, v132
	s_mov_b32 s13, 0x30000
	s_nop 0
	v_addc_co_u32_e32 v137, vcc, 0, v133, vcc
	global_load_dword v205, v[136:137], off
	v_add_co_u32_e32 v136, vcc, s13, v132
	s_mov_b32 s13, 0x34000
	s_nop 0
	v_addc_co_u32_e32 v137, vcc, 0, v133, vcc
	global_load_dword v206, v[136:137], off
	v_add_co_u32_e32 v136, vcc, s13, v132
	s_mov_b32 s13, 0x38000
	s_nop 0
	v_addc_co_u32_e32 v137, vcc, 0, v133, vcc
	global_load_dword v207, v[136:137], off
	v_add_co_u32_e32 v136, vcc, s13, v132
	s_mov_b32 s13, 0x3c000
	s_nop 0
	v_addc_co_u32_e32 v137, vcc, 0, v133, vcc
	global_load_dword v216, v[136:137], off
	v_add_co_u32_e32 v136, vcc, s13, v132
	s_mov_b32 s13, 0x40000
	s_nop 0
	v_addc_co_u32_e32 v137, vcc, 0, v133, vcc
	global_load_dword v217, v[136:137], off
	v_add_co_u32_e32 v136, vcc, s13, v132
	s_mov_b32 s13, 0x44000
	s_nop 0
	v_addc_co_u32_e32 v137, vcc, 0, v133, vcc
	global_load_dword v218, v[136:137], off
	v_add_co_u32_e32 v136, vcc, s13, v132
	s_mov_b32 s13, 0x48000
	s_nop 0
	v_addc_co_u32_e32 v137, vcc, 0, v133, vcc
	global_load_dword v219, v[136:137], off
	v_add_co_u32_e32 v136, vcc, s13, v132
	s_mov_b32 s13, 0x4c000
	s_nop 0
	v_addc_co_u32_e32 v137, vcc, 0, v133, vcc
	global_load_dword v220, v[136:137], off
	v_add_co_u32_e32 v136, vcc, s13, v132
	s_mov_b32 s13, 0x50000
	s_nop 0
	v_addc_co_u32_e32 v137, vcc, 0, v133, vcc
	global_load_dword v221, v[136:137], off
	v_add_co_u32_e32 v136, vcc, s13, v132
	s_mov_b32 s13, 0x54000
	s_nop 0
	v_addc_co_u32_e32 v137, vcc, 0, v133, vcc
	global_load_dword v222, v[136:137], off
	v_add_co_u32_e32 v136, vcc, s13, v132
	s_mov_b32 s13, 0x58000
	s_nop 0
	v_addc_co_u32_e32 v137, vcc, 0, v133, vcc
	global_load_dword v223, v[136:137], off
	v_add_co_u32_e32 v136, vcc, s13, v132
	s_mov_b32 s13, 0x5c000
	s_nop 0
	v_addc_co_u32_e32 v137, vcc, 0, v133, vcc
	global_load_dword v224, v[136:137], off
	v_add_co_u32_e32 v136, vcc, s13, v132
	s_mov_b32 s13, 0x60000
	s_nop 0
	v_addc_co_u32_e32 v137, vcc, 0, v133, vcc
	global_load_dword v225, v[136:137], off
	v_add_co_u32_e32 v136, vcc, s13, v132
	s_mov_b32 s13, 0x64000
	s_nop 0
	v_addc_co_u32_e32 v137, vcc, 0, v133, vcc
	global_load_dword v226, v[136:137], off
	v_add_co_u32_e32 v136, vcc, s13, v132
	s_mov_b32 s13, 0x68000
	s_nop 0
	v_addc_co_u32_e32 v137, vcc, 0, v133, vcc
	global_load_dword v227, v[136:137], off
	v_add_co_u32_e32 v136, vcc, s13, v132
	s_mov_b32 s13, 0x6c000
	s_nop 0
	v_addc_co_u32_e32 v137, vcc, 0, v133, vcc
	global_load_dword v228, v[136:137], off
	v_add_co_u32_e32 v136, vcc, s13, v132
	s_nop 1
	v_addc_co_u32_e32 v137, vcc, 0, v133, vcc
	global_load_dword v229, v[136:137], off
	v_add_co_u32_e32 v136, vcc, 0x70000, v132
	s_nop 1
	v_addc_co_u32_e32 v137, vcc, 0, v133, vcc
	global_load_dword v230, v[136:137], off
	v_add_co_u32_e32 v136, vcc, 0x74000, v132
	s_nop 1
	v_addc_co_u32_e32 v137, vcc, 0, v133, vcc
	global_load_dword v231, v[136:137], off
	v_add_co_u32_e32 v136, vcc, 0x78000, v132
	s_nop 1
	v_addc_co_u32_e32 v137, vcc, 0, v133, vcc
	v_add_co_u32_e32 v132, vcc, 0x7c000, v132
	global_load_dword v232, v[136:137], off
	s_nop 0
	v_addc_co_u32_e32 v133, vcc, 0, v133, vcc
	global_load_dword v233, v[132:133], off
.LBB0_882:
	s_lshl_b32 s12, s12, 8
	s_add_i32 s12, s12, s3
	v_and_or_b32 v170, v134, 15, s12
	s_lshl_b32 s12, s54, 8
	v_ashrrev_i32_e32 v0, 1, v134
	s_or_b32 s12, s12, s1
	v_and_b32_e32 v0, -8, v0
	v_add_u32_e32 v168, s12, v0
	s_lshl_b32 s12, s54, 2
	v_ashrrev_i32_e32 v171, 31, v170
	s_or_b32 s62, s12, s83
	v_lshlrev_b64 v[148:149], 13, v[170:171]
	v_ashrrev_i32_e32 v169, 31, v168
	v_cmp_gt_u32_e64 s[12:13], 16, v134
	s_ashr_i32 s63, s62, 31
	s_and_b64 vcc, exec, s[42:43]
	v_or_b32_e32 v172, 16, v170
	v_lshl_add_u64 v[174:175], s[14:15], 0, v[148:149]
	s_cbranch_vccz .LBB0_900
	v_lshl_add_u64 v[150:151], v[168:169], 2, s[20:21]
	v_lshlrev_b64 v[132:133], 14, v[170:171]
	v_lshl_add_u64 v[132:133], v[150:151], 0, v[132:133]
	global_load_dwordx4 v[152:155], v[132:133], off
	global_load_dwordx4 v[176:179], v[132:133], off offset:16
	global_load_dwordx4 v[180:183], v[132:133], off offset:512
	global_load_dwordx4 v[184:187], v[132:133], off offset:528
	v_ashrrev_i32_e32 v173, 31, v172
	v_lshlrev_b64 v[132:133], 14, v[172:173]
	v_lshl_add_u64 v[132:133], v[150:151], 0, v[132:133]
	global_load_dwordx4 v[144:147], v[132:133], off
	global_load_dwordx4 v[140:143], v[132:133], off offset:16
	global_load_dwordx4 v[136:139], v[132:133], off offset:512
	s_nop 0
	global_load_dwordx4 v[132:135], v[132:133], off offset:528
	s_waitcnt vmcnt(0) lgkmcnt(0)
	v_pk_add_f32 v[154:155], v[130:131], v[154:155]
	v_pk_add_f32 v[152:153], v[128:129], v[152:153]
	v_mul_f32_e32 v192, v155, v155
	v_mul_f32_e32 v0, v153, v153
	v_pk_add_f32 v[176:177], v[124:125], v[176:177]
	v_fmac_f32_e32 v0, v152, v152
	v_fmac_f32_e32 v192, v154, v154
	v_add_f32_e32 v0, v0, v192
	v_mul_f32_e32 v192, v177, v177
	v_pk_add_f32 v[178:179], v[126:127], v[178:179]
	v_fmac_f32_e32 v192, v176, v176
	v_cvt_pk_bf16_f32 v152, v152, v153
	v_cvt_pk_bf16_f32 v153, v154, v155
	v_cvt_pk_bf16_f32 v154, v176, v177
	v_cvt_pk_bf16_f32 v155, v178, v179
	v_lshl_add_u64 v[176:177], v[168:169], 1, v[174:175]
	global_store_dwordx4 v[176:177], v[152:155], off
	v_add_f32_e32 v0, v0, v192
	v_mul_f32_e32 v192, v179, v179
	v_pk_add_f32 v[154:155], v[122:123], v[182:183]
	v_pk_add_f32 v[152:153], v[120:121], v[180:181]
	v_mul_f32_e32 v183, v155, v155
	v_mul_f32_e32 v182, v153, v153
	v_pk_add_f32 v[180:181], v[116:117], v[184:185]
	v_fmac_f32_e32 v182, v152, v152
	v_fmac_f32_e32 v183, v154, v154
	v_add_f32_e32 v182, v182, v183
	v_mul_f32_e32 v183, v181, v181
	v_fmac_f32_e32 v192, v178, v178
	v_pk_add_f32 v[178:179], v[118:119], v[186:187]
	v_fmac_f32_e32 v183, v180, v180
	v_add_f32_e32 v182, v182, v183
	v_mul_f32_e32 v183, v179, v179
	v_fmac_f32_e32 v183, v178, v178
	v_add_f32_e32 v0, v192, v0
	v_add_f32_e32 v182, v183, v182
	v_add_f32_e32 v0, v0, v182
	v_cvt_pk_bf16_f32 v152, v152, v153
	v_cvt_pk_bf16_f32 v153, v154, v155
	v_cvt_pk_bf16_f32 v154, v180, v181
	v_cvt_pk_bf16_f32 v155, v178, v179
	global_store_dwordx4 v[176:177], v[152:155], off offset:256
	ds_swizzle_b32 v152, v0 offset:swizzle(SWAP,16)
	s_waitcnt lgkmcnt(0)
	v_add_f32_e32 v0, v0, v152
	v_mov_b32_e32 v152, v0
	s_nop 1
	v_permlane32_swap_b32_e32 v0, v152
	s_and_saveexec_b64 s[58:59], s[12:13]
	s_cbranch_execz .LBB0_885
	v_lshlrev_b64 v[154:155], 8, v[170:171]
	v_lshl_add_u64 v[154:155], s[22:23], 0, v[154:155]
	v_lshl_add_u64 v[154:155], s[62:63], 2, v[154:155]
	v_add_f32_e32 v0, v0, v152
	global_store_dword v[154:155], v0, off

.LBB0_887:
	s_or_b64 exec, exec, s[58:59]
	v_or_b32_e32 v154, 32, v170
	v_ashrrev_i32_e32 v155, 31, v154
	v_lshlrev_b64 v[132:133], 14, v[154:155]
	v_lshl_add_u64 v[132:133], v[150:151], 0, v[132:133]
	global_load_dwordx4 v[176:179], v[132:133], off
	global_load_dwordx4 v[180:183], v[132:133], off offset:16
	global_load_dwordx4 v[184:187], v[132:133], off offset:512
	global_load_dwordx4 v[192:195], v[132:133], off offset:528
	v_or_b32_e32 v152, 48, v170
	v_ashrrev_i32_e32 v153, 31, v152
	v_lshlrev_b64 v[132:133], 14, v[152:153]
	v_lshl_add_u64 v[132:133], v[150:151], 0, v[132:133]
	global_load_dwordx4 v[144:147], v[132:133], off
	global_load_dwordx4 v[140:143], v[132:133], off offset:16
	global_load_dwordx4 v[136:139], v[132:133], off offset:512
	s_nop 0
	global_load_dwordx4 v[132:135], v[132:133], off offset:528
	s_waitcnt vmcnt(0) lgkmcnt(0)
	v_pk_add_f32 v[178:179], v[98:99], v[178:179]
	v_pk_add_f32 v[176:177], v[96:97], v[176:177]
	v_mul_f32_e32 v173, v179, v179
	v_mul_f32_e32 v0, v177, v177
	v_pk_add_f32 v[180:181], v[92:93], v[180:181]
	v_fmac_f32_e32 v0, v176, v176
	v_fmac_f32_e32 v173, v178, v178
	v_add_f32_e32 v0, v0, v173
	v_mul_f32_e32 v173, v181, v181
	v_fmac_f32_e32 v173, v180, v180
	v_cvt_pk_bf16_f32 v176, v176, v177
	v_cvt_pk_bf16_f32 v177, v178, v179
	v_cvt_pk_bf16_f32 v178, v180, v181
	v_lshlrev_b64 v[180:181], 13, v[154:155]
	v_pk_add_f32 v[182:183], v[94:95], v[182:183]
	v_lshl_add_u64 v[180:181], s[14:15], 0, v[180:181]
	v_add_f32_e32 v0, v0, v173
	v_mul_f32_e32 v173, v183, v183
	v_cvt_pk_bf16_f32 v179, v182, v183
	v_lshl_add_u64 v[180:181], v[168:169], 1, v[180:181]
	v_fmac_f32_e32 v173, v182, v182
	global_store_dwordx4 v[180:181], v[176:179], off
	v_add_f32_e32 v0, v173, v0
	v_pk_add_f32 v[182:183], v[86:87], v[194:195]
	v_pk_add_f32 v[178:179], v[90:91], v[186:187]
	v_pk_add_f32 v[176:177], v[88:89], v[184:185]
	v_mul_f32_e32 v186, v179, v179
	v_mul_f32_e32 v173, v177, v177
	v_pk_add_f32 v[184:185], v[84:85], v[192:193]
	v_fmac_f32_e32 v173, v176, v176
	v_fmac_f32_e32 v186, v178, v178
	v_add_f32_e32 v173, v173, v186
	v_mul_f32_e32 v186, v185, v185
	v_fmac_f32_e32 v186, v184, v184
	v_add_f32_e32 v173, v173, v186
	v_mul_f32_e32 v186, v183, v183
	v_fmac_f32_e32 v186, v182, v182
	v_add_f32_e32 v173, v186, v173
	v_add_f32_e32 v0, v0, v173
	ds_swizzle_b32 v173, v0 offset:swizzle(SWAP,16)
	v_cvt_pk_bf16_f32 v176, v176, v177
	v_cvt_pk_bf16_f32 v177, v178, v179
	v_cvt_pk_bf16_f32 v178, v184, v185
	v_cvt_pk_bf16_f32 v179, v182, v183
	s_waitcnt lgkmcnt(0)
	v_add_f32_e32 v0, v0, v173
	v_mov_b32_e32 v173, v0
	s_nop 1
	v_permlane32_swap_b32_e32 v0, v173
	global_store_dwordx4 v[180:181], v[176:179], off offset:256
	s_and_saveexec_b64 s[58:59], s[12:13]
	s_cbranch_execz .LBB0_889
	v_lshlrev_b64 v[154:155], 8, v[154:155]
	v_lshl_add_u64 v[154:155], s[22:23], 0, v[154:155]
	v_lshl_add_u64 v[154:155], s[62:63], 2, v[154:155]
	v_add_f32_e32 v0, v0, v173
	global_store_dword v[154:155], v0, off

.LBB0_891:
	s_or_b64 exec, exec, s[58:59]
	v_add_u32_e32 v154, 0x80, v170
	v_ashrrev_i32_e32 v155, 31, v154
	v_lshlrev_b64 v[132:133], 14, v[154:155]
	v_lshl_add_u64 v[132:133], v[150:151], 0, v[132:133]
	global_load_dwordx4 v[176:179], v[132:133], off
	global_load_dwordx4 v[180:183], v[132:133], off offset:16
	global_load_dwordx4 v[184:187], v[132:133], off offset:512
	global_load_dwordx4 v[192:195], v[132:133], off offset:528
	v_add_u32_e32 v152, 0x90, v170
	v_ashrrev_i32_e32 v153, 31, v152
	v_lshlrev_b64 v[132:133], 14, v[152:153]
	v_lshl_add_u64 v[132:133], v[150:151], 0, v[132:133]
	global_load_dwordx4 v[144:147], v[132:133], off
	global_load_dwordx4 v[140:143], v[132:133], off offset:16
	global_load_dwordx4 v[136:139], v[132:133], off offset:512
	s_nop 0
	global_load_dwordx4 v[132:135], v[132:133], off offset:528
	s_waitcnt vmcnt(0) lgkmcnt(0)
	v_pk_add_f32 v[178:179], v[66:67], v[178:179]
	v_pk_add_f32 v[176:177], v[64:65], v[176:177]
	v_mul_f32_e32 v173, v179, v179
	v_mul_f32_e32 v0, v177, v177
	v_pk_add_f32 v[180:181], v[60:61], v[180:181]
	v_fmac_f32_e32 v0, v176, v176
	v_fmac_f32_e32 v173, v178, v178
	v_add_f32_e32 v0, v0, v173
	v_mul_f32_e32 v173, v181, v181
	v_fmac_f32_e32 v173, v180, v180
	v_cvt_pk_bf16_f32 v176, v176, v177
	v_cvt_pk_bf16_f32 v177, v178, v179
	v_cvt_pk_bf16_f32 v178, v180, v181
	v_lshlrev_b64 v[180:181], 13, v[154:155]
	v_pk_add_f32 v[182:183], v[62:63], v[182:183]
	v_lshl_add_u64 v[180:181], s[14:15], 0, v[180:181]
	v_add_f32_e32 v0, v0, v173
	v_mul_f32_e32 v173, v183, v183
	v_cvt_pk_bf16_f32 v179, v182, v183
	v_lshl_add_u64 v[180:181], v[168:169], 1, v[180:181]
	v_fmac_f32_e32 v173, v182, v182
	global_store_dwordx4 v[180:181], v[176:179], off
	v_add_f32_e32 v0, v173, v0
	v_pk_add_f32 v[182:183], v[54:55], v[194:195]
	v_pk_add_f32 v[178:179], v[58:59], v[186:187]
	v_pk_add_f32 v[176:177], v[56:57], v[184:185]
	v_mul_f32_e32 v186, v179, v179
	v_mul_f32_e32 v173, v177, v177
	v_pk_add_f32 v[184:185], v[52:53], v[192:193]
	v_fmac_f32_e32 v173, v176, v176
	v_fmac_f32_e32 v186, v178, v178
	v_add_f32_e32 v173, v173, v186
	v_mul_f32_e32 v186, v185, v185
	v_fmac_f32_e32 v186, v184, v184
	v_add_f32_e32 v173, v173, v186
	v_mul_f32_e32 v186, v183, v183
	v_fmac_f32_e32 v186, v182, v182
	v_add_f32_e32 v173, v186, v173
	v_add_f32_e32 v0, v0, v173
	ds_swizzle_b32 v173, v0 offset:swizzle(SWAP,16)
	v_cvt_pk_bf16_f32 v176, v176, v177
	v_cvt_pk_bf16_f32 v177, v178, v179
	v_cvt_pk_bf16_f32 v178, v184, v185
	v_cvt_pk_bf16_f32 v179, v182, v183
	s_waitcnt lgkmcnt(0)
	v_add_f32_e32 v0, v0, v173
	v_mov_b32_e32 v173, v0
	s_nop 1
	v_permlane32_swap_b32_e32 v0, v173
	global_store_dwordx4 v[180:181], v[176:179], off offset:256
	s_and_saveexec_b64 s[58:59], s[12:13]
	s_cbranch_execz .LBB0_893
	v_lshlrev_b64 v[154:155], 8, v[154:155]
	v_lshl_add_u64 v[154:155], s[22:23], 0, v[154:155]
	v_lshl_add_u64 v[154:155], s[62:63], 2, v[154:155]
	v_add_f32_e32 v0, v0, v173
	global_store_dword v[154:155], v0, off

.LBB0_895:
	s_or_b64 exec, exec, s[58:59]
	v_add_u32_e32 v154, 0xa0, v170
	v_ashrrev_i32_e32 v155, 31, v154
	v_lshlrev_b64 v[132:133], 14, v[154:155]
	v_lshl_add_u64 v[132:133], v[150:151], 0, v[132:133]
	global_load_dwordx4 v[176:179], v[132:133], off
	global_load_dwordx4 v[180:183], v[132:133], off offset:16
	global_load_dwordx4 v[184:187], v[132:133], off offset:512
	global_load_dwordx4 v[192:195], v[132:133], off offset:528
	v_add_u32_e32 v152, 0xb0, v170
	v_ashrrev_i32_e32 v153, 31, v152
	v_lshlrev_b64 v[132:133], 14, v[152:153]
	v_lshl_add_u64 v[132:133], v[150:151], 0, v[132:133]
	global_load_dwordx4 v[144:147], v[132:133], off
	global_load_dwordx4 v[140:143], v[132:133], off offset:16
	global_load_dwordx4 v[136:139], v[132:133], off offset:512
	s_nop 0
	global_load_dwordx4 v[132:135], v[132:133], off offset:528
	s_waitcnt vmcnt(0) lgkmcnt(0)
	v_pk_add_f32 v[150:151], v[32:33], v[178:179]
	v_pk_add_f32 v[176:177], v[30:31], v[176:177]
	v_mul_f32_e32 v173, v151, v151
	v_mul_f32_e32 v0, v177, v177
	v_pk_add_f32 v[178:179], v[26:27], v[180:181]
	v_fmac_f32_e32 v0, v176, v176
	v_fmac_f32_e32 v173, v150, v150
	v_add_f32_e32 v0, v0, v173
	v_mul_f32_e32 v173, v179, v179
	v_cvt_pk_bf16_f32 v176, v176, v177
	v_cvt_pk_bf16_f32 v177, v150, v151
	v_lshlrev_b64 v[150:151], 13, v[154:155]
	v_pk_add_f32 v[182:183], v[28:29], v[182:183]
	v_fmac_f32_e32 v173, v178, v178
	v_lshl_add_u64 v[150:151], s[14:15], 0, v[150:151]
	v_add_f32_e32 v0, v0, v173
	v_mul_f32_e32 v173, v183, v183
	v_cvt_pk_bf16_f32 v178, v178, v179
	v_cvt_pk_bf16_f32 v179, v182, v183
	v_lshl_add_u64 v[150:151], v[168:169], 1, v[150:151]
	v_fmac_f32_e32 v173, v182, v182
	global_store_dwordx4 v[150:151], v[176:179], off
	v_add_f32_e32 v0, v173, v0
	v_pk_add_f32 v[182:183], v[18:19], v[192:193]
	v_pk_add_f32 v[178:179], v[24:25], v[186:187]
	v_pk_add_f32 v[176:177], v[22:23], v[184:185]
	v_mul_f32_e32 v184, v179, v179
	v_mul_f32_e32 v173, v177, v177
	v_fmac_f32_e32 v173, v176, v176
	v_fmac_f32_e32 v184, v178, v178
	v_add_f32_e32 v173, v173, v184
	v_mul_f32_e32 v184, v183, v183
	v_pk_add_f32 v[180:181], v[20:21], v[194:195]
	v_fmac_f32_e32 v184, v182, v182
	v_add_f32_e32 v173, v173, v184
	v_mul_f32_e32 v184, v181, v181
	v_fmac_f32_e32 v184, v180, v180
	v_add_f32_e32 v173, v184, v173
	v_add_f32_e32 v0, v0, v173
	v_cvt_pk_bf16_f32 v176, v176, v177
	v_cvt_pk_bf16_f32 v177, v178, v179
	v_cvt_pk_bf16_f32 v178, v182, v183
	v_cvt_pk_bf16_f32 v179, v180, v181
	global_store_dwordx4 v[150:151], v[176:179], off offset:256
	ds_swizzle_b32 v150, v0 offset:swizzle(SWAP,16)
	s_waitcnt lgkmcnt(0)
	v_add_f32_e32 v0, v0, v150
	v_mov_b32_e32 v150, v0
	s_nop 1
	v_permlane32_swap_b32_e32 v0, v150
	s_and_saveexec_b64 s[58:59], s[12:13]
	s_cbranch_execz .LBB0_897
	v_lshlrev_b64 v[154:155], 8, v[154:155]
	v_lshl_add_u64 v[154:155], s[22:23], 0, v[154:155]
	v_lshl_add_u64 v[154:155], s[62:63], 2, v[154:155]
	v_add_f32_e32 v0, v0, v150
	global_store_dword v[154:155], v0, off

.LBB0_929:
	s_add_i32 s9, s8, 0x5a00
	s_mul_hi_i32 s9, s9, 0x2e8ba2e9
	s_lshr_b32 s10, s9, 31
	s_ashr_i32 s9, s9, 13
	s_add_i32 s11, s9, s10
	v_mov_b32_e32 v0, s8
	v_mad_i32_i24 v10, s11, v215, v0
	s_and_b32 s10, s8, 63
	v_readfirstlane_b32 s9, v10
	s_ashr_i32 s14, s9, 6
	s_and_b32 s9, s14, 1
	s_lshl_b32 s10, s10, 6
	s_mul_i32 s12, s11, 0x11200000
	s_mul_hi_i32 s13, s11, 0x11200000
	s_add_u32 s12, s16, s12
	s_addc_u32 s13, s17, s13
	s_mul_hi_i32 s15, s11, 0xac00000
	s_mul_i32 s11, s11, 0xac00000
	s_add_u32 s11, s18, s11
	s_addc_u32 s20, s19, s15
	s_lshl_b32 s14, s14, 5
	s_ashr_i32 s15, s14, 31
	s_lshl_b64 s[14:15], s[14:15], 14
	s_add_u32 s14, s11, s14
	s_addc_u32 s15, s20, s15
	s_bfe_u32 s11, s8, 0x40002
	v_mov_b32_e32 v0, 0x560000
	v_mul_u32_u24_e32 v0, s11, v0
	v_lshl_add_u64 v[8:9], s[12:13], 0, v[0:1]
	v_ashrrev_i32_e32 v10, 7, v10
	v_add_u32_e32 v0, s10, v12
	v_ashrrev_i32_e32 v11, 31, v10
	v_and_or_b32 v0, v0, s42, v13
	v_lshlrev_b64 v[10:11], 15, v[10:11]
	v_lshl_or_b32 v0, v0, 2, v14
	v_lshl_add_u64 v[8:9], v[8:9], 0, v[10:11]
	v_lshl_add_u64 v[10:11], s[14:15], 0, v[0:1]
	v_add_co_u32_e32 v16, vcc, s78, v10
	s_mov_b32 s11, 0x74000
	s_nop 0
	v_addc_co_u32_e32 v17, vcc, 0, v11, vcc
	global_load_dword v16, v[16:17], off
	s_nop 0
	global_load_dword v17, v[10:11], off
	v_add_co_u32_e32 v18, vcc, s37, v10
	s_and_b32 s10, s10, 0xc0
	s_nop 0
	v_addc_co_u32_e32 v19, vcc, 0, v11, vcc
	v_add_co_u32_e32 v20, vcc, s34, v10
	global_load_dword v18, v[18:19], off
	s_nop 0
	v_addc_co_u32_e32 v21, vcc, 0, v11, vcc
	global_load_dword v19, v[20:21], off
	v_add_co_u32_e32 v20, vcc, s22, v10
	v_add_u32_e32 v0, s10, v12
	s_nop 0
	v_addc_co_u32_e32 v21, vcc, 0, v11, vcc
	v_add_co_u32_e32 v22, vcc, s21, v10
	global_load_dword v20, v[20:21], off
	s_nop 0
	v_addc_co_u32_e32 v23, vcc, 0, v11, vcc
	global_load_dword v21, v[22:23], off
	v_add_co_u32_e32 v22, vcc, s35, v10
	s_add_i32 s31, s31, 1
	s_nop 0
	v_addc_co_u32_e32 v23, vcc, 0, v11, vcc
	v_add_co_u32_e32 v24, vcc, s23, v10
	global_load_dword v22, v[22:23], off
	s_nop 0
	v_addc_co_u32_e32 v25, vcc, 0, v11, vcc
	v_add_co_u32_e32 v26, vcc, s43, v10
	global_load_dword v24, v[24:25], off
	s_nop 0
	v_addc_co_u32_e32 v27, vcc, 0, v11, vcc
	global_load_dword v23, v[26:27], off
	v_add_co_u32_e32 v26, vcc, s68, v10
	s_nop 1
	v_addc_co_u32_e32 v27, vcc, 0, v11, vcc
	global_load_dword v25, v[26:27], off
	v_add_co_u32_e32 v26, vcc, s49, v10
	s_nop 1
	v_addc_co_u32_e32 v27, vcc, 0, v11, vcc
	v_add_co_u32_e32 v28, vcc, s48, v10
	global_load_dword v26, v[26:27], off
	s_nop 0
	v_addc_co_u32_e32 v29, vcc, 0, v11, vcc
	global_load_dword v27, v[28:29], off
	v_add_co_u32_e32 v28, vcc, s51, v10
	s_nop 1
	v_addc_co_u32_e32 v29, vcc, 0, v11, vcc
	v_add_co_u32_e32 v30, vcc, s50, v10
	global_load_dword v28, v[28:29], off
	s_nop 0
	v_addc_co_u32_e32 v31, vcc, 0, v11, vcc
	global_load_dword v29, v[30:31], off
	v_add_co_u32_e32 v30, vcc, s53, v10
	s_nop 1
	v_addc_co_u32_e32 v31, vcc, 0, v11, vcc
	v_add_co_u32_e32 v32, vcc, s52, v10
	global_load_dword v30, v[30:31], off
	s_nop 0
	v_addc_co_u32_e32 v33, vcc, 0, v11, vcc
	global_load_dword v31, v[32:33], off
	v_add_co_u32_e32 v32, vcc, s56, v10
	s_nop 1
	v_addc_co_u32_e32 v33, vcc, 0, v11, vcc
	v_add_co_u32_e32 v36, vcc, s55, v10
	global_load_dword v32, v[32:33], off
	s_nop 0
	v_addc_co_u32_e32 v37, vcc, 0, v11, vcc
	global_load_dword v33, v[36:37], off
	v_add_co_u32_e32 v36, vcc, s58, v10
	s_nop 1
	v_addc_co_u32_e32 v37, vcc, 0, v11, vcc
	global_load_dword v35, v[36:37], off
	v_add_co_u32_e32 v36, vcc, s57, v10
	s_nop 1
	v_addc_co_u32_e32 v37, vcc, 0, v11, vcc
	v_add_co_u32_e32 v38, vcc, s60, v10
	global_load_dword v36, v[36:37], off
	s_nop 0
	v_addc_co_u32_e32 v39, vcc, 0, v11, vcc
	global_load_dword v37, v[38:39], off
	v_add_co_u32_e32 v38, vcc, s59, v10
	s_nop 1
	v_addc_co_u32_e32 v39, vcc, 0, v11, vcc
	v_add_co_u32_e32 v40, vcc, s62, v10
	global_load_dword v38, v[38:39], off
	s_nop 0
	v_addc_co_u32_e32 v41, vcc, 0, v11, vcc
	global_load_dword v39, v[40:41], off
	v_add_co_u32_e32 v40, vcc, s61, v10
	s_nop 1
	v_addc_co_u32_e32 v41, vcc, 0, v11, vcc
	v_add_co_u32_e32 v42, vcc, s64, v10
	global_load_dword v40, v[40:41], off
	s_nop 0
	v_addc_co_u32_e32 v43, vcc, 0, v11, vcc
	global_load_dword v41, v[42:43], off
	v_add_co_u32_e32 v42, vcc, s63, v10
	s_nop 1
	v_addc_co_u32_e32 v43, vcc, 0, v11, vcc
	v_add_co_u32_e32 v44, vcc, s66, v10
	global_load_dword v42, v[42:43], off
	s_nop 0
	v_addc_co_u32_e32 v45, vcc, 0, v11, vcc
	global_load_dword v43, v[44:45], off
	v_add_co_u32_e32 v44, vcc, s65, v10
	s_nop 1
	v_addc_co_u32_e32 v45, vcc, 0, v11, vcc
	v_add_co_u32_e32 v46, vcc, s11, v10
	global_load_dword v44, v[44:45], off
	s_nop 0
	v_addc_co_u32_e32 v47, vcc, 0, v11, vcc
	global_load_dword v45, v[46:47], off
	v_add_co_u32_e32 v46, vcc, s67, v10
	s_mov_b32 s11, 0x7c000
	s_nop 0
	v_addc_co_u32_e32 v47, vcc, 0, v11, vcc
	global_load_dword v48, v[46:47], off
	v_add_co_u32_e32 v46, vcc, s11, v10
	s_mov_b32 s11, 0x78000
	s_nop 0
	v_addc_co_u32_e32 v47, vcc, 0, v11, vcc
	v_add_co_u32_e32 v10, vcc, s11, v10
	global_load_dword v49, v[46:47], off
	s_nop 0
	v_addc_co_u32_e32 v11, vcc, 0, v11, vcc
	global_load_dword v50, v[10:11], off
	v_lshlrev_b32_e32 v10, 7, v0
	v_lshrrev_b32_e32 v0, 3, v0
	v_and_or_b32 v0, v0, 14, s9
	v_and_b32_e32 v10, 0xffffc000, v10
	v_lshlrev_b32_e32 v0, 10, v0
	v_or3_b32 v0, v0, v10, v15
	v_lshl_add_u64 v[8:9], v[8:9], 0, v[0:1]
	s_waitcnt vmcnt(0) lgkmcnt(0)
	v_cvt_pk_bf16_f32 v16, v17, v16
	v_cvt_pk_bf16_f32 v17, v19, v18
	v_cvt_pk_bf16_f32 v18, v21, v20
	v_lshl_add_u64 v[20:21], v[8:9], 0, s[94:95]
	v_lshl_add_u64 v[46:47], v[20:21], 0, v[2:3]
	v_cvt_pk_bf16_f32 v19, v24, v22
	global_store_dwordx4 v[46:47], v[16:19], off
	v_cvt_pk_bf16_f32 v8, v25, v23
	v_cvt_pk_bf16_f32 v9, v27, v26
	v_cvt_pk_bf16_f32 v10, v29, v28
	v_cvt_pk_bf16_f32 v11, v31, v30
	global_store_dwordx4 v[46:47], v[8:11], off offset:16
	s_nop 0
	v_lshl_add_u64 v[16:17], v[20:21], 0, v[4:5]
	v_mov_b32_e32 v0, 0xfffff800
	v_cvt_pk_bf16_f32 v8, v33, v32
	v_cvt_pk_bf16_f32 v9, v36, v35
	v_cvt_pk_bf16_f32 v10, v38, v37
	v_cvt_pk_bf16_f32 v11, v40, v39
	global_store_dwordx4 v[16:17], v[8:11], off
	v_lshl_add_u64 v[16:17], v[20:21], 0, v[6:7]
	v_sub_co_u32_e32 v0, vcc, s8, v0
	v_cvt_pk_bf16_f32 v8, v42, v41
	v_cvt_pk_bf16_f32 v9, v44, v43
	v_cvt_pk_bf16_f32 v10, v48, v45
	v_cvt_pk_bf16_f32 v11, v50, v49
	global_store_dwordx4 v[16:17], v[8:11], off offset:16
	v_readfirstlane_b32 s8, v0
	s_and_b64 vcc, exec, vcc
	s_cbranch_vccnz .LBB0_929
	s_movk_i32 s37, 0x17ff

.LBB0_1091:
	s_lshl_b32 s34, s48, 5
	s_ashr_i32 s35, s34, 31
	s_lshl_b64 s[48:49], s[34:35], 2
	s_add_u32 s48, s94, s48
	s_addc_u32 s49, s95, s49
	s_cmp_lg_u64 s[94:95], 0
	s_mul_i32 s35, s66, s35
	s_mul_hi_u32 s58, s66, s34
	s_cselect_b32 s49, s49, 0
	s_cselect_b32 s48, s48, 0
	s_add_i32 s35, s58, s35
	s_mul_i32 s58, s67, s34
	s_add_i32 s35, s35, s58
	s_mul_i32 s34, s66, s34
	s_lshl_b64 s[34:35], s[34:35], 2
	s_add_u32 s68, s74, s34
	s_addc_u32 s69, s75, s35
	v_and_b32_e32 v0, 31, v101
	s_cmp_eq_u64 s[48:49], 0
	s_cselect_b32 s35, s69, s49
	s_cselect_b32 s34, s68, s48
	v_lshlrev_b32_e32 v0, 2, v0
	s_waitcnt vmcnt(0)
	v_lshl_add_u64 v[2:3], s[34:35], 0, v[0:1]
	global_load_dword v198, v[2:3], off
	v_lshlrev_b32_e32 v0, 1, v101
	v_lshrrev_b32_e32 v2, 2, v101
	v_lshl_add_u32 v3, s59, 6, v101
	v_and_b32_e32 v0, 24, v0
	v_and_b32_e32 v4, 4, v2
	v_and_b32_e32 v2, 0xffffffe3, v3
	s_andn2_b64 vcc, exec, s[12:13]
	v_or3_b32 v0, v0, v2, v4
	s_cbranch_vccnz .LBB0_1097
	s_movk_i32 s2, 0x9ff
	v_cmp_lt_i32_e64 s[12:13], s2, v0
	s_movk_i32 s2, 0xa00
	v_cmp_gt_i32_e32 vcc, s2, v0
	s_and_saveexec_b64 s[58:59], vcc
	v_readlane_b32 s74, v255, 21
	v_readlane_b32 s75, v255, 22
	v_lshlrev_b32_e32 v2, 2, v4
	v_and_b32_e32 v4, 0x60, v3
	v_cmp_ne_u32_e32 vcc, 0, v4
	s_movk_i32 s2, 0xff8f
	s_andn2_b64 s[12:13], s[12:13], exec
	s_and_b64 s[34:35], vcc, exec
	v_and_or_b32 v2, v3, s2, v2
	s_or_b64 s[12:13], s[12:13], s[34:35]
	s_or_b64 exec, exec, s[58:59]
	s_and_saveexec_b64 s[58:59], s[12:13]
	v_mov_b32_e32 v2, v0
	s_or_b64 exec, exec, s[58:59]
	v_mov_b32_e32 v0, v2
	s_branch .LBB0_1098

.LBB0_1098:
	v_lshlrev_b32_e32 v0, 2, v0
	v_lshl_add_u64 v[4:5], s[68:69], 0, v[0:1]
	s_lshl_b64 s[12:13], s[66:67], 2
	global_load_dword v2, v[4:5], off
	v_lshl_add_u64 v[4:5], v[4:5], 0, s[12:13]
	v_lshl_add_u64 v[6:7], v[4:5], 0, s[12:13]
	global_load_dword v3, v[4:5], off
	s_mov_b32 s68, 0x20000
	global_load_dword v4, v[6:7], off
	v_lshl_add_u64 v[6:7], v[6:7], 0, s[12:13]
	v_lshl_add_u64 v[8:9], v[6:7], 0, s[12:13]
	global_load_dword v5, v[6:7], off
	s_nop 0
	global_load_dword v6, v[8:9], off
	v_lshl_add_u64 v[8:9], v[8:9], 0, s[12:13]
	v_lshl_add_u64 v[10:11], v[8:9], 0, s[12:13]
	global_load_dword v7, v[8:9], off
	s_nop 0
	global_load_dword v8, v[10:11], off
	v_lshl_add_u64 v[10:11], v[10:11], 0, s[12:13]
	v_lshl_add_u64 v[12:13], v[10:11], 0, s[12:13]
	global_load_dword v9, v[10:11], off
	s_nop 0
	global_load_dword v10, v[12:13], off
	v_lshl_add_u64 v[12:13], v[12:13], 0, s[12:13]
	v_lshl_add_u64 v[14:15], v[12:13], 0, s[12:13]
	global_load_dword v11, v[12:13], off
	s_nop 0
	global_load_dword v12, v[14:15], off
	v_lshl_add_u64 v[14:15], v[14:15], 0, s[12:13]
	v_lshl_add_u64 v[16:17], v[14:15], 0, s[12:13]
	global_load_dword v13, v[14:15], off
	s_nop 0
	global_load_dword v14, v[16:17], off
	v_lshl_add_u64 v[16:17], v[16:17], 0, s[12:13]
	v_lshl_add_u64 v[18:19], v[16:17], 0, s[12:13]
	global_load_dword v15, v[16:17], off
	s_nop 0
	global_load_dword v16, v[18:19], off
	v_lshl_add_u64 v[18:19], v[18:19], 0, s[12:13]
	v_lshl_add_u64 v[20:21], v[18:19], 0, s[12:13]
	global_load_dword v17, v[18:19], off
	s_nop 0
	global_load_dword v18, v[20:21], off
	v_lshl_add_u64 v[20:21], v[20:21], 0, s[12:13]
	v_lshl_add_u64 v[22:23], v[20:21], 0, s[12:13]
	global_load_dword v19, v[20:21], off
	s_nop 0
	global_load_dword v20, v[22:23], off
	v_lshl_add_u64 v[22:23], v[22:23], 0, s[12:13]
	v_lshl_add_u64 v[24:25], v[22:23], 0, s[12:13]
	global_load_dword v21, v[22:23], off
	s_nop 0
	global_load_dword v22, v[24:25], off
	v_lshl_add_u64 v[24:25], v[24:25], 0, s[12:13]
	v_lshl_add_u64 v[26:27], v[24:25], 0, s[12:13]
	global_load_dword v23, v[24:25], off
	s_nop 0
	global_load_dword v24, v[26:27], off
	v_lshl_add_u64 v[26:27], v[26:27], 0, s[12:13]
	v_lshl_add_u64 v[28:29], v[26:27], 0, s[12:13]
	global_load_dword v25, v[26:27], off
	s_nop 0
	global_load_dword v26, v[28:29], off
	v_lshl_add_u64 v[28:29], v[28:29], 0, s[12:13]
	v_lshl_add_u64 v[30:31], v[28:29], 0, s[12:13]
	global_load_dword v27, v[28:29], off
	s_nop 0
	global_load_dword v28, v[30:31], off
	v_lshl_add_u64 v[30:31], v[30:31], 0, s[12:13]
	v_lshl_add_u64 v[32:33], v[30:31], 0, s[12:13]
	global_load_dword v29, v[30:31], off
	s_nop 0
	global_load_dword v30, v[32:33], off
	v_lshl_add_u64 v[32:33], v[32:33], 0, s[12:13]
	v_lshl_add_u64 v[102:103], v[32:33], 0, s[12:13]
	global_load_dword v31, v[32:33], off
	s_nop 0
	global_load_dword v32, v[102:103], off
	v_lshl_add_u64 v[102:103], v[102:103], 0, s[12:13]
	global_load_dword v33, v[102:103], off

.LBB0_1131:
	s_ashr_i32 s6, s55, 2
	s_ashr_i32 s7, s6, 31
	s_mul_i32 s7, s52, s7
	s_mul_hi_u32 s35, s52, s6
	s_add_i32 s7, s35, s7
	s_mul_i32 s35, s53, s6
	s_and_b32 s34, s54, 1
	s_add_i32 s7, s7, s35
	s_mul_i32 s6, s52, s6
	s_add_u32 s14, s14, s6
	s_addc_u32 s15, s15, s7
	s_ashr_i32 s6, s54, 1
	s_ashr_i32 s7, s6, 31
	s_lshl_b64 s[6:7], s[6:7], 15
	s_add_u32 s6, s14, s6
	v_lshlrev_b32_e32 v14, 2, v13
	v_mov_b32_e32 v15, v1
	s_addc_u32 s7, s15, s7
	v_lshl_add_u64 v[14:15], s[50:51], 0, v[14:15]
	s_lshl_b64 s[12:13], s[12:13], 2
	global_load_dword v13, v[14:15], off
	v_lshl_add_u64 v[14:15], v[14:15], 0, s[12:13]
	global_load_dword v16, v[14:15], off
	v_lshl_add_u64 v[14:15], v[14:15], 0, s[12:13]
	global_load_dword v17, v[14:15], off
	v_lshl_add_u64 v[14:15], v[14:15], 0, s[12:13]
	global_load_dword v20, v[14:15], off
	v_lshl_add_u64 v[14:15], v[14:15], 0, s[12:13]
	global_load_dword v21, v[14:15], off
	v_lshl_add_u64 v[14:15], v[14:15], 0, s[12:13]
	global_load_dword v22, v[14:15], off
	v_lshl_add_u64 v[14:15], v[14:15], 0, s[12:13]
	global_load_dword v23, v[14:15], off
	v_lshl_add_u64 v[14:15], v[14:15], 0, s[12:13]
	global_load_dword v24, v[14:15], off
	v_lshl_add_u64 v[14:15], v[14:15], 0, s[12:13]
	global_load_dword v25, v[14:15], off
	v_lshl_add_u64 v[14:15], v[14:15], 0, s[12:13]
	global_load_dword v26, v[14:15], off
	v_lshl_add_u64 v[14:15], v[14:15], 0, s[12:13]
	global_load_dword v27, v[14:15], off
	v_lshl_add_u64 v[14:15], v[14:15], 0, s[12:13]
	global_load_dword v28, v[14:15], off
	v_lshl_add_u64 v[14:15], v[14:15], 0, s[12:13]
	global_load_dword v29, v[14:15], off
	v_lshl_add_u64 v[14:15], v[14:15], 0, s[12:13]
	global_load_dword v30, v[14:15], off
	v_lshl_add_u64 v[14:15], v[14:15], 0, s[12:13]
	global_load_dword v31, v[14:15], off
	v_lshl_add_u64 v[14:15], v[14:15], 0, s[12:13]
	global_load_dword v32, v[14:15], off
	v_lshl_add_u64 v[14:15], v[14:15], 0, s[12:13]
	global_load_dword v33, v[14:15], off
	v_lshl_add_u64 v[14:15], v[14:15], 0, s[12:13]
	global_load_dword v35, v[14:15], off
	v_lshl_add_u64 v[14:15], v[14:15], 0, s[12:13]
	global_load_dword v36, v[14:15], off
	v_lshl_add_u64 v[14:15], v[14:15], 0, s[12:13]
	global_load_dword v37, v[14:15], off
	v_lshl_add_u64 v[14:15], v[14:15], 0, s[12:13]
	global_load_dword v38, v[14:15], off
	v_lshl_add_u64 v[14:15], v[14:15], 0, s[12:13]
	global_load_dword v39, v[14:15], off
	v_lshl_add_u64 v[14:15], v[14:15], 0, s[12:13]
	global_load_dword v40, v[14:15], off
	v_lshl_add_u64 v[14:15], v[14:15], 0, s[12:13]
	global_load_dword v41, v[14:15], off
	v_lshl_add_u64 v[14:15], v[14:15], 0, s[12:13]
	global_load_dword v42, v[14:15], off
	v_lshl_add_u64 v[14:15], v[14:15], 0, s[12:13]
	global_load_dword v43, v[14:15], off
	v_lshl_add_u64 v[14:15], v[14:15], 0, s[12:13]
	global_load_dword v44, v[14:15], off
	v_lshl_add_u64 v[14:15], v[14:15], 0, s[12:13]
	global_load_dword v45, v[14:15], off
	v_lshl_add_u64 v[14:15], v[14:15], 0, s[12:13]
	global_load_dword v46, v[14:15], off
	v_lshl_add_u64 v[14:15], v[14:15], 0, s[12:13]
	global_load_dword v47, v[14:15], off
	v_lshl_add_u64 v[14:15], v[14:15], 0, s[12:13]
	global_load_dword v48, v[14:15], off
	v_lshl_add_u64 v[14:15], v[14:15], 0, s[12:13]
	global_load_dword v49, v[14:15], off
	s_and_b32 s12, s56, 0xc0
	v_add_u32_e32 v14, s12, v8
	v_lshlrev_b32_e32 v15, 7, v14
	v_lshrrev_b32_e32 v14, 3, v14
	v_and_or_b32 v14, v14, 14, s34
	v_and_b32_e32 v15, 0xffffc000, v15
	v_lshlrev_b32_e32 v14, 10, v14
	s_waitcnt vmcnt(0) lgkmcnt(0)
	v_readlane_b32 s12, v12, 0
	v_or3_b32 v18, v14, v15, v10
	v_mov_b32_e32 v19, v1
	v_mov_b32_e32 v14, s12
	v_readlane_b32 s12, v12, 1
	v_cndmask_b32_e64 v14, v14, 1.0, s[10:11]
	v_lshl_add_u64 v[18:19], s[6:7], 0, v[18:19]
	v_mov_b32_e32 v15, s12
	v_readlane_b32 s12, v12, 2
	v_cndmask_b32_e64 v15, v15, 1.0, s[10:11]
	v_mul_f32_e32 v13, v13, v14
	v_mov_b32_e32 v50, s12
	v_readlane_b32 s12, v12, 3
	v_cndmask_b32_e64 v50, v50, 1.0, s[10:11]
	v_mul_f32_e32 v14, v16, v15
	v_mov_b32_e32 v51, s12
	v_readlane_b32 s12, v12, 4
	v_cndmask_b32_e64 v51, v51, 1.0, s[10:11]
	v_cvt_pk_bf16_f32 v14, v13, v14
	v_mul_f32_e32 v13, v17, v50
	v_mov_b32_e32 v52, s12
	v_readlane_b32 s12, v12, 5
	v_cndmask_b32_e64 v52, v52, 1.0, s[10:11]
	v_mul_f32_e32 v15, v20, v51
	v_mov_b32_e32 v53, s12
	v_readlane_b32 s12, v12, 6
	v_cndmask_b32_e64 v53, v53, 1.0, s[10:11]
	v_cvt_pk_bf16_f32 v15, v13, v15
	v_mul_f32_e32 v13, v21, v52
	v_mov_b32_e32 v54, s12
	v_readlane_b32 s12, v12, 7
	v_cndmask_b32_e64 v54, v54, 1.0, s[10:11]
	v_mul_f32_e32 v16, v22, v53
	v_mov_b32_e32 v55, s12
	v_cndmask_b32_e64 v55, v55, 1.0, s[10:11]
	v_cvt_pk_bf16_f32 v16, v13, v16
	v_mul_f32_e32 v13, v23, v54
	v_mul_f32_e32 v17, v24, v55
	v_readlane_b32 s6, v12, 8
	v_cvt_pk_bf16_f32 v17, v13, v17
	v_lshl_add_u64 v[20:21], v[18:19], 0, v[2:3]
	global_store_dwordx4 v[20:21], v[14:17], off
	v_mov_b32_e32 v13, s6
	v_readlane_b32 s6, v12, 9
	v_cndmask_b32_e64 v13, v13, 1.0, s[10:11]
	v_mul_f32_e32 v13, v25, v13
	v_mov_b32_e32 v14, s6
	v_readlane_b32 s6, v12, 10
	v_cndmask_b32_e64 v14, v14, 1.0, s[10:11]
	v_mul_f32_e32 v14, v26, v14
	v_mov_b32_e32 v15, s6
	v_readlane_b32 s6, v12, 11
	v_cndmask_b32_e64 v15, v15, 1.0, s[10:11]
	v_cvt_pk_bf16_f32 v14, v13, v14
	v_mul_f32_e32 v13, v27, v15
	v_mov_b32_e32 v16, s6
	v_readlane_b32 s6, v12, 12
	v_cndmask_b32_e64 v16, v16, 1.0, s[10:11]
	v_mul_f32_e32 v15, v28, v16
	v_mov_b32_e32 v17, s6
	v_readlane_b32 s6, v12, 13
	v_cndmask_b32_e64 v17, v17, 1.0, s[10:11]
	v_cvt_pk_bf16_f32 v15, v13, v15
	v_mul_f32_e32 v13, v29, v17
	v_mov_b32_e32 v22, s6
	v_readlane_b32 s6, v12, 14
	v_cndmask_b32_e64 v22, v22, 1.0, s[10:11]
	v_mul_f32_e32 v16, v30, v22
	v_mov_b32_e32 v23, s6
	v_readlane_b32 s6, v12, 15
	v_cndmask_b32_e64 v23, v23, 1.0, s[10:11]
	v_cvt_pk_bf16_f32 v16, v13, v16
	v_mul_f32_e32 v13, v31, v23
	v_mov_b32_e32 v24, s6
	v_cndmask_b32_e64 v24, v24, 1.0, s[10:11]
	v_mul_f32_e32 v17, v32, v24
	v_readlane_b32 s6, v12, 16
	v_cvt_pk_bf16_f32 v17, v13, v17
	global_store_dwordx4 v[20:21], v[14:17], off offset:16
	s_add_i32 s31, s31, 1
	v_mov_b32_e32 v13, s6
	v_readlane_b32 s6, v12, 17
	v_cndmask_b32_e64 v13, v13, 1.0, s[10:11]
	v_mul_f32_e32 v13, v33, v13
	v_mov_b32_e32 v14, s6
	v_readlane_b32 s6, v12, 18
	v_cndmask_b32_e64 v14, v14, 1.0, s[10:11]
	v_mul_f32_e32 v14, v35, v14
	v_mov_b32_e32 v15, s6
	v_readlane_b32 s6, v12, 19
	v_cndmask_b32_e64 v15, v15, 1.0, s[10:11]
	v_cvt_pk_bf16_f32 v14, v13, v14
	v_mul_f32_e32 v13, v36, v15
	v_mov_b32_e32 v16, s6
	v_readlane_b32 s6, v12, 20
	v_cndmask_b32_e64 v16, v16, 1.0, s[10:11]
	v_mul_f32_e32 v15, v37, v16
	v_mov_b32_e32 v17, s6
	v_readlane_b32 s6, v12, 21
	v_cndmask_b32_e64 v17, v17, 1.0, s[10:11]
	v_cvt_pk_bf16_f32 v15, v13, v15
	v_mul_f32_e32 v13, v38, v17
	v_mov_b32_e32 v20, s6
	v_readlane_b32 s6, v12, 22
	v_cndmask_b32_e64 v20, v20, 1.0, s[10:11]
	v_mul_f32_e32 v16, v39, v20
	v_mov_b32_e32 v21, s6
	v_readlane_b32 s6, v12, 23
	v_cndmask_b32_e64 v21, v21, 1.0, s[10:11]
	v_cvt_pk_bf16_f32 v16, v13, v16
	v_mul_f32_e32 v13, v40, v21
	v_mov_b32_e32 v22, s6
	v_cndmask_b32_e64 v22, v22, 1.0, s[10:11]
	v_mul_f32_e32 v17, v41, v22
	v_readlane_b32 s6, v12, 24
	v_cvt_pk_bf16_f32 v17, v13, v17
	v_lshl_add_u64 v[20:21], v[18:19], 0, v[4:5]
	global_store_dwordx4 v[20:21], v[14:17], off
	v_mov_b32_e32 v13, s6
	v_readlane_b32 s6, v12, 25
	v_cndmask_b32_e64 v13, v13, 1.0, s[10:11]
	s_addk_i32 s9, 0x800
	v_mov_b32_e32 v14, s6
	v_readlane_b32 s6, v12, 26
	v_cndmask_b32_e64 v14, v14, 1.0, s[10:11]
	s_cmp_lt_i32 s9, s8
	v_mov_b32_e32 v15, s6
	v_readlane_b32 s6, v12, 27
	v_cndmask_b32_e64 v15, v15, 1.0, s[10:11]
	s_nop 0
	v_mov_b32_e32 v16, s6
	v_readlane_b32 s6, v12, 28
	v_cndmask_b32_e64 v16, v16, 1.0, s[10:11]
	s_nop 0
	v_mov_b32_e32 v17, s6
	v_readlane_b32 s6, v12, 29
	v_cndmask_b32_e64 v17, v17, 1.0, s[10:11]
	s_nop 0
	v_mov_b32_e32 v20, s6
	v_readlane_b32 s6, v12, 30
	v_cndmask_b32_e64 v20, v20, 1.0, s[10:11]
	s_nop 0
	v_mov_b32_e32 v21, s6
	v_readlane_b32 s6, v12, 31
	v_cndmask_b32_e64 v21, v21, 1.0, s[10:11]
	s_nop 0
	v_mov_b32_e32 v12, s6
	v_cndmask_b32_e64 v22, v12, 1.0, s[10:11]
	v_mul_f32_e32 v12, v42, v13
	v_mul_f32_e32 v13, v43, v14
	v_cvt_pk_bf16_f32 v12, v12, v13
	v_mul_f32_e32 v13, v44, v15
	v_mul_f32_e32 v14, v45, v16
	v_cvt_pk_bf16_f32 v13, v13, v14
	v_mul_f32_e32 v14, v46, v17
	v_mul_f32_e32 v15, v47, v20
	v_cvt_pk_bf16_f32 v14, v14, v15
	v_mul_f32_e32 v15, v48, v21
	v_mul_f32_e32 v16, v49, v22
	v_cvt_pk_bf16_f32 v15, v15, v16
	v_lshl_add_u64 v[16:17], v[18:19], 0, v[6:7]
	global_store_dwordx4 v[16:17], v[12:15], off offset:16
	s_cbranch_scc0 .LBB0_1155

.LBB0_1149:
	s_lshl_b32 s10, s54, 5
	s_ashr_i32 s11, s10, 31
	s_lshl_b64 s[34:35], s[10:11], 2
	s_add_u32 s34, s62, s34
	s_addc_u32 s35, s63, s35
	s_cmp_lg_u64 s[62:63], 0
	s_mul_i32 s11, s12, s11
	s_mul_hi_u32 s48, s12, s10
	s_cselect_b32 s35, s35, 0
	s_cselect_b32 s34, s34, 0
	s_add_i32 s11, s48, s11
	s_mul_i32 s48, s13, s10
	s_add_i32 s11, s11, s48
	s_mul_i32 s10, s12, s10
	s_lshl_b32 s56, s55, 6
	s_lshl_b64 s[10:11], s[10:11], 2
	s_add_u32 s50, s60, s10
	s_addc_u32 s51, s61, s11
	s_cmp_eq_u64 s[34:35], 0
	s_cselect_b64 s[10:11], -1, 0
	s_and_b64 s[48:49], s[10:11], exec
	s_cselect_b32 s35, s51, s35
	s_cselect_b32 s34, s50, s34
	v_lshl_add_u64 v[12:13], s[34:35], 0, v[0:1]
	global_load_dword v12, v[12:13], off
	v_add_u32_e32 v14, s56, v8
	s_movk_i32 s34, 0xffe3
	v_and_or_b32 v13, v14, s34, v11
	s_andn2_b64 vcc, exec, s[6:7]
	s_cbranch_vccnz .LBB0_1131
	s_movk_i32 s6, 0x9ff
	s_movk_i32 s34, 0xa00
	v_cmp_lt_i32_e64 s[6:7], s6, v13
	v_cmp_gt_i32_e32 vcc, s34, v13
	s_and_saveexec_b64 s[58:59], vcc
	v_and_b32_e32 v15, 0x60, v14
	v_cmp_ne_u32_e32 vcc, 0, v15
	s_movk_i32 s34, 0xff8f
	v_and_or_b32 v15, v14, s34, v9
	s_andn2_b64 s[6:7], s[6:7], exec
	s_and_b64 s[34:35], vcc, exec
	s_or_b64 s[6:7], s[6:7], s[34:35]
	s_or_b64 exec, exec, s[58:59]
	s_and_saveexec_b64 s[58:59], s[6:7]
	s_cbranch_execz .LBB0_1130
	v_mov_b32_e32 v15, v13
	s_branch .LBB0_1130

.LBB0_1264:
	s_lshl_b32 s50, s31, 11
	s_add_i32 s50, s50, s26
	s_cmp_lt_i32 s50, 0
	s_cselect_b64 s[22:23], -1, 0
	v_mov_b32_e32 v232, v35
	v_mov_b32_e32 v0, v35
	s_and_b64 vcc, exec, s[22:23]
	s_cbranch_vccz .LBB0_1266
	s_add_i32 s34, s50, 0x10a00
	s_mul_hi_i32 s34, s34, 0x2e8ba2e9
	s_lshr_b32 s35, s34, 31
	s_ashr_i32 s34, s34, 13
	s_add_i32 s34, s34, s35
	v_mov_b32_e32 v134, s50
	v_mad_i32_i24 v134, s34, v215, v134
	s_mul_hi_i32 s42, s34, 0xac00000
	v_readfirstlane_b32 s35, v134
	s_add_i32 s35, s35, 0xb000
	s_mul_i32 s34, s34, 0xac00000
	s_add_u32 s43, s12, s34
	s_addc_u32 s42, s13, s42
	s_ashr_i32 s34, s35, 1
	s_andn2_b32 s34, s34, 31
	v_lshlrev_b32_e32 v133, 1, v0
	s_ashr_i32 s35, s34, 31
	v_and_b32_e32 v132, 16, v0
	v_and_b32_e32 v133, 24, v133
	s_lshl_b64 s[34:35], s[34:35], 14
	v_add_u32_e32 v0, s97, v0
	s_mov_b32 s37, 0x3fffffe3
	s_add_u32 s34, s43, s34
	v_and_or_b32 v0, v0, s37, v133
	s_addc_u32 s35, s42, s35
	v_lshl_or_b32 v0, v0, 2, v132
	v_lshl_add_u64 v[132:133], s[34:35], 0, v[0:1]
	v_add_co_u32_e32 v134, vcc, s78, v132
	s_mov_b32 s34, 0x8000
	s_nop 0
	v_addc_co_u32_e32 v135, vcc, 0, v133, vcc
	global_load_dword v188, v[132:133], off
	global_load_dword v189, v[134:135], off
	v_add_co_u32_e32 v134, vcc, s34, v132
	s_mov_b32 s34, 0xc000
	s_nop 0
	v_addc_co_u32_e32 v135, vcc, 0, v133, vcc
	global_load_dword v190, v[134:135], off
	v_add_co_u32_e32 v134, vcc, s34, v132
	s_mov_b32 s34, 0x10000
	s_nop 0
	v_addc_co_u32_e32 v135, vcc, 0, v133, vcc
	global_load_dword v191, v[134:135], off
	v_add_co_u32_e32 v134, vcc, s34, v132
	s_mov_b32 s34, 0x14000
	s_nop 0
	v_addc_co_u32_e32 v135, vcc, 0, v133, vcc
	global_load_dword v196, v[134:135], off
	v_add_co_u32_e32 v134, vcc, s34, v132
	s_mov_b32 s34, 0x18000
	s_nop 0
	v_addc_co_u32_e32 v135, vcc, 0, v133, vcc
	global_load_dword v197, v[134:135], off
	v_add_co_u32_e32 v134, vcc, s34, v132
	s_mov_b32 s34, 0x1c000
	s_nop 0
	v_addc_co_u32_e32 v135, vcc, 0, v133, vcc
	global_load_dword v198, v[134:135], off
	v_add_co_u32_e32 v134, vcc, s34, v132
	s_mov_b32 s34, 0x24000
	s_nop 0
	v_addc_co_u32_e32 v135, vcc, 0, v133, vcc
	global_load_dword v199, v[134:135], off
	v_add_co_u32_e32 v134, vcc, s68, v132
	s_nop 1
	v_addc_co_u32_e32 v135, vcc, 0, v133, vcc
	global_load_dword v200, v[134:135], off
	v_add_co_u32_e32 v134, vcc, s34, v132
	s_mov_b32 s34, 0x28000
	s_nop 0
	v_addc_co_u32_e32 v135, vcc, 0, v133, vcc
	global_load_dword v201, v[134:135], off
	v_add_co_u32_e32 v134, vcc, s34, v132
	s_mov_b32 s34, 0x2c000
	s_nop 0
	v_addc_co_u32_e32 v135, vcc, 0, v133, vcc
	global_load_dword v202, v[134:135], off
	v_add_co_u32_e32 v134, vcc, s34, v132
	s_mov_b32 s34, 0x30000
	s_nop 0
	v_addc_co_u32_e32 v135, vcc, 0, v133, vcc
	global_load_dword v203, v[134:135], off
	v_add_co_u32_e32 v134, vcc, s34, v132
	s_mov_b32 s34, 0x34000
	s_nop 0
	v_addc_co_u32_e32 v135, vcc, 0, v133, vcc
	global_load_dword v204, v[134:135], off
	v_add_co_u32_e32 v134, vcc, s34, v132
	s_mov_b32 s34, 0x38000
	s_nop 0
	v_addc_co_u32_e32 v135, vcc, 0, v133, vcc
	global_load_dword v205, v[134:135], off
	v_add_co_u32_e32 v134, vcc, s34, v132
	s_mov_b32 s34, 0x3c000
	s_nop 0
	v_addc_co_u32_e32 v135, vcc, 0, v133, vcc
	global_load_dword v206, v[134:135], off
	v_add_co_u32_e32 v134, vcc, s34, v132
	s_mov_b32 s34, 0x40000
	s_nop 0
	v_addc_co_u32_e32 v135, vcc, 0, v133, vcc
	global_load_dword v207, v[134:135], off
	v_add_co_u32_e32 v134, vcc, s34, v132
	s_mov_b32 s34, 0x44000
	s_nop 0
	v_addc_co_u32_e32 v135, vcc, 0, v133, vcc
	global_load_dword v216, v[134:135], off
	v_add_co_u32_e32 v134, vcc, s34, v132
	s_mov_b32 s34, 0x48000
	s_nop 0
	v_addc_co_u32_e32 v135, vcc, 0, v133, vcc
	global_load_dword v217, v[134:135], off
	v_add_co_u32_e32 v134, vcc, s34, v132
	s_mov_b32 s34, 0x4c000
	s_nop 0
	v_addc_co_u32_e32 v135, vcc, 0, v133, vcc
	global_load_dword v218, v[134:135], off
	v_add_co_u32_e32 v134, vcc, s34, v132
	s_mov_b32 s34, 0x50000
	s_nop 0
	v_addc_co_u32_e32 v135, vcc, 0, v133, vcc
	global_load_dword v219, v[134:135], off
	v_add_co_u32_e32 v134, vcc, s34, v132
	s_mov_b32 s34, 0x54000
	s_nop 0
	v_addc_co_u32_e32 v135, vcc, 0, v133, vcc
	global_load_dword v220, v[134:135], off
	v_add_co_u32_e32 v134, vcc, s34, v132
	s_mov_b32 s34, 0x58000
	s_nop 0
	v_addc_co_u32_e32 v135, vcc, 0, v133, vcc
	global_load_dword v221, v[134:135], off
	v_add_co_u32_e32 v134, vcc, s34, v132
	s_mov_b32 s34, 0x5c000
	s_nop 0
	v_addc_co_u32_e32 v135, vcc, 0, v133, vcc
	global_load_dword v222, v[134:135], off
	v_add_co_u32_e32 v134, vcc, s34, v132
	s_mov_b32 s34, 0x60000
	s_nop 0
	v_addc_co_u32_e32 v135, vcc, 0, v133, vcc
	global_load_dword v223, v[134:135], off
	v_add_co_u32_e32 v134, vcc, s34, v132
	s_mov_b32 s34, 0x64000
	s_nop 0
	v_addc_co_u32_e32 v135, vcc, 0, v133, vcc
	global_load_dword v224, v[134:135], off
	v_add_co_u32_e32 v134, vcc, s34, v132
	s_mov_b32 s34, 0x68000
	s_nop 0
	v_addc_co_u32_e32 v135, vcc, 0, v133, vcc
	global_load_dword v225, v[134:135], off
	v_add_co_u32_e32 v134, vcc, s34, v132
	s_mov_b32 s34, 0x6c000
	s_nop 0
	v_addc_co_u32_e32 v135, vcc, 0, v133, vcc
	global_load_dword v226, v[134:135], off
	v_add_co_u32_e32 v134, vcc, s34, v132
	s_nop 1
	v_addc_co_u32_e32 v135, vcc, 0, v133, vcc
	global_load_dword v227, v[134:135], off
	v_add_co_u32_e32 v134, vcc, 0x70000, v132
	s_nop 1
	v_addc_co_u32_e32 v135, vcc, 0, v133, vcc
	global_load_dword v228, v[134:135], off
	v_add_co_u32_e32 v134, vcc, 0x74000, v132
	s_nop 1
	v_addc_co_u32_e32 v135, vcc, 0, v133, vcc
	global_load_dword v229, v[134:135], off
	v_add_co_u32_e32 v134, vcc, 0x78000, v132
	s_nop 1
	v_addc_co_u32_e32 v135, vcc, 0, v133, vcc
	v_add_co_u32_e32 v132, vcc, 0x7c000, v132
	global_load_dword v230, v[134:135], off
	s_nop 0
	v_addc_co_u32_e32 v133, vcc, 0, v133, vcc
	global_load_dword v231, v[132:133], off
